# GEMM K-loops: loop counter / exit test moved in front of the loop-back barrier (back-edge rotation)
# baseline (speedup 1.0000x reference)
; #define PG8_STAGE(bufoff, gbase, voff) do { _Pragma("unroll") for (int _i = 0; _i < 2; ++_i) \
;         __builtin_amdgcn_global_load_lds((const unsigned*)((const char*)(gbase) + (voff)[_i]), (PG8_LAS unsigned*)(lds + (bufoff) + ldsw + _i * 8192), 16, 0, 0); } while (0)
; #define PG8_LDA(dst, b, h) do { _Pragma("unroll") for (int m = 0; m < 4; ++m) _Pragma("unroll") for (int k = 0; k < 2; ++k) dst[m][k] = *(const PG8_LAS bf16x8*)(lds + PG8_SA(b, h) + aoff + m * 2048 + k * 1024); } while (0)
; #define PG8_LDB(dst, b, h) do { _Pragma("unroll") for (int n = 0; n < 2; ++n) _Pragma("unroll") for (int k = 0; k < 2; ++k) dst[n][k] = *(const PG8_LAS bf16x8*)(lds + PG8_SB(b, h) + boff + n * 2048 + k * 1024); } while (0)
; #define PG8_MMA(ai, bj, At, Bt) do { __builtin_amdgcn_s_setprio(1); _Pragma("unroll") for (int m = 0; m < 4; ++m) _Pragma("unroll") for (int n = 0; n < 2; ++n) _Pragma("unroll") for (int k = 0; k < 2; ++k) \
;         acc[ai][bj][m][n] = __builtin_amdgcn_mfma_f32_16x16x32_f16(H8(Bt[n][k]), H8(At[m][k]), acc[ai][bj][m][n], 0, 0, 0); __builtin_amdgcn_s_setprio(0); } while (0)
; #define PG8_WAIT_V(n) asm volatile("s_waitcnt vmcnt(" #n ")" ::: "memory")
; #define PG8_WAIT_L(n) asm volatile("s_waitcnt lgkmcnt(" #n ")" ::: "memory")
; #define PG8_BAR __builtin_amdgcn_s_barrier()
; #define PG8_SCHED __builtin_amdgcn_sched_barrier(0)
; template <class Epi, class Sched, bool ALIGN_EPI = false, bool SP2 = false>
; __device__ __forceinline__ void gemm_phase(PG8_LAS unsigned char* lds, const Gemm g, const Sched& S, const Epi& E) {
;     ...
;             const bool last = (t == nt - 2);
;             const char* a1 = cA + (size_t)(t + 1) * kstep;
;             const char* a2 = last ? nA : cA + (size_t)(t + 2) * kstep; const char* b2 = last ? nB : cB + (size_t)(t + 2) * kstep;
;             const char* a3 = a2 + kstep; const char* b3 = b2 + kstep;
;             if (last && has_next) S.a_ready(nxt);
;             if constexpr (SP2) {
;             PG8_LDB(B0, 0, 0); PG8_LDB(B1, 0, 1); PG8_SCHED; PG8_LDA(At, 0, 0); PG8_STAGE(PG8_SA(1, 1), a1 + hstep, voffA);
;             PG8_WAIT_V(8); PG8_WAIT_L(0); PG8_BAR; PG8_MMA(0, 0, At, B0); PG8_MMA(0, 1, At, B1); PG8_BAR; PG8_SCHED;
;             PG8_LDA(At, 0, 1); PG8_STAGE(PG8_SB(0, 0), b2, voffB); PG8_STAGE(PG8_SB(0, 1), b2 + hstep, voffB); PG8_STAGE(PG8_SA(0, 0), a2, voffA);
.LBB0_166:
	ds_read_b128 v[146:149], v154
	ds_read_b128 v[158:161], v154 offset:1024
	ds_read_b128 v[164:167], v154 offset:2048
	ds_read_b128 v[168:171], v154 offset:3072
	ds_read_b128 v[172:175], v155
	ds_read_b128 v[176:179], v155 offset:1024
	ds_read_b128 v[180:183], v155 offset:2048
	ds_read_b128 v[184:187], v155 offset:3072
	s_add_u32 s26, s24, 0xfffc0080
	s_addc_u32 s27, s25, -1
	s_cmp_eq_u32 s78, 12
	s_cselect_b32 s29, s17, s27
	s_cselect_b32 s28, s68, s26
	s_cselect_b32 s27, s15, s77
	s_cselect_b32 s26, s69, s76
	v_lshl_add_u64 v[150:151], s[24:25], 0, v[138:139]
	s_add_i32 m0, s23, 0xc000
	ds_read_b128 v[188:191], v156
	ds_read_b128 v[192:195], v156 offset:1024
	ds_read_b128 v[196:199], v156 offset:2048
	ds_read_b128 v[200:203], v156 offset:3072
	ds_read_b128 v[204:207], v156 offset:4096
	ds_read_b128 v[208:211], v156 offset:5120
	ds_read_b128 v[212:215], v156 offset:6144
	ds_read_b128 v[216:219], v156 offset:7168
	global_load_lds_dwordx4 v[150:151], off
	v_lshl_add_u64 v[150:151], s[24:25], 0, v[140:141]
	s_add_i32 m0, s23, 0xe000
	s_nop 0
	global_load_lds_dwordx4 v[150:151], off
	s_waitcnt vmcnt(8)
	s_waitcnt lgkmcnt(0)
	s_barrier
	s_setprio 1
	s_waitcnt lgkmcnt(0)
	v_mfma_f32_16x16x32_f16 v[118:121], v[146:149], v[188:191], v[118:121]
	v_mfma_f32_16x16x32_f16 v[114:117], v[164:167], v[188:191], v[114:117]
	v_mfma_f32_16x16x32_f16 v[102:105], v[146:149], v[196:199], v[102:105]
	v_mfma_f32_16x16x32_f16 v[98:101], v[164:167], v[196:199], v[98:101]
	v_mfma_f32_16x16x32_f16 v[86:89], v[146:149], v[204:207], v[86:89]
	v_mfma_f32_16x16x32_f16 v[82:85], v[164:167], v[204:207], v[82:85]
	v_mfma_f32_16x16x32_f16 v[70:73], v[146:149], v[212:215], v[70:73]
	v_mfma_f32_16x16x32_f16 v[66:69], v[164:167], v[212:215], v[66:69]
	v_mfma_f32_16x16x32_f16 v[118:121], v[158:161], v[192:195], v[118:121]
	v_mfma_f32_16x16x32_f16 v[114:117], v[168:171], v[192:195], v[114:117]
	v_mfma_f32_16x16x32_f16 v[102:105], v[158:161], v[200:203], v[102:105]
	v_mfma_f32_16x16x32_f16 v[98:101], v[168:171], v[200:203], v[98:101]
	v_mfma_f32_16x16x32_f16 v[86:89], v[158:161], v[208:211], v[86:89]
	v_mfma_f32_16x16x32_f16 v[82:85], v[168:171], v[208:211], v[82:85]
	v_mfma_f32_16x16x32_f16 v[70:73], v[158:161], v[216:219], v[70:73]
	v_mfma_f32_16x16x32_f16 v[66:69], v[168:171], v[216:219], v[66:69]
	s_setprio 0
	s_setprio 1
	v_mfma_f32_16x16x32_f16 v[126:129], v[172:175], v[188:191], v[126:129]
	v_mfma_f32_16x16x32_f16 v[122:125], v[180:183], v[188:191], v[122:125]
	v_mfma_f32_16x16x32_f16 v[110:113], v[172:175], v[196:199], v[110:113]
	v_mfma_f32_16x16x32_f16 v[106:109], v[180:183], v[196:199], v[106:109]
	v_mfma_f32_16x16x32_f16 v[94:97], v[172:175], v[204:207], v[94:97]
	v_mfma_f32_16x16x32_f16 v[90:93], v[180:183], v[204:207], v[90:93]
	v_mfma_f32_16x16x32_f16 v[78:81], v[172:175], v[212:215], v[78:81]
	v_mfma_f32_16x16x32_f16 v[74:77], v[180:183], v[212:215], v[74:77]
	v_mfma_f32_16x16x32_f16 v[126:129], v[176:179], v[192:195], v[126:129]
	v_mfma_f32_16x16x32_f16 v[122:125], v[184:187], v[192:195], v[122:125]
	v_mfma_f32_16x16x32_f16 v[110:113], v[176:179], v[200:203], v[110:113]
	v_mfma_f32_16x16x32_f16 v[106:109], v[184:187], v[200:203], v[106:109]
	v_mfma_f32_16x16x32_f16 v[94:97], v[176:179], v[208:211], v[94:97]
	v_mfma_f32_16x16x32_f16 v[90:93], v[184:187], v[208:211], v[90:93]
	v_mfma_f32_16x16x32_f16 v[78:81], v[176:179], v[216:219], v[78:81]
	v_mfma_f32_16x16x32_f16 v[74:77], v[184:187], v[216:219], v[74:77]
	s_setprio 0
	s_barrier
	s_add_i32 s79, s52, s33
	v_lshl_add_u64 v[150:151], s[26:27], 0, v[134:135]
	s_mov_b32 m0, s79
	ds_read_b128 v[188:191], v156 offset:16384
	ds_read_b128 v[192:195], v156 offset:17408
	ds_read_b128 v[196:199], v156 offset:18432
	ds_read_b128 v[200:203], v156 offset:19456
	ds_read_b128 v[204:207], v156 offset:20480
	ds_read_b128 v[208:211], v156 offset:21504
	ds_read_b128 v[212:215], v156 offset:22528
	ds_read_b128 v[216:219], v156 offset:23552
	global_load_lds_dwordx4 v[150:151], off
	s_add_i32 m0, s79, 0x2000
	s_add_u32 s84, s26, 0x40000
	v_lshl_add_u64 v[220:221], s[26:27], 0, v[130:131]
	s_addc_u32 s85, s27, 0
	s_add_i32 s79, s53, s33
	global_load_lds_dwordx4 v[220:221], off
	v_lshl_add_u64 v[222:223], s[84:85], 0, v[134:135]
	s_mov_b32 m0, s79
	v_lshl_add_u64 v[224:225], s[28:29], 0, v[132:133]
	global_load_lds_dwordx4 v[222:223], off
	v_lshl_add_u64 v[222:223], s[84:85], 0, v[130:131]
	s_add_i32 m0, s79, 0x2000
	s_nop 0
	global_load_lds_dwordx4 v[222:223], off
	v_lshl_add_u64 v[222:223], s[28:29], 0, v[136:137]
	s_mov_b32 m0, s23
	s_nop 0
	global_load_lds_dwordx4 v[222:223], off
	s_mov_b32 m0, s36
	s_nop 0
	global_load_lds_dwordx4 v[224:225], off
	s_waitcnt vmcnt(8)
	s_waitcnt lgkmcnt(0)
	s_barrier
; #define PG8_STAGE(bufoff, gbase, voff) do { _Pragma("unroll") for (int _i = 0; _i < 2; ++_i) \
;         __builtin_amdgcn_global_load_lds((const unsigned*)((const char*)(gbase) + (voff)[_i]), (PG8_LAS unsigned*)(lds + (bufoff) + ldsw + _i * 8192), 16, 0, 0); } while (0)
; #define PG8_LDA(dst, b, h) do { _Pragma("unroll") for (int m = 0; m < 4; ++m) _Pragma("unroll") for (int k = 0; k < 2; ++k) dst[m][k] = *(const PG8_LAS bf16x8*)(lds + PG8_SA(b, h) + aoff + m * 2048 + k * 1024); } while (0)
; #define PG8_LDB(dst, b, h) do { _Pragma("unroll") for (int n = 0; n < 2; ++n) _Pragma("unroll") for (int k = 0; k < 2; ++k) dst[n][k] = *(const PG8_LAS bf16x8*)(lds + PG8_SB(b, h) + boff + n * 2048 + k * 1024); } while (0)
; #define PG8_MMA(ai, bj, At, Bt) do { __builtin_amdgcn_s_setprio(1); _Pragma("unroll") for (int m = 0; m < 4; ++m) _Pragma("unroll") for (int n = 0; n < 2; ++n) _Pragma("unroll") for (int k = 0; k < 2; ++k) \
;         acc[ai][bj][m][n] = __builtin_amdgcn_mfma_f32_16x16x32_f16(H8(Bt[n][k]), H8(At[m][k]), acc[ai][bj][m][n], 0, 0, 0); __builtin_amdgcn_s_setprio(0); } while (0)
; #define PG8_WAIT_V(n) asm volatile("s_waitcnt vmcnt(" #n ")" ::: "memory")
; #define PG8_WAIT_L(n) asm volatile("s_waitcnt lgkmcnt(" #n ")" ::: "memory")
; #define PG8_BAR __builtin_amdgcn_s_barrier()
; #define PG8_SCHED __builtin_amdgcn_sched_barrier(0)
; template <class Epi, class Sched, bool ALIGN_EPI = false, bool SP2 = false>
; __device__ __forceinline__ void gemm_phase(PG8_LAS unsigned char* lds, const Gemm g, const Sched& S, const Epi& E) {
;     ...
;             PG8_LDA(At, 0, 1); PG8_STAGE(PG8_SB(0, 0), b2, voffB); PG8_STAGE(PG8_SB(0, 1), b2 + hstep, voffB); PG8_STAGE(PG8_SA(0, 0), a2, voffA);
;             PG8_WAIT_V(8); PG8_WAIT_L(0); PG8_BAR; PG8_MMA(1, 0, At, B0); PG8_MMA(1, 1, At, B1); PG8_BAR; PG8_SCHED;
;             PG8_LDB(B0, 1, 0); PG8_LDB(B1, 1, 1); PG8_SCHED; PG8_LDA(At, 1, 0); PG8_STAGE(PG8_SA(0, 1), a2 + hstep, voffA);
;             PG8_WAIT_V(8); PG8_WAIT_L(0); PG8_BAR; PG8_MMA(0, 0, At, B0); PG8_MMA(0, 1, At, B1); PG8_BAR; PG8_SCHED;
	s_setprio 1
	s_waitcnt lgkmcnt(0)
	v_mfma_f32_16x16x32_f16 v[54:57], v[146:149], v[188:191], v[54:57]
	v_mfma_f32_16x16x32_f16 v[50:53], v[164:167], v[188:191], v[50:53]
	v_mfma_f32_16x16x32_f16 v[38:41], v[146:149], v[196:199], v[38:41]
	v_mfma_f32_16x16x32_f16 v[34:37], v[164:167], v[196:199], v[34:37]
	v_mfma_f32_16x16x32_f16 v[22:25], v[146:149], v[204:207], v[22:25]
	v_mfma_f32_16x16x32_f16 v[18:21], v[164:167], v[204:207], v[18:21]
	v_mfma_f32_16x16x32_f16 v[6:9], v[146:149], v[212:215], v[6:9]
	v_mfma_f32_16x16x32_f16 v[2:5], v[164:167], v[212:215], v[2:5]
	v_mfma_f32_16x16x32_f16 v[54:57], v[158:161], v[192:195], v[54:57]
	v_mfma_f32_16x16x32_f16 v[50:53], v[168:171], v[192:195], v[50:53]
	v_mfma_f32_16x16x32_f16 v[38:41], v[158:161], v[200:203], v[38:41]
	v_mfma_f32_16x16x32_f16 v[34:37], v[168:171], v[200:203], v[34:37]
	v_mfma_f32_16x16x32_f16 v[22:25], v[158:161], v[208:211], v[22:25]
	v_mfma_f32_16x16x32_f16 v[18:21], v[168:171], v[208:211], v[18:21]
	v_mfma_f32_16x16x32_f16 v[6:9], v[158:161], v[216:219], v[6:9]
	v_mfma_f32_16x16x32_f16 v[2:5], v[168:171], v[216:219], v[2:5]
	s_setprio 0
	s_setprio 1
	v_mfma_f32_16x16x32_f16 v[62:65], v[172:175], v[188:191], v[62:65]
	v_mfma_f32_16x16x32_f16 v[58:61], v[180:183], v[188:191], v[58:61]
	v_mfma_f32_16x16x32_f16 v[46:49], v[172:175], v[196:199], v[46:49]
	v_mfma_f32_16x16x32_f16 v[42:45], v[180:183], v[196:199], v[42:45]
	v_mfma_f32_16x16x32_f16 v[30:33], v[172:175], v[204:207], v[30:33]
	v_mfma_f32_16x16x32_f16 v[26:29], v[180:183], v[204:207], v[26:29]
	v_mfma_f32_16x16x32_f16 v[14:17], v[172:175], v[212:215], v[14:17]
	v_mfma_f32_16x16x32_f16 v[10:13], v[180:183], v[212:215], v[10:13]
	v_mfma_f32_16x16x32_f16 v[62:65], v[176:179], v[192:195], v[62:65]
	v_mfma_f32_16x16x32_f16 v[58:61], v[184:187], v[192:195], v[58:61]
	v_mfma_f32_16x16x32_f16 v[46:49], v[176:179], v[200:203], v[46:49]
	v_mfma_f32_16x16x32_f16 v[42:45], v[184:187], v[200:203], v[42:45]
	v_mfma_f32_16x16x32_f16 v[30:33], v[176:179], v[208:211], v[30:33]
	v_mfma_f32_16x16x32_f16 v[26:29], v[184:187], v[208:211], v[26:29]
	v_mfma_f32_16x16x32_f16 v[14:17], v[176:179], v[216:219], v[14:17]
	v_mfma_f32_16x16x32_f16 v[10:13], v[184:187], v[216:219], v[10:13]
	s_setprio 0
	s_barrier
	s_add_i32 s79, 0, 0x18000
	v_add_u32_e32 v157, s79, v152
	s_add_i32 s81, 0, 0x1c000
	ds_read_b128 v[146:149], v157
	ds_read_b128 v[158:161], v157 offset:1024
	ds_read_b128 v[164:167], v157 offset:2048
	ds_read_b128 v[168:171], v157 offset:3072
	v_add_u32_e32 v157, s81, v152
	ds_read_b128 v[172:175], v157
	ds_read_b128 v[176:179], v157 offset:1024
	ds_read_b128 v[180:183], v157 offset:2048
	ds_read_b128 v[184:187], v157 offset:3072
	s_add_u32 s28, s28, 0x40000
	s_addc_u32 s29, s29, 0
	s_mov_b32 m0, s37
	v_lshl_add_u64 v[226:227], s[28:29], 0, v[136:137]
	ds_read_b128 v[188:191], v156 offset:32768
	ds_read_b128 v[192:195], v156 offset:33792
	ds_read_b128 v[196:199], v156 offset:34816
	ds_read_b128 v[200:203], v156 offset:35840
	ds_read_b128 v[204:207], v156 offset:36864
	ds_read_b128 v[208:211], v156 offset:37888
	ds_read_b128 v[212:215], v156 offset:38912
	ds_read_b128 v[216:219], v156 offset:39936
	global_load_lds_dwordx4 v[226:227], off
	v_lshl_add_u64 v[226:227], s[28:29], 0, v[132:133]
	s_mov_b32 m0, s44
	s_nop 0
	global_load_lds_dwordx4 v[226:227], off
	s_waitcnt vmcnt(8)
	s_waitcnt lgkmcnt(0)
	s_barrier
	s_setprio 1
	s_waitcnt lgkmcnt(0)
	v_mfma_f32_16x16x32_f16 v[118:121], v[146:149], v[188:191], v[118:121]
	v_mfma_f32_16x16x32_f16 v[114:117], v[164:167], v[188:191], v[114:117]
	v_mfma_f32_16x16x32_f16 v[102:105], v[146:149], v[196:199], v[102:105]
	v_mfma_f32_16x16x32_f16 v[98:101], v[164:167], v[196:199], v[98:101]
	v_mfma_f32_16x16x32_f16 v[86:89], v[146:149], v[204:207], v[86:89]
	v_mfma_f32_16x16x32_f16 v[82:85], v[164:167], v[204:207], v[82:85]
	v_mfma_f32_16x16x32_f16 v[70:73], v[146:149], v[212:215], v[70:73]
	v_mfma_f32_16x16x32_f16 v[66:69], v[164:167], v[212:215], v[66:69]
	v_mfma_f32_16x16x32_f16 v[118:121], v[158:161], v[192:195], v[118:121]
	v_mfma_f32_16x16x32_f16 v[114:117], v[168:171], v[192:195], v[114:117]
	v_mfma_f32_16x16x32_f16 v[102:105], v[158:161], v[200:203], v[102:105]
	v_mfma_f32_16x16x32_f16 v[98:101], v[168:171], v[200:203], v[98:101]
	v_mfma_f32_16x16x32_f16 v[86:89], v[158:161], v[208:211], v[86:89]
	v_mfma_f32_16x16x32_f16 v[82:85], v[168:171], v[208:211], v[82:85]
	v_mfma_f32_16x16x32_f16 v[70:73], v[158:161], v[216:219], v[70:73]
	v_mfma_f32_16x16x32_f16 v[66:69], v[168:171], v[216:219], v[66:69]
	s_setprio 0
	s_setprio 1
	v_mfma_f32_16x16x32_f16 v[126:129], v[172:175], v[188:191], v[126:129]
	v_mfma_f32_16x16x32_f16 v[122:125], v[180:183], v[188:191], v[122:125]
	v_mfma_f32_16x16x32_f16 v[110:113], v[172:175], v[196:199], v[110:113]
	v_mfma_f32_16x16x32_f16 v[106:109], v[180:183], v[196:199], v[106:109]
	v_mfma_f32_16x16x32_f16 v[94:97], v[172:175], v[204:207], v[94:97]
	v_mfma_f32_16x16x32_f16 v[90:93], v[180:183], v[204:207], v[90:93]
	v_mfma_f32_16x16x32_f16 v[78:81], v[172:175], v[212:215], v[78:81]
	v_mfma_f32_16x16x32_f16 v[74:77], v[180:183], v[212:215], v[74:77]
	v_mfma_f32_16x16x32_f16 v[126:129], v[176:179], v[192:195], v[126:129]
	v_mfma_f32_16x16x32_f16 v[122:125], v[184:187], v[192:195], v[122:125]
	v_mfma_f32_16x16x32_f16 v[110:113], v[176:179], v[200:203], v[110:113]
	v_mfma_f32_16x16x32_f16 v[106:109], v[184:187], v[200:203], v[106:109]
	v_mfma_f32_16x16x32_f16 v[94:97], v[176:179], v[208:211], v[94:97]
	v_mfma_f32_16x16x32_f16 v[90:93], v[184:187], v[208:211], v[90:93]
	v_mfma_f32_16x16x32_f16 v[78:81], v[176:179], v[216:219], v[78:81]
	v_mfma_f32_16x16x32_f16 v[74:77], v[184:187], v[216:219], v[74:77]
	s_setprio 0
	s_barrier
; #define PG8_STAGE(bufoff, gbase, voff) do { _Pragma("unroll") for (int _i = 0; _i < 2; ++_i) \
;         __builtin_amdgcn_global_load_lds((const unsigned*)((const char*)(gbase) + (voff)[_i]), (PG8_LAS unsigned*)(lds + (bufoff) + ldsw + _i * 8192), 16, 0, 0); } while (0)
; #define PG8_LDA(dst, b, h) do { _Pragma("unroll") for (int m = 0; m < 4; ++m) _Pragma("unroll") for (int k = 0; k < 2; ++k) dst[m][k] = *(const PG8_LAS bf16x8*)(lds + PG8_SA(b, h) + aoff + m * 2048 + k * 1024); } while (0)
; #define PG8_LDB(dst, b, h) do { _Pragma("unroll") for (int n = 0; n < 2; ++n) _Pragma("unroll") for (int k = 0; k < 2; ++k) dst[n][k] = *(const PG8_LAS bf16x8*)(lds + PG8_SB(b, h) + boff + n * 2048 + k * 1024); } while (0)
; template <class Epi, class Sched, bool ALIGN_EPI = false, bool SP2 = false>
; __device__ __forceinline__ void gemm_phase(PG8_LAS unsigned char* lds, const Gemm g, const Sched& S, const Epi& E) {
;     ...
;         for (int t = 0; t < nt; t += 2) {
;             const bool last = (t == nt - 2);
;             const char* a1 = cA + (size_t)(t + 1) * kstep;
;             const char* a2 = last ? nA : cA + (size_t)(t + 2) * kstep; const char* b2 = last ? nB : cB + (size_t)(t + 2) * kstep;
;             const char* a3 = a2 + kstep; const char* b3 = b2 + kstep;
;             if (last && has_next) S.a_ready(nxt);
;             if constexpr (SP2) {
;             PG8_LDB(B0, 0, 0); PG8_LDB(B1, 0, 1); PG8_SCHED; PG8_LDA(At, 0, 0); PG8_STAGE(PG8_SA(1, 1), a1 + hstep, voffA);
;             PG8_WAIT_V(8); PG8_WAIT_L(0); PG8_BAR; PG8_MMA(0, 0, At, B0); PG8_MMA(0, 1, At, B1); PG8_BAR; PG8_SCHED;
;             PG8_LDA(At, 0, 1); PG8_STAGE(PG8_SB(0, 0), b2, voffB); PG8_STAGE(PG8_SB(0, 1), b2 + hstep, voffB); PG8_STAGE(PG8_SA(0, 0), a2, voffA);
;             PG8_WAIT_V(8); PG8_WAIT_L(0); PG8_BAR; PG8_MMA(1, 0, At, B0); PG8_MMA(1, 1, At, B1); PG8_BAR; PG8_SCHED;
;             PG8_LDB(B0, 1, 0); PG8_LDB(B1, 1, 1); PG8_SCHED; PG8_LDA(At, 1, 0); PG8_STAGE(PG8_SA(0, 1), a2 + hstep, voffA);
;             PG8_WAIT_V(8); PG8_WAIT_L(0); PG8_BAR; PG8_MMA(0, 0, At, B0); PG8_MMA(0, 1, At, B1); PG8_BAR; PG8_SCHED;
;             PG8_LDA(At, 1, 1); PG8_STAGE(PG8_SB(1, 0), b3, voffB); PG8_STAGE(PG8_SB(1, 1), b3 + hstep, voffB); PG8_STAGE(PG8_SA(1, 0), a3, voffA);
;             PG8_WAIT_V(8); PG8_WAIT_L(0); PG8_BAR; PG8_MMA(1, 0, At, B0); PG8_MMA(1, 1, At, B1); PG8_BAR; PG8_SCHED;
	s_add_i32 s28, s79, s33
	v_lshl_add_u64 v[150:151], v[150:151], 0, s[10:11]
	s_mov_b32 m0, s28
	ds_read_b128 v[188:191], v156 offset:49152
	ds_read_b128 v[192:195], v156 offset:50176
	ds_read_b128 v[196:199], v156 offset:51200
	ds_read_b128 v[200:203], v156 offset:52224
	ds_read_b128 v[204:207], v156 offset:53248
	ds_read_b128 v[208:211], v156 offset:54272
	ds_read_b128 v[212:215], v156 offset:55296
	ds_read_b128 v[216:219], v156 offset:56320
	global_load_lds_dwordx4 v[150:151], off
	s_add_i32 m0, s28, 0x2000
	s_add_u32 s26, s26, 0x40080
	v_lshl_add_u64 v[150:151], v[220:221], 0, s[10:11]
	s_addc_u32 s27, s27, 0
	s_add_i32 s28, s81, s33
	global_load_lds_dwordx4 v[150:151], off
	v_lshl_add_u64 v[150:151], s[26:27], 0, v[134:135]
	s_mov_b32 m0, s28
	s_nop 0
	global_load_lds_dwordx4 v[150:151], off
	v_lshl_add_u64 v[150:151], s[26:27], 0, v[130:131]
	s_add_i32 m0, s28, 0x2000
	s_nop 0
	global_load_lds_dwordx4 v[150:151], off
	v_lshl_add_u64 v[150:151], v[222:223], 0, s[10:11]
	s_mov_b32 m0, s48
	s_nop 0
	global_load_lds_dwordx4 v[150:151], off
	v_lshl_add_u64 v[150:151], v[224:225], 0, s[10:11]
	s_mov_b32 m0, s49
	s_nop 0
	global_load_lds_dwordx4 v[150:151], off
	s_waitcnt vmcnt(8)
	s_waitcnt lgkmcnt(0)
	s_barrier
	s_setprio 1
	s_waitcnt lgkmcnt(0)
	v_mfma_f32_16x16x32_f16 v[54:57], v[146:149], v[188:191], v[54:57]
	v_mfma_f32_16x16x32_f16 v[50:53], v[164:167], v[188:191], v[50:53]
	v_mfma_f32_16x16x32_f16 v[38:41], v[146:149], v[196:199], v[38:41]
	v_mfma_f32_16x16x32_f16 v[34:37], v[164:167], v[196:199], v[34:37]
	v_mfma_f32_16x16x32_f16 v[22:25], v[146:149], v[204:207], v[22:25]
	v_mfma_f32_16x16x32_f16 v[18:21], v[164:167], v[204:207], v[18:21]
	v_mfma_f32_16x16x32_f16 v[6:9], v[146:149], v[212:215], v[6:9]
	v_mfma_f32_16x16x32_f16 v[2:5], v[164:167], v[212:215], v[2:5]
	v_mfma_f32_16x16x32_f16 v[54:57], v[158:161], v[192:195], v[54:57]
	v_mfma_f32_16x16x32_f16 v[50:53], v[168:171], v[192:195], v[50:53]
	v_mfma_f32_16x16x32_f16 v[38:41], v[158:161], v[200:203], v[38:41]
	v_mfma_f32_16x16x32_f16 v[34:37], v[168:171], v[200:203], v[34:37]
	v_mfma_f32_16x16x32_f16 v[22:25], v[158:161], v[208:211], v[22:25]
	v_mfma_f32_16x16x32_f16 v[18:21], v[168:171], v[208:211], v[18:21]
	v_mfma_f32_16x16x32_f16 v[6:9], v[158:161], v[216:219], v[6:9]
	v_mfma_f32_16x16x32_f16 v[2:5], v[168:171], v[216:219], v[2:5]
	s_setprio 0
	s_setprio 1
	v_mfma_f32_16x16x32_f16 v[62:65], v[172:175], v[188:191], v[62:65]
	v_mfma_f32_16x16x32_f16 v[58:61], v[180:183], v[188:191], v[58:61]
	v_mfma_f32_16x16x32_f16 v[46:49], v[172:175], v[196:199], v[46:49]
	v_mfma_f32_16x16x32_f16 v[42:45], v[180:183], v[196:199], v[42:45]
	v_mfma_f32_16x16x32_f16 v[30:33], v[172:175], v[204:207], v[30:33]
	v_mfma_f32_16x16x32_f16 v[26:29], v[180:183], v[204:207], v[26:29]
	v_mfma_f32_16x16x32_f16 v[14:17], v[172:175], v[212:215], v[14:17]
	v_mfma_f32_16x16x32_f16 v[10:13], v[180:183], v[212:215], v[10:13]
	v_mfma_f32_16x16x32_f16 v[62:65], v[176:179], v[192:195], v[62:65]
	v_mfma_f32_16x16x32_f16 v[58:61], v[184:187], v[192:195], v[58:61]
	v_mfma_f32_16x16x32_f16 v[46:49], v[176:179], v[200:203], v[46:49]
	v_mfma_f32_16x16x32_f16 v[42:45], v[184:187], v[200:203], v[42:45]
	v_mfma_f32_16x16x32_f16 v[30:33], v[176:179], v[208:211], v[30:33]
	v_mfma_f32_16x16x32_f16 v[26:29], v[184:187], v[208:211], v[26:29]
	v_mfma_f32_16x16x32_f16 v[14:17], v[176:179], v[216:219], v[14:17]
	v_mfma_f32_16x16x32_f16 v[10:13], v[184:187], v[216:219], v[10:13]
	s_setprio 0
	s_add_i32 s78, s78, 2
	s_add_u32 s24, s24, 0x100
	s_addc_u32 s25, s25, 0
	s_add_u32 s76, s76, 0x100
	s_addc_u32 s77, s77, 0
	s_cmp_gt_u32 s78, 13
	s_barrier
	s_cbranch_scc0 .LBB0_166
	s_and_b64 vcc, exec, s[12:13]
	s_cbranch_vccz .LBB0_169
	s_barrier

; #define PG8_STAGE(bufoff, gbase, voff) do { _Pragma("unroll") for (int _i = 0; _i < 2; ++_i) \
;         __builtin_amdgcn_global_load_lds((const unsigned*)((const char*)(gbase) + (voff)[_i]), (PG8_LAS unsigned*)(lds + (bufoff) + ldsw + _i * 8192), 16, 0, 0); } while (0)
; #define PG8_LDA(dst, b, h) do { _Pragma("unroll") for (int m = 0; m < 4; ++m) _Pragma("unroll") for (int k = 0; k < 2; ++k) dst[m][k] = *(const PG8_LAS bf16x8*)(lds + PG8_SA(b, h) + aoff + m * 2048 + k * 1024); } while (0)
; #define PG8_LDB(dst, b, h) do { _Pragma("unroll") for (int n = 0; n < 2; ++n) _Pragma("unroll") for (int k = 0; k < 2; ++k) dst[n][k] = *(const PG8_LAS bf16x8*)(lds + PG8_SB(b, h) + boff + n * 2048 + k * 1024); } while (0)
; #define PG8_MMA(ai, bj, At, Bt) do { __builtin_amdgcn_s_setprio(1); _Pragma("unroll") for (int m = 0; m < 4; ++m) _Pragma("unroll") for (int n = 0; n < 2; ++n) _Pragma("unroll") for (int k = 0; k < 2; ++k) \
;         acc[ai][bj][m][n] = __builtin_amdgcn_mfma_f32_16x16x32_f16(H8(Bt[n][k]), H8(At[m][k]), acc[ai][bj][m][n], 0, 0, 0); __builtin_amdgcn_s_setprio(0); } while (0)
; #define PG8_WAIT_V(n) asm volatile("s_waitcnt vmcnt(" #n ")" ::: "memory")
; #define PG8_WAIT_L(n) asm volatile("s_waitcnt lgkmcnt(" #n ")" ::: "memory")
; #define PG8_BAR __builtin_amdgcn_s_barrier()
; #define PG8_SCHED __builtin_amdgcn_sched_barrier(0)
; template <class Epi, class Sched, bool ALIGN_EPI = false, bool SP2 = false>
; __device__ __forceinline__ void gemm_phase(PG8_LAS unsigned char* lds, const Gemm g, const Sched& S, const Epi& E) {
;     ...
;             const bool last = (t == nt - 2);
;             const char* a1 = cA + (size_t)(t + 1) * kstep;
;             const char* a2 = last ? nA : cA + (size_t)(t + 2) * kstep; const char* b2 = last ? nB : cB + (size_t)(t + 2) * kstep;
;             const char* a3 = a2 + kstep; const char* b3 = b2 + kstep;
;             if (last && has_next) S.a_ready(nxt);
;             if constexpr (SP2) {
;             PG8_LDB(B0, 0, 0); PG8_LDB(B1, 0, 1); PG8_SCHED; PG8_LDA(At, 0, 0); PG8_STAGE(PG8_SA(1, 1), a1 + hstep, voffA);
;             PG8_WAIT_V(8); PG8_WAIT_L(0); PG8_BAR; PG8_MMA(0, 0, At, B0); PG8_MMA(0, 1, At, B1); PG8_BAR; PG8_SCHED;
;             PG8_LDA(At, 0, 1); PG8_STAGE(PG8_SB(0, 0), b2, voffB); PG8_STAGE(PG8_SB(0, 1), b2 + hstep, voffB); PG8_STAGE(PG8_SA(0, 0), a2, voffA);
.LBB0_261:
	ds_read_b128 v[154:157], v150
	ds_read_b128 v[158:161], v150 offset:1024
	ds_read_b128 v[164:167], v150 offset:2048
	ds_read_b128 v[168:171], v150 offset:3072
	ds_read_b128 v[172:175], v151
	ds_read_b128 v[176:179], v151 offset:1024
	ds_read_b128 v[180:183], v151 offset:2048
	ds_read_b128 v[184:187], v151 offset:3072
	s_add_u32 s20, s18, 0xfff50080
	s_addc_u32 s21, s19, -1
	s_cmp_eq_u32 s76, 40
	s_cselect_b32 s23, s5, s21
	s_cselect_b32 s22, s4, s20
	s_cselect_b32 s21, s17, s69
	s_cselect_b32 s20, s16, s68
	v_lshl_add_u64 v[146:147], s[18:19], 0, v[138:139]
	s_add_i32 m0, s30, 0xc000
	ds_read_b128 v[188:191], v152
	ds_read_b128 v[192:195], v152 offset:1024
	ds_read_b128 v[196:199], v152 offset:2048
	ds_read_b128 v[200:203], v152 offset:3072
	ds_read_b128 v[204:207], v152 offset:4096
	ds_read_b128 v[208:211], v152 offset:5120
	ds_read_b128 v[212:215], v152 offset:6144
	ds_read_b128 v[216:219], v152 offset:7168
	global_load_lds_dwordx4 v[146:147], off
	v_lshl_add_u64 v[146:147], s[18:19], 0, v[140:141]
	s_add_i32 m0, s30, 0xe000
	s_nop 0
	global_load_lds_dwordx4 v[146:147], off
	s_waitcnt vmcnt(8)
	s_waitcnt lgkmcnt(0)
	s_barrier
	s_setprio 1
	s_waitcnt lgkmcnt(0)
	v_mfma_f32_16x16x32_f16 v[126:129], v[154:157], v[188:191], v[126:129]
	v_mfma_f32_16x16x32_f16 v[122:125], v[164:167], v[188:191], v[122:125]
	v_mfma_f32_16x16x32_f16 v[118:121], v[154:157], v[196:199], v[118:121]
	v_mfma_f32_16x16x32_f16 v[110:113], v[164:167], v[196:199], v[110:113]
	v_mfma_f32_16x16x32_f16 v[102:105], v[154:157], v[204:207], v[102:105]
	v_mfma_f32_16x16x32_f16 v[94:97], v[164:167], v[204:207], v[94:97]
	v_mfma_f32_16x16x32_f16 v[86:89], v[154:157], v[212:215], v[86:89]
	v_mfma_f32_16x16x32_f16 v[78:81], v[164:167], v[212:215], v[78:81]
	v_mfma_f32_16x16x32_f16 v[126:129], v[158:161], v[192:195], v[126:129]
	v_mfma_f32_16x16x32_f16 v[122:125], v[168:171], v[192:195], v[122:125]
	v_mfma_f32_16x16x32_f16 v[118:121], v[158:161], v[200:203], v[118:121]
	v_mfma_f32_16x16x32_f16 v[110:113], v[168:171], v[200:203], v[110:113]
	v_mfma_f32_16x16x32_f16 v[102:105], v[158:161], v[208:211], v[102:105]
	v_mfma_f32_16x16x32_f16 v[94:97], v[168:171], v[208:211], v[94:97]
	v_mfma_f32_16x16x32_f16 v[86:89], v[158:161], v[216:219], v[86:89]
	v_mfma_f32_16x16x32_f16 v[78:81], v[168:171], v[216:219], v[78:81]
	s_setprio 0
	s_setprio 1
	v_mfma_f32_16x16x32_f16 v[114:117], v[172:175], v[188:191], v[114:117]
	v_mfma_f32_16x16x32_f16 v[106:109], v[180:183], v[188:191], v[106:109]
	v_mfma_f32_16x16x32_f16 v[98:101], v[172:175], v[196:199], v[98:101]
	v_mfma_f32_16x16x32_f16 v[90:93], v[180:183], v[196:199], v[90:93]
	v_mfma_f32_16x16x32_f16 v[82:85], v[172:175], v[204:207], v[82:85]
	v_mfma_f32_16x16x32_f16 v[74:77], v[180:183], v[204:207], v[74:77]
	v_mfma_f32_16x16x32_f16 v[70:73], v[172:175], v[212:215], v[70:73]
	v_mfma_f32_16x16x32_f16 v[66:69], v[180:183], v[212:215], v[66:69]
	v_mfma_f32_16x16x32_f16 v[114:117], v[176:179], v[192:195], v[114:117]
	v_mfma_f32_16x16x32_f16 v[106:109], v[184:187], v[192:195], v[106:109]
	v_mfma_f32_16x16x32_f16 v[98:101], v[176:179], v[200:203], v[98:101]
	v_mfma_f32_16x16x32_f16 v[90:93], v[184:187], v[200:203], v[90:93]
	v_mfma_f32_16x16x32_f16 v[82:85], v[176:179], v[208:211], v[82:85]
	v_mfma_f32_16x16x32_f16 v[74:77], v[184:187], v[208:211], v[74:77]
	v_mfma_f32_16x16x32_f16 v[70:73], v[176:179], v[216:219], v[70:73]
	v_mfma_f32_16x16x32_f16 v[66:69], v[184:187], v[216:219], v[66:69]
	s_setprio 0
	s_barrier
	s_add_i32 s77, s48, s29
	v_lshl_add_u64 v[146:147], s[20:21], 0, v[132:133]
	s_mov_b32 m0, s77
	ds_read_b128 v[188:191], v152 offset:16384
	ds_read_b128 v[192:195], v152 offset:17408
	ds_read_b128 v[196:199], v152 offset:18432
	ds_read_b128 v[200:203], v152 offset:19456
	ds_read_b128 v[204:207], v152 offset:20480
	ds_read_b128 v[208:211], v152 offset:21504
	ds_read_b128 v[212:215], v152 offset:22528
	ds_read_b128 v[216:219], v152 offset:23552
	global_load_lds_dwordx4 v[146:147], off
	s_add_i32 m0, s77, 0x2000
	s_add_u32 s78, s20, 0xb0000
	v_lshl_add_u64 v[220:221], s[20:21], 0, v[136:137]
	s_addc_u32 s79, s21, 0
	s_add_i32 s77, s49, s29
	global_load_lds_dwordx4 v[220:221], off
	v_lshl_add_u64 v[222:223], s[78:79], 0, v[132:133]
	s_mov_b32 m0, s77
	v_lshl_add_u64 v[224:225], s[22:23], 0, v[134:135]
	global_load_lds_dwordx4 v[222:223], off
	v_lshl_add_u64 v[222:223], s[78:79], 0, v[136:137]
	s_add_i32 m0, s77, 0x2000
	s_nop 0
	global_load_lds_dwordx4 v[222:223], off
	v_lshl_add_u64 v[222:223], s[22:23], 0, v[130:131]
	s_mov_b32 m0, s30
	s_nop 0
	global_load_lds_dwordx4 v[222:223], off
	s_mov_b32 m0, s31
	s_nop 0
	global_load_lds_dwordx4 v[224:225], off
	s_waitcnt vmcnt(8)
	s_waitcnt lgkmcnt(0)
	s_barrier
; #define PG8_STAGE(bufoff, gbase, voff) do { _Pragma("unroll") for (int _i = 0; _i < 2; ++_i) \
;         __builtin_amdgcn_global_load_lds((const unsigned*)((const char*)(gbase) + (voff)[_i]), (PG8_LAS unsigned*)(lds + (bufoff) + ldsw + _i * 8192), 16, 0, 0); } while (0)
; #define PG8_LDA(dst, b, h) do { _Pragma("unroll") for (int m = 0; m < 4; ++m) _Pragma("unroll") for (int k = 0; k < 2; ++k) dst[m][k] = *(const PG8_LAS bf16x8*)(lds + PG8_SA(b, h) + aoff + m * 2048 + k * 1024); } while (0)
; #define PG8_LDB(dst, b, h) do { _Pragma("unroll") for (int n = 0; n < 2; ++n) _Pragma("unroll") for (int k = 0; k < 2; ++k) dst[n][k] = *(const PG8_LAS bf16x8*)(lds + PG8_SB(b, h) + boff + n * 2048 + k * 1024); } while (0)
; #define PG8_MMA(ai, bj, At, Bt) do { __builtin_amdgcn_s_setprio(1); _Pragma("unroll") for (int m = 0; m < 4; ++m) _Pragma("unroll") for (int n = 0; n < 2; ++n) _Pragma("unroll") for (int k = 0; k < 2; ++k) \
;         acc[ai][bj][m][n] = __builtin_amdgcn_mfma_f32_16x16x32_f16(H8(Bt[n][k]), H8(At[m][k]), acc[ai][bj][m][n], 0, 0, 0); __builtin_amdgcn_s_setprio(0); } while (0)
; #define PG8_WAIT_V(n) asm volatile("s_waitcnt vmcnt(" #n ")" ::: "memory")
; #define PG8_WAIT_L(n) asm volatile("s_waitcnt lgkmcnt(" #n ")" ::: "memory")
; #define PG8_BAR __builtin_amdgcn_s_barrier()
; #define PG8_SCHED __builtin_amdgcn_sched_barrier(0)
; template <class Epi, class Sched, bool ALIGN_EPI = false, bool SP2 = false>
; __device__ __forceinline__ void gemm_phase(PG8_LAS unsigned char* lds, const Gemm g, const Sched& S, const Epi& E) {
;     ...
;             PG8_LDA(At, 0, 1); PG8_STAGE(PG8_SB(0, 0), b2, voffB); PG8_STAGE(PG8_SB(0, 1), b2 + hstep, voffB); PG8_STAGE(PG8_SA(0, 0), a2, voffA);
;             PG8_WAIT_V(8); PG8_WAIT_L(0); PG8_BAR; PG8_MMA(1, 0, At, B0); PG8_MMA(1, 1, At, B1); PG8_BAR; PG8_SCHED;
;             PG8_LDB(B0, 1, 0); PG8_LDB(B1, 1, 1); PG8_SCHED; PG8_LDA(At, 1, 0); PG8_STAGE(PG8_SA(0, 1), a2 + hstep, voffA);
;             PG8_WAIT_V(8); PG8_WAIT_L(0); PG8_BAR; PG8_MMA(0, 0, At, B0); PG8_MMA(0, 1, At, B1); PG8_BAR; PG8_SCHED;
	s_setprio 1
	s_waitcnt lgkmcnt(0)
	v_mfma_f32_16x16x32_f16 v[62:65], v[154:157], v[188:191], v[62:65]
	v_mfma_f32_16x16x32_f16 v[58:61], v[164:167], v[188:191], v[58:61]
	v_mfma_f32_16x16x32_f16 v[54:57], v[154:157], v[196:199], v[54:57]
	v_mfma_f32_16x16x32_f16 v[46:49], v[164:167], v[196:199], v[46:49]
	v_mfma_f32_16x16x32_f16 v[38:41], v[154:157], v[204:207], v[38:41]
	v_mfma_f32_16x16x32_f16 v[30:33], v[164:167], v[204:207], v[30:33]
	v_mfma_f32_16x16x32_f16 v[22:25], v[154:157], v[212:215], v[22:25]
	v_mfma_f32_16x16x32_f16 v[14:17], v[164:167], v[212:215], v[14:17]
	v_mfma_f32_16x16x32_f16 v[62:65], v[158:161], v[192:195], v[62:65]
	v_mfma_f32_16x16x32_f16 v[58:61], v[168:171], v[192:195], v[58:61]
	v_mfma_f32_16x16x32_f16 v[54:57], v[158:161], v[200:203], v[54:57]
	v_mfma_f32_16x16x32_f16 v[46:49], v[168:171], v[200:203], v[46:49]
	v_mfma_f32_16x16x32_f16 v[38:41], v[158:161], v[208:211], v[38:41]
	v_mfma_f32_16x16x32_f16 v[30:33], v[168:171], v[208:211], v[30:33]
	v_mfma_f32_16x16x32_f16 v[22:25], v[158:161], v[216:219], v[22:25]
	v_mfma_f32_16x16x32_f16 v[14:17], v[168:171], v[216:219], v[14:17]
	s_setprio 0
	s_setprio 1
	v_mfma_f32_16x16x32_f16 v[50:53], v[172:175], v[188:191], v[50:53]
	v_mfma_f32_16x16x32_f16 v[42:45], v[180:183], v[188:191], v[42:45]
	v_mfma_f32_16x16x32_f16 v[34:37], v[172:175], v[196:199], v[34:37]
	v_mfma_f32_16x16x32_f16 v[26:29], v[180:183], v[196:199], v[26:29]
	v_mfma_f32_16x16x32_f16 v[18:21], v[172:175], v[204:207], v[18:21]
	v_mfma_f32_16x16x32_f16 v[10:13], v[180:183], v[204:207], v[10:13]
	v_mfma_f32_16x16x32_f16 v[6:9], v[172:175], v[212:215], v[6:9]
	v_mfma_f32_16x16x32_f16 v[2:5], v[180:183], v[212:215], v[2:5]
	v_mfma_f32_16x16x32_f16 v[50:53], v[176:179], v[192:195], v[50:53]
	v_mfma_f32_16x16x32_f16 v[42:45], v[184:187], v[192:195], v[42:45]
	v_mfma_f32_16x16x32_f16 v[34:37], v[176:179], v[200:203], v[34:37]
	v_mfma_f32_16x16x32_f16 v[26:29], v[184:187], v[200:203], v[26:29]
	v_mfma_f32_16x16x32_f16 v[18:21], v[176:179], v[208:211], v[18:21]
	v_mfma_f32_16x16x32_f16 v[10:13], v[184:187], v[208:211], v[10:13]
	v_mfma_f32_16x16x32_f16 v[6:9], v[176:179], v[216:219], v[6:9]
	v_mfma_f32_16x16x32_f16 v[2:5], v[184:187], v[216:219], v[2:5]
	s_setprio 0
	s_barrier
	s_add_i32 s77, 0, 0x18000
	v_add_u32_e32 v153, s77, v148
	s_add_i32 s78, 0, 0x1c000
	ds_read_b128 v[154:157], v153
	ds_read_b128 v[158:161], v153 offset:1024
	ds_read_b128 v[164:167], v153 offset:2048
	ds_read_b128 v[168:171], v153 offset:3072
	v_add_u32_e32 v153, s78, v148
	ds_read_b128 v[172:175], v153
	ds_read_b128 v[176:179], v153 offset:1024
	ds_read_b128 v[180:183], v153 offset:2048
	ds_read_b128 v[184:187], v153 offset:3072
	s_add_u32 s22, s22, 0xb0000
	s_addc_u32 s23, s23, 0
	s_mov_b32 m0, s33
	v_lshl_add_u64 v[226:227], s[22:23], 0, v[130:131]
	ds_read_b128 v[188:191], v152 offset:32768
	ds_read_b128 v[192:195], v152 offset:33792
	ds_read_b128 v[196:199], v152 offset:34816
	ds_read_b128 v[200:203], v152 offset:35840
	ds_read_b128 v[204:207], v152 offset:36864
	ds_read_b128 v[208:211], v152 offset:37888
	ds_read_b128 v[212:215], v152 offset:38912
	ds_read_b128 v[216:219], v152 offset:39936
	global_load_lds_dwordx4 v[226:227], off
	v_lshl_add_u64 v[226:227], s[22:23], 0, v[134:135]
	s_mov_b32 m0, s34
	s_nop 0
	global_load_lds_dwordx4 v[226:227], off
	s_waitcnt vmcnt(8)
	s_waitcnt lgkmcnt(0)
	s_barrier
	s_setprio 1
	s_waitcnt lgkmcnt(0)
	v_mfma_f32_16x16x32_f16 v[126:129], v[154:157], v[188:191], v[126:129]
	v_mfma_f32_16x16x32_f16 v[122:125], v[164:167], v[188:191], v[122:125]
	v_mfma_f32_16x16x32_f16 v[118:121], v[154:157], v[196:199], v[118:121]
	v_mfma_f32_16x16x32_f16 v[110:113], v[164:167], v[196:199], v[110:113]
	v_mfma_f32_16x16x32_f16 v[102:105], v[154:157], v[204:207], v[102:105]
	v_mfma_f32_16x16x32_f16 v[94:97], v[164:167], v[204:207], v[94:97]
	v_mfma_f32_16x16x32_f16 v[86:89], v[154:157], v[212:215], v[86:89]
	v_mfma_f32_16x16x32_f16 v[78:81], v[164:167], v[212:215], v[78:81]
	v_mfma_f32_16x16x32_f16 v[126:129], v[158:161], v[192:195], v[126:129]
	v_mfma_f32_16x16x32_f16 v[122:125], v[168:171], v[192:195], v[122:125]
	v_mfma_f32_16x16x32_f16 v[118:121], v[158:161], v[200:203], v[118:121]
	v_mfma_f32_16x16x32_f16 v[110:113], v[168:171], v[200:203], v[110:113]
	v_mfma_f32_16x16x32_f16 v[102:105], v[158:161], v[208:211], v[102:105]
	v_mfma_f32_16x16x32_f16 v[94:97], v[168:171], v[208:211], v[94:97]
	v_mfma_f32_16x16x32_f16 v[86:89], v[158:161], v[216:219], v[86:89]
	v_mfma_f32_16x16x32_f16 v[78:81], v[168:171], v[216:219], v[78:81]
	s_setprio 0
	s_setprio 1
	v_mfma_f32_16x16x32_f16 v[114:117], v[172:175], v[188:191], v[114:117]
	v_mfma_f32_16x16x32_f16 v[106:109], v[180:183], v[188:191], v[106:109]
	v_mfma_f32_16x16x32_f16 v[98:101], v[172:175], v[196:199], v[98:101]
	v_mfma_f32_16x16x32_f16 v[90:93], v[180:183], v[196:199], v[90:93]
	v_mfma_f32_16x16x32_f16 v[82:85], v[172:175], v[204:207], v[82:85]
	v_mfma_f32_16x16x32_f16 v[74:77], v[180:183], v[204:207], v[74:77]
	v_mfma_f32_16x16x32_f16 v[70:73], v[172:175], v[212:215], v[70:73]
	v_mfma_f32_16x16x32_f16 v[66:69], v[180:183], v[212:215], v[66:69]
	v_mfma_f32_16x16x32_f16 v[114:117], v[176:179], v[192:195], v[114:117]
	v_mfma_f32_16x16x32_f16 v[106:109], v[184:187], v[192:195], v[106:109]
	v_mfma_f32_16x16x32_f16 v[98:101], v[176:179], v[200:203], v[98:101]
	v_mfma_f32_16x16x32_f16 v[90:93], v[184:187], v[200:203], v[90:93]
	v_mfma_f32_16x16x32_f16 v[82:85], v[176:179], v[208:211], v[82:85]
	v_mfma_f32_16x16x32_f16 v[74:77], v[184:187], v[208:211], v[74:77]
	v_mfma_f32_16x16x32_f16 v[70:73], v[176:179], v[216:219], v[70:73]
	v_mfma_f32_16x16x32_f16 v[66:69], v[184:187], v[216:219], v[66:69]
	s_setprio 0
	s_barrier
; #define PG8_STAGE(bufoff, gbase, voff) do { _Pragma("unroll") for (int _i = 0; _i < 2; ++_i) \
;         __builtin_amdgcn_global_load_lds((const unsigned*)((const char*)(gbase) + (voff)[_i]), (PG8_LAS unsigned*)(lds + (bufoff) + ldsw + _i * 8192), 16, 0, 0); } while (0)
; #define PG8_LDA(dst, b, h) do { _Pragma("unroll") for (int m = 0; m < 4; ++m) _Pragma("unroll") for (int k = 0; k < 2; ++k) dst[m][k] = *(const PG8_LAS bf16x8*)(lds + PG8_SA(b, h) + aoff + m * 2048 + k * 1024); } while (0)
; #define PG8_LDB(dst, b, h) do { _Pragma("unroll") for (int n = 0; n < 2; ++n) _Pragma("unroll") for (int k = 0; k < 2; ++k) dst[n][k] = *(const PG8_LAS bf16x8*)(lds + PG8_SB(b, h) + boff + n * 2048 + k * 1024); } while (0)
; template <class Epi, class Sched, bool ALIGN_EPI = false, bool SP2 = false>
; __device__ __forceinline__ void gemm_phase(PG8_LAS unsigned char* lds, const Gemm g, const Sched& S, const Epi& E) {
;     ...
;         for (int t = 0; t < nt; t += 2) {
;             const bool last = (t == nt - 2);
;             const char* a1 = cA + (size_t)(t + 1) * kstep;
;             const char* a2 = last ? nA : cA + (size_t)(t + 2) * kstep; const char* b2 = last ? nB : cB + (size_t)(t + 2) * kstep;
;             const char* a3 = a2 + kstep; const char* b3 = b2 + kstep;
;             if (last && has_next) S.a_ready(nxt);
;             if constexpr (SP2) {
;             PG8_LDB(B0, 0, 0); PG8_LDB(B1, 0, 1); PG8_SCHED; PG8_LDA(At, 0, 0); PG8_STAGE(PG8_SA(1, 1), a1 + hstep, voffA);
;             PG8_WAIT_V(8); PG8_WAIT_L(0); PG8_BAR; PG8_MMA(0, 0, At, B0); PG8_MMA(0, 1, At, B1); PG8_BAR; PG8_SCHED;
;             PG8_LDA(At, 0, 1); PG8_STAGE(PG8_SB(0, 0), b2, voffB); PG8_STAGE(PG8_SB(0, 1), b2 + hstep, voffB); PG8_STAGE(PG8_SA(0, 0), a2, voffA);
;             PG8_WAIT_V(8); PG8_WAIT_L(0); PG8_BAR; PG8_MMA(1, 0, At, B0); PG8_MMA(1, 1, At, B1); PG8_BAR; PG8_SCHED;
;             PG8_LDB(B0, 1, 0); PG8_LDB(B1, 1, 1); PG8_SCHED; PG8_LDA(At, 1, 0); PG8_STAGE(PG8_SA(0, 1), a2 + hstep, voffA);
;             PG8_WAIT_V(8); PG8_WAIT_L(0); PG8_BAR; PG8_MMA(0, 0, At, B0); PG8_MMA(0, 1, At, B1); PG8_BAR; PG8_SCHED;
;             PG8_LDA(At, 1, 1); PG8_STAGE(PG8_SB(1, 0), b3, voffB); PG8_STAGE(PG8_SB(1, 1), b3 + hstep, voffB); PG8_STAGE(PG8_SA(1, 0), a3, voffA);
;             PG8_WAIT_V(8); PG8_WAIT_L(0); PG8_BAR; PG8_MMA(1, 0, At, B0); PG8_MMA(1, 1, At, B1); PG8_BAR; PG8_SCHED;
	s_add_i32 s22, s77, s29
	v_lshl_add_u64 v[146:147], v[146:147], 0, s[10:11]
	s_mov_b32 m0, s22
	ds_read_b128 v[188:191], v152 offset:49152
	ds_read_b128 v[192:195], v152 offset:50176
	ds_read_b128 v[196:199], v152 offset:51200
	ds_read_b128 v[200:203], v152 offset:52224
	ds_read_b128 v[204:207], v152 offset:53248
	ds_read_b128 v[208:211], v152 offset:54272
	ds_read_b128 v[212:215], v152 offset:55296
	ds_read_b128 v[216:219], v152 offset:56320
	global_load_lds_dwordx4 v[146:147], off
	s_add_i32 m0, s22, 0x2000
	s_add_u32 s20, s20, 0xb0080
	v_lshl_add_u64 v[146:147], v[220:221], 0, s[10:11]
	s_addc_u32 s21, s21, 0
	s_add_i32 s22, s78, s29
	global_load_lds_dwordx4 v[146:147], off
	v_lshl_add_u64 v[146:147], s[20:21], 0, v[132:133]
	s_mov_b32 m0, s22
	s_nop 0
	global_load_lds_dwordx4 v[146:147], off
	v_lshl_add_u64 v[146:147], s[20:21], 0, v[136:137]
	s_add_i32 m0, s22, 0x2000
	s_nop 0
	global_load_lds_dwordx4 v[146:147], off
	v_lshl_add_u64 v[146:147], v[222:223], 0, s[10:11]
	s_mov_b32 m0, s36
	s_nop 0
	global_load_lds_dwordx4 v[146:147], off
	v_lshl_add_u64 v[146:147], v[224:225], 0, s[10:11]
	s_mov_b32 m0, s37
	s_nop 0
	global_load_lds_dwordx4 v[146:147], off
	s_waitcnt vmcnt(8)
	s_waitcnt lgkmcnt(0)
	s_barrier
	s_setprio 1
	s_waitcnt lgkmcnt(0)
	v_mfma_f32_16x16x32_f16 v[62:65], v[154:157], v[188:191], v[62:65]
	v_mfma_f32_16x16x32_f16 v[58:61], v[164:167], v[188:191], v[58:61]
	v_mfma_f32_16x16x32_f16 v[54:57], v[154:157], v[196:199], v[54:57]
	v_mfma_f32_16x16x32_f16 v[46:49], v[164:167], v[196:199], v[46:49]
	v_mfma_f32_16x16x32_f16 v[38:41], v[154:157], v[204:207], v[38:41]
	v_mfma_f32_16x16x32_f16 v[30:33], v[164:167], v[204:207], v[30:33]
	v_mfma_f32_16x16x32_f16 v[22:25], v[154:157], v[212:215], v[22:25]
	v_mfma_f32_16x16x32_f16 v[14:17], v[164:167], v[212:215], v[14:17]
	v_mfma_f32_16x16x32_f16 v[62:65], v[158:161], v[192:195], v[62:65]
	v_mfma_f32_16x16x32_f16 v[58:61], v[168:171], v[192:195], v[58:61]
	v_mfma_f32_16x16x32_f16 v[54:57], v[158:161], v[200:203], v[54:57]
	v_mfma_f32_16x16x32_f16 v[46:49], v[168:171], v[200:203], v[46:49]
	v_mfma_f32_16x16x32_f16 v[38:41], v[158:161], v[208:211], v[38:41]
	v_mfma_f32_16x16x32_f16 v[30:33], v[168:171], v[208:211], v[30:33]
	v_mfma_f32_16x16x32_f16 v[22:25], v[158:161], v[216:219], v[22:25]
	v_mfma_f32_16x16x32_f16 v[14:17], v[168:171], v[216:219], v[14:17]
	s_setprio 0
	s_setprio 1
	v_mfma_f32_16x16x32_f16 v[50:53], v[172:175], v[188:191], v[50:53]
	v_mfma_f32_16x16x32_f16 v[42:45], v[180:183], v[188:191], v[42:45]
	v_mfma_f32_16x16x32_f16 v[34:37], v[172:175], v[196:199], v[34:37]
	v_mfma_f32_16x16x32_f16 v[26:29], v[180:183], v[196:199], v[26:29]
	v_mfma_f32_16x16x32_f16 v[18:21], v[172:175], v[204:207], v[18:21]
	v_mfma_f32_16x16x32_f16 v[10:13], v[180:183], v[204:207], v[10:13]
	v_mfma_f32_16x16x32_f16 v[6:9], v[172:175], v[212:215], v[6:9]
	v_mfma_f32_16x16x32_f16 v[2:5], v[180:183], v[212:215], v[2:5]
	v_mfma_f32_16x16x32_f16 v[50:53], v[176:179], v[192:195], v[50:53]
	v_mfma_f32_16x16x32_f16 v[42:45], v[184:187], v[192:195], v[42:45]
	v_mfma_f32_16x16x32_f16 v[34:37], v[176:179], v[200:203], v[34:37]
	v_mfma_f32_16x16x32_f16 v[26:29], v[184:187], v[200:203], v[26:29]
	v_mfma_f32_16x16x32_f16 v[18:21], v[176:179], v[208:211], v[18:21]
	v_mfma_f32_16x16x32_f16 v[10:13], v[184:187], v[208:211], v[10:13]
	v_mfma_f32_16x16x32_f16 v[6:9], v[176:179], v[216:219], v[6:9]
	v_mfma_f32_16x16x32_f16 v[2:5], v[184:187], v[216:219], v[2:5]
	s_setprio 0
	s_add_i32 s76, s76, 2
	s_add_u32 s18, s18, 0x100
	s_addc_u32 s19, s19, 0
	s_add_u32 s68, s68, 0x100
	s_addc_u32 s69, s69, 0
	s_cmp_gt_u32 s76, 41
	s_barrier
	s_cbranch_scc0 .LBB0_261
	s_and_b64 vcc, exec, s[12:13]
	s_cbranch_vccz .LBB0_264
	s_barrier

; #define PG8_STAGE(bufoff, gbase, voff) do { _Pragma("unroll") for (int _i = 0; _i < 2; ++_i) \
;         __builtin_amdgcn_global_load_lds((const unsigned*)((const char*)(gbase) + (voff)[_i]), (PG8_LAS unsigned*)(lds + (bufoff) + ldsw + _i * 8192), 16, 0, 0); } while (0)
; #define PG8_LDA(dst, b, h) do { _Pragma("unroll") for (int m = 0; m < 4; ++m) _Pragma("unroll") for (int k = 0; k < 2; ++k) dst[m][k] = *(const PG8_LAS bf16x8*)(lds + PG8_SA(b, h) + aoff + m * 2048 + k * 1024); } while (0)
; #define PG8_LDB(dst, b, h) do { _Pragma("unroll") for (int n = 0; n < 2; ++n) _Pragma("unroll") for (int k = 0; k < 2; ++k) dst[n][k] = *(const PG8_LAS bf16x8*)(lds + PG8_SB(b, h) + boff + n * 2048 + k * 1024); } while (0)
; #define PG8_MMA(ai, bj, At, Bt) do { __builtin_amdgcn_s_setprio(1); _Pragma("unroll") for (int m = 0; m < 4; ++m) _Pragma("unroll") for (int n = 0; n < 2; ++n) _Pragma("unroll") for (int k = 0; k < 2; ++k) \
;         acc[ai][bj][m][n] = __builtin_amdgcn_mfma_f32_16x16x32_f16(H8(Bt[n][k]), H8(At[m][k]), acc[ai][bj][m][n], 0, 0, 0); __builtin_amdgcn_s_setprio(0); } while (0)
; #define PG8_WAIT_V(n) asm volatile("s_waitcnt vmcnt(" #n ")" ::: "memory")
; #define PG8_WAIT_L(n) asm volatile("s_waitcnt lgkmcnt(" #n ")" ::: "memory")
; #define PG8_BAR __builtin_amdgcn_s_barrier()
; #define PG8_SCHED __builtin_amdgcn_sched_barrier(0)
; template <class Epi, class Sched, bool ALIGN_EPI = false, bool SP2 = false>
; __device__ __forceinline__ void gemm_phase(PG8_LAS unsigned char* lds, const Gemm g, const Sched& S, const Epi& E) {
;     ...
;             const bool last = (t == nt - 2);
;             const char* a1 = cA + (size_t)(t + 1) * kstep;
;             const char* a2 = last ? nA : cA + (size_t)(t + 2) * kstep; const char* b2 = last ? nB : cB + (size_t)(t + 2) * kstep;
;             const char* a3 = a2 + kstep; const char* b3 = b2 + kstep;
;             if (last && has_next) S.a_ready(nxt);
;             if constexpr (SP2) {
;             PG8_LDB(B0, 0, 0); PG8_LDB(B1, 0, 1); PG8_SCHED; PG8_LDA(At, 0, 0); PG8_STAGE(PG8_SA(1, 1), a1 + hstep, voffA);
;             PG8_WAIT_V(8); PG8_WAIT_L(0); PG8_BAR; PG8_MMA(0, 0, At, B0); PG8_MMA(0, 1, At, B1); PG8_BAR; PG8_SCHED;
;             PG8_LDA(At, 0, 1); PG8_STAGE(PG8_SB(0, 0), b2, voffB); PG8_STAGE(PG8_SB(0, 1), b2 + hstep, voffB); PG8_STAGE(PG8_SA(0, 0), a2, voffA);
.LBB0_418:
	ds_read_b128 v[138:141], v164
	ds_read_b128 v[168:171], v164 offset:1024
	ds_read_b128 v[172:175], v164 offset:2048
	ds_read_b128 v[176:179], v164 offset:3072
	ds_read_b128 v[180:183], v165
	ds_read_b128 v[184:187], v165 offset:1024
	ds_read_b128 v[188:191], v165 offset:2048
	ds_read_b128 v[192:195], v165 offset:3072
	s_add_u32 s24, s22, 0xfffc0080
	s_addc_u32 s25, s23, -1
	s_cmp_eq_u32 s77, 12
	s_cselect_b32 s27, s15, s25
	s_cselect_b32 s26, s55, s24
	s_cselect_b32 s25, s13, s76
	s_cselect_b32 s24, s68, s69
	v_lshl_add_u64 v[142:143], s[22:23], 0, v[130:131]
	s_add_i32 m0, s21, 0xc000
	ds_read_b128 v[196:199], v166
	ds_read_b128 v[200:203], v166 offset:1024
	ds_read_b128 v[204:207], v166 offset:2048
	ds_read_b128 v[208:211], v166 offset:3072
	ds_read_b128 v[212:215], v166 offset:4096
	ds_read_b128 v[216:219], v166 offset:5120
	ds_read_b128 v[220:223], v166 offset:6144
	ds_read_b128 v[224:227], v166 offset:7168
	global_load_lds_dwordx4 v[142:143], off
	v_lshl_add_u64 v[142:143], s[22:23], 0, v[132:133]
	s_add_i32 m0, s21, 0xe000
	s_nop 0
	global_load_lds_dwordx4 v[142:143], off
	s_waitcnt vmcnt(8)
	s_waitcnt lgkmcnt(0)
	s_barrier
	s_setprio 1
	s_waitcnt lgkmcnt(0)
	v_mfma_f32_16x16x32_f16 v[126:129], v[138:141], v[196:199], v[126:129]
	v_mfma_f32_16x16x32_f16 v[122:125], v[172:175], v[196:199], v[122:125]
	v_mfma_f32_16x16x32_f16 v[110:113], v[138:141], v[204:207], v[110:113]
	v_mfma_f32_16x16x32_f16 v[106:109], v[172:175], v[204:207], v[106:109]
	v_mfma_f32_16x16x32_f16 v[94:97], v[138:141], v[212:215], v[94:97]
	v_mfma_f32_16x16x32_f16 v[90:93], v[172:175], v[212:215], v[90:93]
	v_mfma_f32_16x16x32_f16 v[86:89], v[138:141], v[220:223], v[86:89]
	v_mfma_f32_16x16x32_f16 v[78:81], v[172:175], v[220:223], v[78:81]
	v_mfma_f32_16x16x32_f16 v[126:129], v[168:171], v[200:203], v[126:129]
	v_mfma_f32_16x16x32_f16 v[122:125], v[176:179], v[200:203], v[122:125]
	v_mfma_f32_16x16x32_f16 v[110:113], v[168:171], v[208:211], v[110:113]
	v_mfma_f32_16x16x32_f16 v[106:109], v[176:179], v[208:211], v[106:109]
	v_mfma_f32_16x16x32_f16 v[94:97], v[168:171], v[216:219], v[94:97]
	v_mfma_f32_16x16x32_f16 v[90:93], v[176:179], v[216:219], v[90:93]
	v_mfma_f32_16x16x32_f16 v[86:89], v[168:171], v[224:227], v[86:89]
	v_mfma_f32_16x16x32_f16 v[78:81], v[176:179], v[224:227], v[78:81]
	s_setprio 0
	s_setprio 1
	v_mfma_f32_16x16x32_f16 v[118:121], v[180:183], v[196:199], v[118:121]
	v_mfma_f32_16x16x32_f16 v[114:117], v[188:191], v[196:199], v[114:117]
	v_mfma_f32_16x16x32_f16 v[102:105], v[180:183], v[204:207], v[102:105]
	v_mfma_f32_16x16x32_f16 v[98:101], v[188:191], v[204:207], v[98:101]
	v_mfma_f32_16x16x32_f16 v[82:85], v[180:183], v[212:215], v[82:85]
	v_mfma_f32_16x16x32_f16 v[74:77], v[188:191], v[212:215], v[74:77]
	v_mfma_f32_16x16x32_f16 v[70:73], v[180:183], v[220:223], v[70:73]
	v_mfma_f32_16x16x32_f16 v[66:69], v[188:191], v[220:223], v[66:69]
	v_mfma_f32_16x16x32_f16 v[118:121], v[184:187], v[200:203], v[118:121]
	v_mfma_f32_16x16x32_f16 v[114:117], v[192:195], v[200:203], v[114:117]
	v_mfma_f32_16x16x32_f16 v[102:105], v[184:187], v[208:211], v[102:105]
	v_mfma_f32_16x16x32_f16 v[98:101], v[192:195], v[208:211], v[98:101]
	v_mfma_f32_16x16x32_f16 v[82:85], v[184:187], v[216:219], v[82:85]
	v_mfma_f32_16x16x32_f16 v[74:77], v[192:195], v[216:219], v[74:77]
	v_mfma_f32_16x16x32_f16 v[70:73], v[184:187], v[224:227], v[70:73]
	v_mfma_f32_16x16x32_f16 v[66:69], v[192:195], v[224:227], v[66:69]
	s_setprio 0
	s_barrier
	s_add_i32 s78, s50, s30
	v_lshl_add_u64 v[142:143], s[24:25], 0, v[148:149]
	s_mov_b32 m0, s78
	ds_read_b128 v[196:199], v166 offset:16384
	ds_read_b128 v[200:203], v166 offset:17408
	ds_read_b128 v[204:207], v166 offset:18432
	ds_read_b128 v[208:211], v166 offset:19456
	ds_read_b128 v[212:215], v166 offset:20480
	ds_read_b128 v[216:219], v166 offset:21504
	ds_read_b128 v[220:223], v166 offset:22528
	ds_read_b128 v[224:227], v166 offset:23552
	global_load_lds_dwordx4 v[142:143], off
	s_add_i32 m0, s78, 0x2000
	s_add_u32 s78, s24, 0x40000
	v_lshl_add_u64 v[228:229], s[24:25], 0, v[152:153]
	s_addc_u32 s79, s25, 0
	s_add_i32 s81, s51, s30
	global_load_lds_dwordx4 v[228:229], off
	v_lshl_add_u64 v[230:231], s[78:79], 0, v[148:149]
	s_mov_b32 m0, s81
	v_lshl_add_u64 v[232:233], s[26:27], 0, v[150:151]
	global_load_lds_dwordx4 v[230:231], off
	v_lshl_add_u64 v[230:231], s[78:79], 0, v[152:153]
	s_add_i32 m0, s81, 0x2000
	s_nop 0
	global_load_lds_dwordx4 v[230:231], off
	v_lshl_add_u64 v[230:231], s[26:27], 0, v[146:147]
	s_mov_b32 m0, s21
	s_nop 0
	global_load_lds_dwordx4 v[230:231], off
	s_mov_b32 m0, s34
	s_nop 0
	global_load_lds_dwordx4 v[232:233], off
	s_waitcnt vmcnt(8)
	s_waitcnt lgkmcnt(0)
	s_barrier
; #define PG8_STAGE(bufoff, gbase, voff) do { _Pragma("unroll") for (int _i = 0; _i < 2; ++_i) \
;         __builtin_amdgcn_global_load_lds((const unsigned*)((const char*)(gbase) + (voff)[_i]), (PG8_LAS unsigned*)(lds + (bufoff) + ldsw + _i * 8192), 16, 0, 0); } while (0)
; #define PG8_LDA(dst, b, h) do { _Pragma("unroll") for (int m = 0; m < 4; ++m) _Pragma("unroll") for (int k = 0; k < 2; ++k) dst[m][k] = *(const PG8_LAS bf16x8*)(lds + PG8_SA(b, h) + aoff + m * 2048 + k * 1024); } while (0)
; #define PG8_LDB(dst, b, h) do { _Pragma("unroll") for (int n = 0; n < 2; ++n) _Pragma("unroll") for (int k = 0; k < 2; ++k) dst[n][k] = *(const PG8_LAS bf16x8*)(lds + PG8_SB(b, h) + boff + n * 2048 + k * 1024); } while (0)
; #define PG8_MMA(ai, bj, At, Bt) do { __builtin_amdgcn_s_setprio(1); _Pragma("unroll") for (int m = 0; m < 4; ++m) _Pragma("unroll") for (int n = 0; n < 2; ++n) _Pragma("unroll") for (int k = 0; k < 2; ++k) \
;         acc[ai][bj][m][n] = __builtin_amdgcn_mfma_f32_16x16x32_f16(H8(Bt[n][k]), H8(At[m][k]), acc[ai][bj][m][n], 0, 0, 0); __builtin_amdgcn_s_setprio(0); } while (0)
; #define PG8_WAIT_V(n) asm volatile("s_waitcnt vmcnt(" #n ")" ::: "memory")
; #define PG8_WAIT_L(n) asm volatile("s_waitcnt lgkmcnt(" #n ")" ::: "memory")
; #define PG8_BAR __builtin_amdgcn_s_barrier()
; #define PG8_SCHED __builtin_amdgcn_sched_barrier(0)
; template <class Epi, class Sched, bool ALIGN_EPI = false, bool SP2 = false>
; __device__ __forceinline__ void gemm_phase(PG8_LAS unsigned char* lds, const Gemm g, const Sched& S, const Epi& E) {
;     ...
;             PG8_LDA(At, 0, 1); PG8_STAGE(PG8_SB(0, 0), b2, voffB); PG8_STAGE(PG8_SB(0, 1), b2 + hstep, voffB); PG8_STAGE(PG8_SA(0, 0), a2, voffA);
;             PG8_WAIT_V(8); PG8_WAIT_L(0); PG8_BAR; PG8_MMA(1, 0, At, B0); PG8_MMA(1, 1, At, B1); PG8_BAR; PG8_SCHED;
;             PG8_LDB(B0, 1, 0); PG8_LDB(B1, 1, 1); PG8_SCHED; PG8_LDA(At, 1, 0); PG8_STAGE(PG8_SA(0, 1), a2 + hstep, voffA);
;             PG8_WAIT_V(8); PG8_WAIT_L(0); PG8_BAR; PG8_MMA(0, 0, At, B0); PG8_MMA(0, 1, At, B1); PG8_BAR; PG8_SCHED;
	s_setprio 1
	s_waitcnt lgkmcnt(0)
	v_mfma_f32_16x16x32_f16 v[62:65], v[138:141], v[196:199], v[62:65]
	v_mfma_f32_16x16x32_f16 v[58:61], v[172:175], v[196:199], v[58:61]
	v_mfma_f32_16x16x32_f16 v[46:49], v[138:141], v[204:207], v[46:49]
	v_mfma_f32_16x16x32_f16 v[42:45], v[172:175], v[204:207], v[42:45]
	v_mfma_f32_16x16x32_f16 v[30:33], v[138:141], v[212:215], v[30:33]
	v_mfma_f32_16x16x32_f16 v[26:29], v[172:175], v[212:215], v[26:29]
	v_mfma_f32_16x16x32_f16 v[14:17], v[138:141], v[220:223], v[14:17]
	v_mfma_f32_16x16x32_f16 v[10:13], v[172:175], v[220:223], v[10:13]
	v_mfma_f32_16x16x32_f16 v[62:65], v[168:171], v[200:203], v[62:65]
	v_mfma_f32_16x16x32_f16 v[58:61], v[176:179], v[200:203], v[58:61]
	v_mfma_f32_16x16x32_f16 v[46:49], v[168:171], v[208:211], v[46:49]
	v_mfma_f32_16x16x32_f16 v[42:45], v[176:179], v[208:211], v[42:45]
	v_mfma_f32_16x16x32_f16 v[30:33], v[168:171], v[216:219], v[30:33]
	v_mfma_f32_16x16x32_f16 v[26:29], v[176:179], v[216:219], v[26:29]
	v_mfma_f32_16x16x32_f16 v[14:17], v[168:171], v[224:227], v[14:17]
	v_mfma_f32_16x16x32_f16 v[10:13], v[176:179], v[224:227], v[10:13]
	s_setprio 0
	s_setprio 1
	v_mfma_f32_16x16x32_f16 v[54:57], v[180:183], v[196:199], v[54:57]
	v_mfma_f32_16x16x32_f16 v[50:53], v[188:191], v[196:199], v[50:53]
	v_mfma_f32_16x16x32_f16 v[38:41], v[180:183], v[204:207], v[38:41]
	v_mfma_f32_16x16x32_f16 v[34:37], v[188:191], v[204:207], v[34:37]
	v_mfma_f32_16x16x32_f16 v[22:25], v[180:183], v[212:215], v[22:25]
	v_mfma_f32_16x16x32_f16 v[18:21], v[188:191], v[212:215], v[18:21]
	v_mfma_f32_16x16x32_f16 v[6:9], v[180:183], v[220:223], v[6:9]
	v_mfma_f32_16x16x32_f16 v[2:5], v[188:191], v[220:223], v[2:5]
	v_mfma_f32_16x16x32_f16 v[54:57], v[184:187], v[200:203], v[54:57]
	v_mfma_f32_16x16x32_f16 v[50:53], v[192:195], v[200:203], v[50:53]
	v_mfma_f32_16x16x32_f16 v[38:41], v[184:187], v[208:211], v[38:41]
	v_mfma_f32_16x16x32_f16 v[34:37], v[192:195], v[208:211], v[34:37]
	v_mfma_f32_16x16x32_f16 v[22:25], v[184:187], v[216:219], v[22:25]
	v_mfma_f32_16x16x32_f16 v[18:21], v[192:195], v[216:219], v[18:21]
	v_mfma_f32_16x16x32_f16 v[6:9], v[184:187], v[224:227], v[6:9]
	v_mfma_f32_16x16x32_f16 v[2:5], v[192:195], v[224:227], v[2:5]
	s_setprio 0
	s_barrier
	s_add_i32 s78, 0, 0x18000
	v_add_u32_e32 v167, s78, v160
	s_add_i32 s79, 0, 0x1c000
	ds_read_b128 v[138:141], v167
	ds_read_b128 v[168:171], v167 offset:1024
	ds_read_b128 v[172:175], v167 offset:2048
	ds_read_b128 v[176:179], v167 offset:3072
	v_add_u32_e32 v167, s79, v160
	ds_read_b128 v[180:183], v167
	ds_read_b128 v[184:187], v167 offset:1024
	ds_read_b128 v[188:191], v167 offset:2048
	ds_read_b128 v[192:195], v167 offset:3072
	s_add_u32 s26, s26, 0x40000
	s_addc_u32 s27, s27, 0
	s_mov_b32 m0, s35
	v_lshl_add_u64 v[234:235], s[26:27], 0, v[146:147]
	ds_read_b128 v[196:199], v166 offset:32768
	ds_read_b128 v[200:203], v166 offset:33792
	ds_read_b128 v[204:207], v166 offset:34816
	ds_read_b128 v[208:211], v166 offset:35840
	ds_read_b128 v[212:215], v166 offset:36864
	ds_read_b128 v[216:219], v166 offset:37888
	ds_read_b128 v[220:223], v166 offset:38912
	ds_read_b128 v[224:227], v166 offset:39936
	global_load_lds_dwordx4 v[234:235], off
	v_lshl_add_u64 v[234:235], s[26:27], 0, v[150:151]
	s_mov_b32 m0, s36
	s_nop 0
	global_load_lds_dwordx4 v[234:235], off
	s_waitcnt vmcnt(8)
	s_waitcnt lgkmcnt(0)
	s_barrier
	s_setprio 1
	s_waitcnt lgkmcnt(0)
	v_mfma_f32_16x16x32_f16 v[126:129], v[138:141], v[196:199], v[126:129]
	v_mfma_f32_16x16x32_f16 v[122:125], v[172:175], v[196:199], v[122:125]
	v_mfma_f32_16x16x32_f16 v[110:113], v[138:141], v[204:207], v[110:113]
	v_mfma_f32_16x16x32_f16 v[106:109], v[172:175], v[204:207], v[106:109]
	v_mfma_f32_16x16x32_f16 v[94:97], v[138:141], v[212:215], v[94:97]
	v_mfma_f32_16x16x32_f16 v[90:93], v[172:175], v[212:215], v[90:93]
	v_mfma_f32_16x16x32_f16 v[86:89], v[138:141], v[220:223], v[86:89]
	v_mfma_f32_16x16x32_f16 v[78:81], v[172:175], v[220:223], v[78:81]
	v_mfma_f32_16x16x32_f16 v[126:129], v[168:171], v[200:203], v[126:129]
	v_mfma_f32_16x16x32_f16 v[122:125], v[176:179], v[200:203], v[122:125]
	v_mfma_f32_16x16x32_f16 v[110:113], v[168:171], v[208:211], v[110:113]
	v_mfma_f32_16x16x32_f16 v[106:109], v[176:179], v[208:211], v[106:109]
	v_mfma_f32_16x16x32_f16 v[94:97], v[168:171], v[216:219], v[94:97]
	v_mfma_f32_16x16x32_f16 v[90:93], v[176:179], v[216:219], v[90:93]
	v_mfma_f32_16x16x32_f16 v[86:89], v[168:171], v[224:227], v[86:89]
	v_mfma_f32_16x16x32_f16 v[78:81], v[176:179], v[224:227], v[78:81]
	s_setprio 0
	s_setprio 1
	v_mfma_f32_16x16x32_f16 v[118:121], v[180:183], v[196:199], v[118:121]
	v_mfma_f32_16x16x32_f16 v[114:117], v[188:191], v[196:199], v[114:117]
	v_mfma_f32_16x16x32_f16 v[102:105], v[180:183], v[204:207], v[102:105]
	v_mfma_f32_16x16x32_f16 v[98:101], v[188:191], v[204:207], v[98:101]
	v_mfma_f32_16x16x32_f16 v[82:85], v[180:183], v[212:215], v[82:85]
	v_mfma_f32_16x16x32_f16 v[74:77], v[188:191], v[212:215], v[74:77]
	v_mfma_f32_16x16x32_f16 v[70:73], v[180:183], v[220:223], v[70:73]
	v_mfma_f32_16x16x32_f16 v[66:69], v[188:191], v[220:223], v[66:69]
	v_mfma_f32_16x16x32_f16 v[118:121], v[184:187], v[200:203], v[118:121]
	v_mfma_f32_16x16x32_f16 v[114:117], v[192:195], v[200:203], v[114:117]
	v_mfma_f32_16x16x32_f16 v[102:105], v[184:187], v[208:211], v[102:105]
	v_mfma_f32_16x16x32_f16 v[98:101], v[192:195], v[208:211], v[98:101]
	v_mfma_f32_16x16x32_f16 v[82:85], v[184:187], v[216:219], v[82:85]
	v_mfma_f32_16x16x32_f16 v[74:77], v[192:195], v[216:219], v[74:77]
	v_mfma_f32_16x16x32_f16 v[70:73], v[184:187], v[224:227], v[70:73]
	v_mfma_f32_16x16x32_f16 v[66:69], v[192:195], v[224:227], v[66:69]
	s_setprio 0
	s_barrier
; #define PG8_STAGE(bufoff, gbase, voff) do { _Pragma("unroll") for (int _i = 0; _i < 2; ++_i) \
;         __builtin_amdgcn_global_load_lds((const unsigned*)((const char*)(gbase) + (voff)[_i]), (PG8_LAS unsigned*)(lds + (bufoff) + ldsw + _i * 8192), 16, 0, 0); } while (0)
; #define PG8_LDA(dst, b, h) do { _Pragma("unroll") for (int m = 0; m < 4; ++m) _Pragma("unroll") for (int k = 0; k < 2; ++k) dst[m][k] = *(const PG8_LAS bf16x8*)(lds + PG8_SA(b, h) + aoff + m * 2048 + k * 1024); } while (0)
; #define PG8_LDB(dst, b, h) do { _Pragma("unroll") for (int n = 0; n < 2; ++n) _Pragma("unroll") for (int k = 0; k < 2; ++k) dst[n][k] = *(const PG8_LAS bf16x8*)(lds + PG8_SB(b, h) + boff + n * 2048 + k * 1024); } while (0)
; template <class Epi, class Sched, bool ALIGN_EPI = false, bool SP2 = false>
; __device__ __forceinline__ void gemm_phase(PG8_LAS unsigned char* lds, const Gemm g, const Sched& S, const Epi& E) {
;     ...
;         for (int t = 0; t < nt; t += 2) {
;             const bool last = (t == nt - 2);
;             const char* a1 = cA + (size_t)(t + 1) * kstep;
;             const char* a2 = last ? nA : cA + (size_t)(t + 2) * kstep; const char* b2 = last ? nB : cB + (size_t)(t + 2) * kstep;
;             const char* a3 = a2 + kstep; const char* b3 = b2 + kstep;
;             if (last && has_next) S.a_ready(nxt);
;             if constexpr (SP2) {
;             PG8_LDB(B0, 0, 0); PG8_LDB(B1, 0, 1); PG8_SCHED; PG8_LDA(At, 0, 0); PG8_STAGE(PG8_SA(1, 1), a1 + hstep, voffA);
;             PG8_WAIT_V(8); PG8_WAIT_L(0); PG8_BAR; PG8_MMA(0, 0, At, B0); PG8_MMA(0, 1, At, B1); PG8_BAR; PG8_SCHED;
;             PG8_LDA(At, 0, 1); PG8_STAGE(PG8_SB(0, 0), b2, voffB); PG8_STAGE(PG8_SB(0, 1), b2 + hstep, voffB); PG8_STAGE(PG8_SA(0, 0), a2, voffA);
;             PG8_WAIT_V(8); PG8_WAIT_L(0); PG8_BAR; PG8_MMA(1, 0, At, B0); PG8_MMA(1, 1, At, B1); PG8_BAR; PG8_SCHED;
;             PG8_LDB(B0, 1, 0); PG8_LDB(B1, 1, 1); PG8_SCHED; PG8_LDA(At, 1, 0); PG8_STAGE(PG8_SA(0, 1), a2 + hstep, voffA);
;             PG8_WAIT_V(8); PG8_WAIT_L(0); PG8_BAR; PG8_MMA(0, 0, At, B0); PG8_MMA(0, 1, At, B1); PG8_BAR; PG8_SCHED;
;             PG8_LDA(At, 1, 1); PG8_STAGE(PG8_SB(1, 0), b3, voffB); PG8_STAGE(PG8_SB(1, 1), b3 + hstep, voffB); PG8_STAGE(PG8_SA(1, 0), a3, voffA);
;             PG8_WAIT_V(8); PG8_WAIT_L(0); PG8_BAR; PG8_MMA(1, 0, At, B0); PG8_MMA(1, 1, At, B1); PG8_BAR; PG8_SCHED;
	s_add_i32 s26, s78, s30
	v_lshl_add_u64 v[142:143], v[142:143], 0, s[8:9]
	s_mov_b32 m0, s26
	ds_read_b128 v[196:199], v166 offset:49152
	ds_read_b128 v[200:203], v166 offset:50176
	ds_read_b128 v[204:207], v166 offset:51200
	ds_read_b128 v[208:211], v166 offset:52224
	ds_read_b128 v[212:215], v166 offset:53248
	ds_read_b128 v[216:219], v166 offset:54272
	ds_read_b128 v[220:223], v166 offset:55296
	ds_read_b128 v[224:227], v166 offset:56320
	global_load_lds_dwordx4 v[142:143], off
	s_add_i32 m0, s26, 0x2000
	s_add_u32 s24, s24, 0x40080
	v_lshl_add_u64 v[142:143], v[228:229], 0, s[8:9]
	s_addc_u32 s25, s25, 0
	s_add_i32 s26, s79, s30
	global_load_lds_dwordx4 v[142:143], off
	v_lshl_add_u64 v[142:143], s[24:25], 0, v[148:149]
	s_mov_b32 m0, s26
	s_nop 0
	global_load_lds_dwordx4 v[142:143], off
	v_lshl_add_u64 v[142:143], s[24:25], 0, v[152:153]
	s_add_i32 m0, s26, 0x2000
	s_nop 0
	global_load_lds_dwordx4 v[142:143], off
	v_lshl_add_u64 v[142:143], v[230:231], 0, s[8:9]
	s_mov_b32 m0, s44
	s_nop 0
	global_load_lds_dwordx4 v[142:143], off
	v_lshl_add_u64 v[142:143], v[232:233], 0, s[8:9]
	s_mov_b32 m0, s45
	s_nop 0
	global_load_lds_dwordx4 v[142:143], off
	s_waitcnt vmcnt(8)
	s_waitcnt lgkmcnt(0)
	s_barrier
	s_setprio 1
	s_waitcnt lgkmcnt(0)
	v_mfma_f32_16x16x32_f16 v[62:65], v[138:141], v[196:199], v[62:65]
	v_mfma_f32_16x16x32_f16 v[58:61], v[172:175], v[196:199], v[58:61]
	v_mfma_f32_16x16x32_f16 v[46:49], v[138:141], v[204:207], v[46:49]
	v_mfma_f32_16x16x32_f16 v[42:45], v[172:175], v[204:207], v[42:45]
	v_mfma_f32_16x16x32_f16 v[30:33], v[138:141], v[212:215], v[30:33]
	v_mfma_f32_16x16x32_f16 v[26:29], v[172:175], v[212:215], v[26:29]
	v_mfma_f32_16x16x32_f16 v[14:17], v[138:141], v[220:223], v[14:17]
	v_mfma_f32_16x16x32_f16 v[10:13], v[172:175], v[220:223], v[10:13]
	v_mfma_f32_16x16x32_f16 v[62:65], v[168:171], v[200:203], v[62:65]
	v_mfma_f32_16x16x32_f16 v[58:61], v[176:179], v[200:203], v[58:61]
	v_mfma_f32_16x16x32_f16 v[46:49], v[168:171], v[208:211], v[46:49]
	v_mfma_f32_16x16x32_f16 v[42:45], v[176:179], v[208:211], v[42:45]
	v_mfma_f32_16x16x32_f16 v[30:33], v[168:171], v[216:219], v[30:33]
	v_mfma_f32_16x16x32_f16 v[26:29], v[176:179], v[216:219], v[26:29]
	v_mfma_f32_16x16x32_f16 v[14:17], v[168:171], v[224:227], v[14:17]
	v_mfma_f32_16x16x32_f16 v[10:13], v[176:179], v[224:227], v[10:13]
	s_setprio 0
	s_setprio 1
	v_mfma_f32_16x16x32_f16 v[54:57], v[180:183], v[196:199], v[54:57]
	v_mfma_f32_16x16x32_f16 v[50:53], v[188:191], v[196:199], v[50:53]
	v_mfma_f32_16x16x32_f16 v[38:41], v[180:183], v[204:207], v[38:41]
	v_mfma_f32_16x16x32_f16 v[34:37], v[188:191], v[204:207], v[34:37]
	v_mfma_f32_16x16x32_f16 v[22:25], v[180:183], v[212:215], v[22:25]
	v_mfma_f32_16x16x32_f16 v[18:21], v[188:191], v[212:215], v[18:21]
	v_mfma_f32_16x16x32_f16 v[6:9], v[180:183], v[220:223], v[6:9]
	v_mfma_f32_16x16x32_f16 v[2:5], v[188:191], v[220:223], v[2:5]
	v_mfma_f32_16x16x32_f16 v[54:57], v[184:187], v[200:203], v[54:57]
	v_mfma_f32_16x16x32_f16 v[50:53], v[192:195], v[200:203], v[50:53]
	v_mfma_f32_16x16x32_f16 v[38:41], v[184:187], v[208:211], v[38:41]
	v_mfma_f32_16x16x32_f16 v[34:37], v[192:195], v[208:211], v[34:37]
	v_mfma_f32_16x16x32_f16 v[22:25], v[184:187], v[216:219], v[22:25]
	v_mfma_f32_16x16x32_f16 v[18:21], v[192:195], v[216:219], v[18:21]
	v_mfma_f32_16x16x32_f16 v[6:9], v[184:187], v[224:227], v[6:9]
	v_mfma_f32_16x16x32_f16 v[2:5], v[192:195], v[224:227], v[2:5]
	s_setprio 0
	s_add_i32 s77, s77, 2
	s_add_u32 s22, s22, 0x100
	s_addc_u32 s23, s23, 0
	s_add_u32 s69, s69, 0x100
	s_addc_u32 s76, s76, 0
	s_cmp_gt_u32 s77, 13
	s_barrier
	s_cbranch_scc0 .LBB0_418
	s_and_b64 vcc, exec, s[10:11]
	s_cbranch_vccz .LBB0_421
	s_barrier

; #define PG8_STAGE(bufoff, gbase, voff) do { _Pragma("unroll") for (int _i = 0; _i < 2; ++_i) \
;         __builtin_amdgcn_global_load_lds((const unsigned*)((const char*)(gbase) + (voff)[_i]), (PG8_LAS unsigned*)(lds + (bufoff) + ldsw + _i * 8192), 16, 0, 0); } while (0)
; #define PG8_LDA(dst, b, h) do { _Pragma("unroll") for (int m = 0; m < 4; ++m) _Pragma("unroll") for (int k = 0; k < 2; ++k) dst[m][k] = *(const PG8_LAS bf16x8*)(lds + PG8_SA(b, h) + aoff + m * 2048 + k * 1024); } while (0)
; #define PG8_LDB(dst, b, h) do { _Pragma("unroll") for (int n = 0; n < 2; ++n) _Pragma("unroll") for (int k = 0; k < 2; ++k) dst[n][k] = *(const PG8_LAS bf16x8*)(lds + PG8_SB(b, h) + boff + n * 2048 + k * 1024); } while (0)
; #define PG8_MMA(ai, bj, At, Bt) do { __builtin_amdgcn_s_setprio(1); _Pragma("unroll") for (int m = 0; m < 4; ++m) _Pragma("unroll") for (int n = 0; n < 2; ++n) _Pragma("unroll") for (int k = 0; k < 2; ++k) \
;         acc[ai][bj][m][n] = __builtin_amdgcn_mfma_f32_16x16x32_f16(H8(Bt[n][k]), H8(At[m][k]), acc[ai][bj][m][n], 0, 0, 0); __builtin_amdgcn_s_setprio(0); } while (0)
; #define PG8_WAIT_V(n) asm volatile("s_waitcnt vmcnt(" #n ")" ::: "memory")
; #define PG8_WAIT_L(n) asm volatile("s_waitcnt lgkmcnt(" #n ")" ::: "memory")
; #define PG8_BAR __builtin_amdgcn_s_barrier()
; #define PG8_SCHED __builtin_amdgcn_sched_barrier(0)
; template <class Epi, class Sched, bool ALIGN_EPI = false, bool SP2 = false>
; __device__ __forceinline__ void gemm_phase(PG8_LAS unsigned char* lds, const Gemm g, const Sched& S, const Epi& E) {
;     ...
;             const bool last = (t == nt - 2);
;             const char* a1 = cA + (size_t)(t + 1) * kstep;
;             const char* a2 = last ? nA : cA + (size_t)(t + 2) * kstep; const char* b2 = last ? nB : cB + (size_t)(t + 2) * kstep;
;             const char* a3 = a2 + kstep; const char* b3 = b2 + kstep;
;             if (last && has_next) S.a_ready(nxt);
;             if constexpr (SP2) {
;             PG8_LDB(B0, 0, 0); PG8_LDB(B1, 0, 1); PG8_SCHED; PG8_LDA(At, 0, 0); PG8_STAGE(PG8_SA(1, 1), a1 + hstep, voffA);
;             PG8_WAIT_V(8); PG8_WAIT_L(0); PG8_BAR; PG8_MMA(0, 0, At, B0); PG8_MMA(0, 1, At, B1); PG8_BAR; PG8_SCHED;
;             PG8_LDA(At, 0, 1); PG8_STAGE(PG8_SB(0, 0), b2, voffB); PG8_STAGE(PG8_SB(0, 1), b2 + hstep, voffB); PG8_STAGE(PG8_SA(0, 0), a2, voffA);
.LBB0_442:
	ds_read_b128 v[130:133], v1
	ds_read_b128 v[134:137], v1 offset:1024
	ds_read_b128 v[138:141], v1 offset:2048
	ds_read_b128 v[142:145], v1 offset:3072
	ds_read_b128 v[172:175], v169
	ds_read_b128 v[176:179], v169 offset:1024
	ds_read_b128 v[180:183], v169 offset:2048
	ds_read_b128 v[184:187], v169 offset:3072
	s_add_u32 s28, s26, 0xfffc0080
	s_addc_u32 s29, s27, -1
	s_cmp_eq_u32 s81, 12
	s_cselect_b32 s31, s19, s29
	s_cselect_b32 s30, s76, s28
	s_cselect_b32 s29, s17, s79
	s_cselect_b32 s28, s77, s78
	v_lshl_add_u64 v[164:165], s[26:27], 0, v[154:155]
	s_add_i32 m0, s25, 0xc000
	ds_read_b128 v[188:191], v170
	ds_read_b128 v[192:195], v170 offset:1024
	ds_read_b128 v[196:199], v170 offset:2048
	ds_read_b128 v[200:203], v170 offset:3072
	ds_read_b128 v[204:207], v170 offset:4096
	ds_read_b128 v[208:211], v170 offset:5120
	ds_read_b128 v[212:215], v170 offset:6144
	ds_read_b128 v[216:219], v170 offset:7168
	global_load_lds_dwordx4 v[164:165], off
	v_lshl_add_u64 v[164:165], s[26:27], 0, v[156:157]
	s_add_i32 m0, s25, 0xe000
	s_nop 0
	global_load_lds_dwordx4 v[164:165], off
	s_waitcnt vmcnt(8)
	s_waitcnt lgkmcnt(0)
	s_barrier
	s_setprio 1
	s_waitcnt lgkmcnt(0)
	v_mfma_f32_16x16x32_f16 v[126:129], v[130:133], v[188:191], v[126:129]
	v_mfma_f32_16x16x32_f16 v[122:125], v[138:141], v[188:191], v[122:125]
	v_mfma_f32_16x16x32_f16 v[118:121], v[130:133], v[196:199], v[118:121]
	v_mfma_f32_16x16x32_f16 v[114:117], v[138:141], v[196:199], v[114:117]
	v_mfma_f32_16x16x32_f16 v[110:113], v[130:133], v[204:207], v[110:113]
	v_mfma_f32_16x16x32_f16 v[102:105], v[138:141], v[204:207], v[102:105]
	v_mfma_f32_16x16x32_f16 v[94:97], v[130:133], v[212:215], v[94:97]
	v_mfma_f32_16x16x32_f16 v[86:89], v[138:141], v[212:215], v[86:89]
	v_mfma_f32_16x16x32_f16 v[126:129], v[134:137], v[192:195], v[126:129]
	v_mfma_f32_16x16x32_f16 v[122:125], v[142:145], v[192:195], v[122:125]
	v_mfma_f32_16x16x32_f16 v[118:121], v[134:137], v[200:203], v[118:121]
	v_mfma_f32_16x16x32_f16 v[114:117], v[142:145], v[200:203], v[114:117]
	v_mfma_f32_16x16x32_f16 v[110:113], v[134:137], v[208:211], v[110:113]
	v_mfma_f32_16x16x32_f16 v[102:105], v[142:145], v[208:211], v[102:105]
	v_mfma_f32_16x16x32_f16 v[94:97], v[134:137], v[216:219], v[94:97]
	v_mfma_f32_16x16x32_f16 v[86:89], v[142:145], v[216:219], v[86:89]
	s_setprio 0
	s_setprio 1
	v_mfma_f32_16x16x32_f16 v[106:109], v[172:175], v[188:191], v[106:109]
	v_mfma_f32_16x16x32_f16 v[98:101], v[180:183], v[188:191], v[98:101]
	v_mfma_f32_16x16x32_f16 v[90:93], v[172:175], v[196:199], v[90:93]
	v_mfma_f32_16x16x32_f16 v[82:85], v[180:183], v[196:199], v[82:85]
	v_mfma_f32_16x16x32_f16 v[78:81], v[172:175], v[204:207], v[78:81]
	v_mfma_f32_16x16x32_f16 v[74:77], v[180:183], v[204:207], v[74:77]
	v_mfma_f32_16x16x32_f16 v[70:73], v[172:175], v[212:215], v[70:73]
	v_mfma_f32_16x16x32_f16 v[66:69], v[180:183], v[212:215], v[66:69]
	v_mfma_f32_16x16x32_f16 v[106:109], v[176:179], v[192:195], v[106:109]
	v_mfma_f32_16x16x32_f16 v[98:101], v[184:187], v[192:195], v[98:101]
	v_mfma_f32_16x16x32_f16 v[90:93], v[176:179], v[200:203], v[90:93]
	v_mfma_f32_16x16x32_f16 v[82:85], v[184:187], v[200:203], v[82:85]
	v_mfma_f32_16x16x32_f16 v[78:81], v[176:179], v[208:211], v[78:81]
	v_mfma_f32_16x16x32_f16 v[74:77], v[184:187], v[208:211], v[74:77]
	v_mfma_f32_16x16x32_f16 v[70:73], v[176:179], v[216:219], v[70:73]
	v_mfma_f32_16x16x32_f16 v[66:69], v[184:187], v[216:219], v[66:69]
	s_setprio 0
	s_barrier
	s_add_i32 s83, s53, s36
	v_lshl_add_u64 v[164:165], s[28:29], 0, v[148:149]
	s_mov_b32 m0, s83
	ds_read_b128 v[188:191], v170 offset:16384
	ds_read_b128 v[192:195], v170 offset:17408
	ds_read_b128 v[196:199], v170 offset:18432
	ds_read_b128 v[200:203], v170 offset:19456
	ds_read_b128 v[204:207], v170 offset:20480
	ds_read_b128 v[208:211], v170 offset:21504
	ds_read_b128 v[212:215], v170 offset:22528
	ds_read_b128 v[216:219], v170 offset:23552
	global_load_lds_dwordx4 v[164:165], off
	s_add_i32 m0, s83, 0x2000
	s_add_u32 s84, s28, 0x40000
	v_lshl_add_u64 v[220:221], s[28:29], 0, v[152:153]
	s_addc_u32 s85, s29, 0
	s_add_i32 s83, s54, s36
	global_load_lds_dwordx4 v[220:221], off
	v_lshl_add_u64 v[222:223], s[84:85], 0, v[148:149]
	s_mov_b32 m0, s83
	v_lshl_add_u64 v[224:225], s[30:31], 0, v[150:151]
	global_load_lds_dwordx4 v[222:223], off
	v_lshl_add_u64 v[222:223], s[84:85], 0, v[152:153]
	s_add_i32 m0, s83, 0x2000
	s_nop 0
	global_load_lds_dwordx4 v[222:223], off
	v_lshl_add_u64 v[222:223], s[30:31], 0, v[146:147]
	s_mov_b32 m0, s25
	s_nop 0
	global_load_lds_dwordx4 v[222:223], off
	s_mov_b32 m0, s37
	s_nop 0
	global_load_lds_dwordx4 v[224:225], off
	s_waitcnt vmcnt(8)
	s_waitcnt lgkmcnt(0)
	s_barrier
; #define PG8_STAGE(bufoff, gbase, voff) do { _Pragma("unroll") for (int _i = 0; _i < 2; ++_i) \
;         __builtin_amdgcn_global_load_lds((const unsigned*)((const char*)(gbase) + (voff)[_i]), (PG8_LAS unsigned*)(lds + (bufoff) + ldsw + _i * 8192), 16, 0, 0); } while (0)
; #define PG8_LDA(dst, b, h) do { _Pragma("unroll") for (int m = 0; m < 4; ++m) _Pragma("unroll") for (int k = 0; k < 2; ++k) dst[m][k] = *(const PG8_LAS bf16x8*)(lds + PG8_SA(b, h) + aoff + m * 2048 + k * 1024); } while (0)
; #define PG8_LDB(dst, b, h) do { _Pragma("unroll") for (int n = 0; n < 2; ++n) _Pragma("unroll") for (int k = 0; k < 2; ++k) dst[n][k] = *(const PG8_LAS bf16x8*)(lds + PG8_SB(b, h) + boff + n * 2048 + k * 1024); } while (0)
; #define PG8_MMA(ai, bj, At, Bt) do { __builtin_amdgcn_s_setprio(1); _Pragma("unroll") for (int m = 0; m < 4; ++m) _Pragma("unroll") for (int n = 0; n < 2; ++n) _Pragma("unroll") for (int k = 0; k < 2; ++k) \
;         acc[ai][bj][m][n] = __builtin_amdgcn_mfma_f32_16x16x32_f16(H8(Bt[n][k]), H8(At[m][k]), acc[ai][bj][m][n], 0, 0, 0); __builtin_amdgcn_s_setprio(0); } while (0)
; #define PG8_WAIT_V(n) asm volatile("s_waitcnt vmcnt(" #n ")" ::: "memory")
; #define PG8_WAIT_L(n) asm volatile("s_waitcnt lgkmcnt(" #n ")" ::: "memory")
; #define PG8_BAR __builtin_amdgcn_s_barrier()
; #define PG8_SCHED __builtin_amdgcn_sched_barrier(0)
; template <class Epi, class Sched, bool ALIGN_EPI = false, bool SP2 = false>
; __device__ __forceinline__ void gemm_phase(PG8_LAS unsigned char* lds, const Gemm g, const Sched& S, const Epi& E) {
;     ...
;             PG8_LDA(At, 0, 1); PG8_STAGE(PG8_SB(0, 0), b2, voffB); PG8_STAGE(PG8_SB(0, 1), b2 + hstep, voffB); PG8_STAGE(PG8_SA(0, 0), a2, voffA);
;             PG8_WAIT_V(8); PG8_WAIT_L(0); PG8_BAR; PG8_MMA(1, 0, At, B0); PG8_MMA(1, 1, At, B1); PG8_BAR; PG8_SCHED;
;             PG8_LDB(B0, 1, 0); PG8_LDB(B1, 1, 1); PG8_SCHED; PG8_LDA(At, 1, 0); PG8_STAGE(PG8_SA(0, 1), a2 + hstep, voffA);
;             PG8_WAIT_V(8); PG8_WAIT_L(0); PG8_BAR; PG8_MMA(0, 0, At, B0); PG8_MMA(0, 1, At, B1); PG8_BAR; PG8_SCHED;
	s_setprio 1
	s_waitcnt lgkmcnt(0)
	v_mfma_f32_16x16x32_f16 v[62:65], v[130:133], v[188:191], v[62:65]
	v_mfma_f32_16x16x32_f16 v[58:61], v[138:141], v[188:191], v[58:61]
	v_mfma_f32_16x16x32_f16 v[50:53], v[130:133], v[196:199], v[50:53]
	v_mfma_f32_16x16x32_f16 v[42:45], v[138:141], v[196:199], v[42:45]
	v_mfma_f32_16x16x32_f16 v[34:37], v[130:133], v[204:207], v[34:37]
	v_mfma_f32_16x16x32_f16 v[26:29], v[138:141], v[204:207], v[26:29]
	v_mfma_f32_16x16x32_f16 v[18:21], v[130:133], v[212:215], v[18:21]
	v_mfma_f32_16x16x32_f16 v[10:13], v[138:141], v[212:215], v[10:13]
	v_mfma_f32_16x16x32_f16 v[62:65], v[134:137], v[192:195], v[62:65]
	v_mfma_f32_16x16x32_f16 v[58:61], v[142:145], v[192:195], v[58:61]
	v_mfma_f32_16x16x32_f16 v[50:53], v[134:137], v[200:203], v[50:53]
	v_mfma_f32_16x16x32_f16 v[42:45], v[142:145], v[200:203], v[42:45]
	v_mfma_f32_16x16x32_f16 v[34:37], v[134:137], v[208:211], v[34:37]
	v_mfma_f32_16x16x32_f16 v[26:29], v[142:145], v[208:211], v[26:29]
	v_mfma_f32_16x16x32_f16 v[18:21], v[134:137], v[216:219], v[18:21]
	v_mfma_f32_16x16x32_f16 v[10:13], v[142:145], v[216:219], v[10:13]
	s_setprio 0
	s_setprio 1
	v_mfma_f32_16x16x32_f16 v[54:57], v[172:175], v[188:191], v[54:57]
	v_mfma_f32_16x16x32_f16 v[46:49], v[180:183], v[188:191], v[46:49]
	v_mfma_f32_16x16x32_f16 v[38:41], v[172:175], v[196:199], v[38:41]
	v_mfma_f32_16x16x32_f16 v[30:33], v[180:183], v[196:199], v[30:33]
	v_mfma_f32_16x16x32_f16 v[22:25], v[172:175], v[204:207], v[22:25]
	v_mfma_f32_16x16x32_f16 v[14:17], v[180:183], v[204:207], v[14:17]
	v_mfma_f32_16x16x32_f16 v[6:9], v[172:175], v[212:215], v[6:9]
	v_mfma_f32_16x16x32_f16 v[2:5], v[180:183], v[212:215], v[2:5]
	v_mfma_f32_16x16x32_f16 v[54:57], v[176:179], v[192:195], v[54:57]
	v_mfma_f32_16x16x32_f16 v[46:49], v[184:187], v[192:195], v[46:49]
	v_mfma_f32_16x16x32_f16 v[38:41], v[176:179], v[200:203], v[38:41]
	v_mfma_f32_16x16x32_f16 v[30:33], v[184:187], v[200:203], v[30:33]
	v_mfma_f32_16x16x32_f16 v[22:25], v[176:179], v[208:211], v[22:25]
	v_mfma_f32_16x16x32_f16 v[14:17], v[184:187], v[208:211], v[14:17]
	v_mfma_f32_16x16x32_f16 v[6:9], v[176:179], v[216:219], v[6:9]
	v_mfma_f32_16x16x32_f16 v[2:5], v[184:187], v[216:219], v[2:5]
	s_setprio 0
	s_barrier
	s_add_i32 s83, 0, 0x18000
	s_add_i32 s84, 0, 0x1c000
	v_add_u32_e32 v142, s83, v167
	v_add_u32_e32 v171, s84, v167
	ds_read_b128 v[130:133], v142
	ds_read_b128 v[134:137], v142 offset:1024
	ds_read_b128 v[138:141], v142 offset:2048
	ds_read_b128 v[142:145], v142 offset:3072
	ds_read_b128 v[172:175], v171
	ds_read_b128 v[176:179], v171 offset:1024
	ds_read_b128 v[180:183], v171 offset:2048
	ds_read_b128 v[184:187], v171 offset:3072
	s_add_u32 s30, s30, 0x40000
	s_addc_u32 s31, s31, 0
	s_mov_b32 m0, s44
	v_lshl_add_u64 v[226:227], s[30:31], 0, v[146:147]
	ds_read_b128 v[188:191], v170 offset:32768
	ds_read_b128 v[192:195], v170 offset:33792
	ds_read_b128 v[196:199], v170 offset:34816
	ds_read_b128 v[200:203], v170 offset:35840
	ds_read_b128 v[204:207], v170 offset:36864
	ds_read_b128 v[208:211], v170 offset:37888
	ds_read_b128 v[212:215], v170 offset:38912
	ds_read_b128 v[216:219], v170 offset:39936
	global_load_lds_dwordx4 v[226:227], off
	v_lshl_add_u64 v[226:227], s[30:31], 0, v[150:151]
	s_mov_b32 m0, s45
	s_nop 0
	global_load_lds_dwordx4 v[226:227], off
	s_waitcnt vmcnt(8)
	s_waitcnt lgkmcnt(0)
	s_barrier
	s_setprio 1
	s_waitcnt lgkmcnt(0)
	v_mfma_f32_16x16x32_f16 v[126:129], v[130:133], v[188:191], v[126:129]
	v_mfma_f32_16x16x32_f16 v[122:125], v[138:141], v[188:191], v[122:125]
	v_mfma_f32_16x16x32_f16 v[118:121], v[130:133], v[196:199], v[118:121]
	v_mfma_f32_16x16x32_f16 v[114:117], v[138:141], v[196:199], v[114:117]
	v_mfma_f32_16x16x32_f16 v[110:113], v[130:133], v[204:207], v[110:113]
	v_mfma_f32_16x16x32_f16 v[102:105], v[138:141], v[204:207], v[102:105]
	v_mfma_f32_16x16x32_f16 v[94:97], v[130:133], v[212:215], v[94:97]
	v_mfma_f32_16x16x32_f16 v[86:89], v[138:141], v[212:215], v[86:89]
	v_mfma_f32_16x16x32_f16 v[126:129], v[134:137], v[192:195], v[126:129]
	v_mfma_f32_16x16x32_f16 v[122:125], v[142:145], v[192:195], v[122:125]
	v_mfma_f32_16x16x32_f16 v[118:121], v[134:137], v[200:203], v[118:121]
	v_mfma_f32_16x16x32_f16 v[114:117], v[142:145], v[200:203], v[114:117]
	v_mfma_f32_16x16x32_f16 v[110:113], v[134:137], v[208:211], v[110:113]
	v_mfma_f32_16x16x32_f16 v[102:105], v[142:145], v[208:211], v[102:105]
	v_mfma_f32_16x16x32_f16 v[94:97], v[134:137], v[216:219], v[94:97]
	v_mfma_f32_16x16x32_f16 v[86:89], v[142:145], v[216:219], v[86:89]
	s_setprio 0
	s_setprio 1
	v_mfma_f32_16x16x32_f16 v[106:109], v[172:175], v[188:191], v[106:109]
	v_mfma_f32_16x16x32_f16 v[98:101], v[180:183], v[188:191], v[98:101]
	v_mfma_f32_16x16x32_f16 v[90:93], v[172:175], v[196:199], v[90:93]
	v_mfma_f32_16x16x32_f16 v[82:85], v[180:183], v[196:199], v[82:85]
	v_mfma_f32_16x16x32_f16 v[78:81], v[172:175], v[204:207], v[78:81]
	v_mfma_f32_16x16x32_f16 v[74:77], v[180:183], v[204:207], v[74:77]
	v_mfma_f32_16x16x32_f16 v[70:73], v[172:175], v[212:215], v[70:73]
	v_mfma_f32_16x16x32_f16 v[66:69], v[180:183], v[212:215], v[66:69]
	v_mfma_f32_16x16x32_f16 v[106:109], v[176:179], v[192:195], v[106:109]
	v_mfma_f32_16x16x32_f16 v[98:101], v[184:187], v[192:195], v[98:101]
	v_mfma_f32_16x16x32_f16 v[90:93], v[176:179], v[200:203], v[90:93]
	v_mfma_f32_16x16x32_f16 v[82:85], v[184:187], v[200:203], v[82:85]
	v_mfma_f32_16x16x32_f16 v[78:81], v[176:179], v[208:211], v[78:81]
	v_mfma_f32_16x16x32_f16 v[74:77], v[184:187], v[208:211], v[74:77]
	v_mfma_f32_16x16x32_f16 v[70:73], v[176:179], v[216:219], v[70:73]
	v_mfma_f32_16x16x32_f16 v[66:69], v[184:187], v[216:219], v[66:69]
	s_setprio 0
	s_barrier
; #define PG8_STAGE(bufoff, gbase, voff) do { _Pragma("unroll") for (int _i = 0; _i < 2; ++_i) \
;         __builtin_amdgcn_global_load_lds((const unsigned*)((const char*)(gbase) + (voff)[_i]), (PG8_LAS unsigned*)(lds + (bufoff) + ldsw + _i * 8192), 16, 0, 0); } while (0)
; #define PG8_LDA(dst, b, h) do { _Pragma("unroll") for (int m = 0; m < 4; ++m) _Pragma("unroll") for (int k = 0; k < 2; ++k) dst[m][k] = *(const PG8_LAS bf16x8*)(lds + PG8_SA(b, h) + aoff + m * 2048 + k * 1024); } while (0)
; #define PG8_LDB(dst, b, h) do { _Pragma("unroll") for (int n = 0; n < 2; ++n) _Pragma("unroll") for (int k = 0; k < 2; ++k) dst[n][k] = *(const PG8_LAS bf16x8*)(lds + PG8_SB(b, h) + boff + n * 2048 + k * 1024); } while (0)
; template <class Epi, class Sched, bool ALIGN_EPI = false, bool SP2 = false>
; __device__ __forceinline__ void gemm_phase(PG8_LAS unsigned char* lds, const Gemm g, const Sched& S, const Epi& E) {
;     ...
;         for (int t = 0; t < nt; t += 2) {
;             const bool last = (t == nt - 2);
;             const char* a1 = cA + (size_t)(t + 1) * kstep;
;             const char* a2 = last ? nA : cA + (size_t)(t + 2) * kstep; const char* b2 = last ? nB : cB + (size_t)(t + 2) * kstep;
;             const char* a3 = a2 + kstep; const char* b3 = b2 + kstep;
;             if (last && has_next) S.a_ready(nxt);
;             if constexpr (SP2) {
;             PG8_LDB(B0, 0, 0); PG8_LDB(B1, 0, 1); PG8_SCHED; PG8_LDA(At, 0, 0); PG8_STAGE(PG8_SA(1, 1), a1 + hstep, voffA);
;             PG8_WAIT_V(8); PG8_WAIT_L(0); PG8_BAR; PG8_MMA(0, 0, At, B0); PG8_MMA(0, 1, At, B1); PG8_BAR; PG8_SCHED;
;             PG8_LDA(At, 0, 1); PG8_STAGE(PG8_SB(0, 0), b2, voffB); PG8_STAGE(PG8_SB(0, 1), b2 + hstep, voffB); PG8_STAGE(PG8_SA(0, 0), a2, voffA);
;             PG8_WAIT_V(8); PG8_WAIT_L(0); PG8_BAR; PG8_MMA(1, 0, At, B0); PG8_MMA(1, 1, At, B1); PG8_BAR; PG8_SCHED;
;             PG8_LDB(B0, 1, 0); PG8_LDB(B1, 1, 1); PG8_SCHED; PG8_LDA(At, 1, 0); PG8_STAGE(PG8_SA(0, 1), a2 + hstep, voffA);
;             PG8_WAIT_V(8); PG8_WAIT_L(0); PG8_BAR; PG8_MMA(0, 0, At, B0); PG8_MMA(0, 1, At, B1); PG8_BAR; PG8_SCHED;
;             PG8_LDA(At, 1, 1); PG8_STAGE(PG8_SB(1, 0), b3, voffB); PG8_STAGE(PG8_SB(1, 1), b3 + hstep, voffB); PG8_STAGE(PG8_SA(1, 0), a3, voffA);
;             PG8_WAIT_V(8); PG8_WAIT_L(0); PG8_BAR; PG8_MMA(1, 0, At, B0); PG8_MMA(1, 1, At, B1); PG8_BAR; PG8_SCHED;
	s_add_i32 s30, s83, s36
	v_lshl_add_u64 v[164:165], v[164:165], 0, s[10:11]
	s_mov_b32 m0, s30
	ds_read_b128 v[188:191], v170 offset:49152
	ds_read_b128 v[192:195], v170 offset:50176
	ds_read_b128 v[196:199], v170 offset:51200
	ds_read_b128 v[200:203], v170 offset:52224
	ds_read_b128 v[204:207], v170 offset:53248
	ds_read_b128 v[208:211], v170 offset:54272
	ds_read_b128 v[212:215], v170 offset:55296
	ds_read_b128 v[216:219], v170 offset:56320
	global_load_lds_dwordx4 v[164:165], off
	s_add_i32 m0, s30, 0x2000
	s_add_u32 s28, s28, 0x40080
	v_lshl_add_u64 v[164:165], v[220:221], 0, s[10:11]
	s_addc_u32 s29, s29, 0
	s_add_i32 s30, s84, s36
	global_load_lds_dwordx4 v[164:165], off
	v_lshl_add_u64 v[164:165], s[28:29], 0, v[148:149]
	s_mov_b32 m0, s30
	s_nop 0
	global_load_lds_dwordx4 v[164:165], off
	v_lshl_add_u64 v[164:165], s[28:29], 0, v[152:153]
	s_add_i32 m0, s30, 0x2000
	s_nop 0
	global_load_lds_dwordx4 v[164:165], off
	v_lshl_add_u64 v[164:165], v[222:223], 0, s[10:11]
	s_mov_b32 m0, s49
	s_nop 0
	global_load_lds_dwordx4 v[164:165], off
	v_lshl_add_u64 v[164:165], v[224:225], 0, s[10:11]
	s_mov_b32 m0, s50
	s_nop 0
	global_load_lds_dwordx4 v[164:165], off
	s_waitcnt vmcnt(8)
	s_waitcnt lgkmcnt(0)
	s_barrier
	s_setprio 1
	s_waitcnt lgkmcnt(0)
	v_mfma_f32_16x16x32_f16 v[62:65], v[130:133], v[188:191], v[62:65]
	v_mfma_f32_16x16x32_f16 v[58:61], v[138:141], v[188:191], v[58:61]
	v_mfma_f32_16x16x32_f16 v[50:53], v[130:133], v[196:199], v[50:53]
	v_mfma_f32_16x16x32_f16 v[42:45], v[138:141], v[196:199], v[42:45]
	v_mfma_f32_16x16x32_f16 v[34:37], v[130:133], v[204:207], v[34:37]
	v_mfma_f32_16x16x32_f16 v[26:29], v[138:141], v[204:207], v[26:29]
	v_mfma_f32_16x16x32_f16 v[18:21], v[130:133], v[212:215], v[18:21]
	v_mfma_f32_16x16x32_f16 v[10:13], v[138:141], v[212:215], v[10:13]
	v_mfma_f32_16x16x32_f16 v[62:65], v[134:137], v[192:195], v[62:65]
	v_mfma_f32_16x16x32_f16 v[58:61], v[142:145], v[192:195], v[58:61]
	v_mfma_f32_16x16x32_f16 v[50:53], v[134:137], v[200:203], v[50:53]
	v_mfma_f32_16x16x32_f16 v[42:45], v[142:145], v[200:203], v[42:45]
	v_mfma_f32_16x16x32_f16 v[34:37], v[134:137], v[208:211], v[34:37]
	v_mfma_f32_16x16x32_f16 v[26:29], v[142:145], v[208:211], v[26:29]
	v_mfma_f32_16x16x32_f16 v[18:21], v[134:137], v[216:219], v[18:21]
	v_mfma_f32_16x16x32_f16 v[10:13], v[142:145], v[216:219], v[10:13]
	s_setprio 0
	s_setprio 1
	v_mfma_f32_16x16x32_f16 v[54:57], v[172:175], v[188:191], v[54:57]
	v_mfma_f32_16x16x32_f16 v[46:49], v[180:183], v[188:191], v[46:49]
	v_mfma_f32_16x16x32_f16 v[38:41], v[172:175], v[196:199], v[38:41]
	v_mfma_f32_16x16x32_f16 v[30:33], v[180:183], v[196:199], v[30:33]
	v_mfma_f32_16x16x32_f16 v[22:25], v[172:175], v[204:207], v[22:25]
	v_mfma_f32_16x16x32_f16 v[14:17], v[180:183], v[204:207], v[14:17]
	v_mfma_f32_16x16x32_f16 v[6:9], v[172:175], v[212:215], v[6:9]
	v_mfma_f32_16x16x32_f16 v[2:5], v[180:183], v[212:215], v[2:5]
	v_mfma_f32_16x16x32_f16 v[54:57], v[176:179], v[192:195], v[54:57]
	v_mfma_f32_16x16x32_f16 v[46:49], v[184:187], v[192:195], v[46:49]
	v_mfma_f32_16x16x32_f16 v[38:41], v[176:179], v[200:203], v[38:41]
	v_mfma_f32_16x16x32_f16 v[30:33], v[184:187], v[200:203], v[30:33]
	v_mfma_f32_16x16x32_f16 v[22:25], v[176:179], v[208:211], v[22:25]
	v_mfma_f32_16x16x32_f16 v[14:17], v[184:187], v[208:211], v[14:17]
	v_mfma_f32_16x16x32_f16 v[6:9], v[176:179], v[216:219], v[6:9]
	v_mfma_f32_16x16x32_f16 v[2:5], v[184:187], v[216:219], v[2:5]
	s_setprio 0
	s_add_i32 s81, s81, 2
	s_add_u32 s78, s78, 0x100
	s_addc_u32 s79, s79, 0
	s_add_u32 s26, s26, 0x100
	s_addc_u32 s27, s27, 0
	s_cmp_gt_u32 s81, 13
	s_barrier
	s_cbranch_scc0 .LBB0_442
	s_and_b64 vcc, exec, s[12:13]
	s_cbranch_vccz .LBB0_445
	s_barrier

; #define PG8_STAGE(bufoff, gbase, voff) do { _Pragma("unroll") for (int _i = 0; _i < 2; ++_i) \
;         __builtin_amdgcn_global_load_lds((const unsigned*)((const char*)(gbase) + (voff)[_i]), (PG8_LAS unsigned*)(lds + (bufoff) + ldsw + _i * 8192), 16, 0, 0); } while (0)
; #define PG8_LDA(dst, b, h) do { _Pragma("unroll") for (int m = 0; m < 4; ++m) _Pragma("unroll") for (int k = 0; k < 2; ++k) dst[m][k] = *(const PG8_LAS bf16x8*)(lds + PG8_SA(b, h) + aoff + m * 2048 + k * 1024); } while (0)
; #define PG8_LDB(dst, b, h) do { _Pragma("unroll") for (int n = 0; n < 2; ++n) _Pragma("unroll") for (int k = 0; k < 2; ++k) dst[n][k] = *(const PG8_LAS bf16x8*)(lds + PG8_SB(b, h) + boff + n * 2048 + k * 1024); } while (0)
; #define PG8_MMA(ai, bj, At, Bt) do { __builtin_amdgcn_s_setprio(1); _Pragma("unroll") for (int m = 0; m < 4; ++m) _Pragma("unroll") for (int n = 0; n < 2; ++n) _Pragma("unroll") for (int k = 0; k < 2; ++k) \
;         acc[ai][bj][m][n] = __builtin_amdgcn_mfma_f32_16x16x32_f16(H8(Bt[n][k]), H8(At[m][k]), acc[ai][bj][m][n], 0, 0, 0); __builtin_amdgcn_s_setprio(0); } while (0)
; #define PG8_WAIT_V(n) asm volatile("s_waitcnt vmcnt(" #n ")" ::: "memory")
; #define PG8_WAIT_L(n) asm volatile("s_waitcnt lgkmcnt(" #n ")" ::: "memory")
; #define PG8_BAR __builtin_amdgcn_s_barrier()
; #define PG8_SCHED __builtin_amdgcn_sched_barrier(0)
; template <class Epi, class Sched, bool ALIGN_EPI = false, bool SP2 = false>
; __device__ __forceinline__ void gemm_phase(PG8_LAS unsigned char* lds, const Gemm g, const Sched& S, const Epi& E) {
;     ...
;             const bool last = (t == nt - 2);
;             const char* a1 = cA + (size_t)(t + 1) * kstep;
;             const char* a2 = last ? nA : cA + (size_t)(t + 2) * kstep; const char* b2 = last ? nB : cB + (size_t)(t + 2) * kstep;
;             const char* a3 = a2 + kstep; const char* b3 = b2 + kstep;
;             if (last && has_next) S.a_ready(nxt);
;             if constexpr (SP2) {
;             PG8_LDB(B0, 0, 0); PG8_LDB(B1, 0, 1); PG8_SCHED; PG8_LDA(At, 0, 0); PG8_STAGE(PG8_SA(1, 1), a1 + hstep, voffA);
;             PG8_WAIT_V(8); PG8_WAIT_L(0); PG8_BAR; PG8_MMA(0, 0, At, B0); PG8_MMA(0, 1, At, B1); PG8_BAR; PG8_SCHED;
;             PG8_LDA(At, 0, 1); PG8_STAGE(PG8_SB(0, 0), b2, voffB); PG8_STAGE(PG8_SB(0, 1), b2 + hstep, voffB); PG8_STAGE(PG8_SA(0, 0), a2, voffA);
.LBB0_857:
	ds_read_b128 v[154:157], v150
	ds_read_b128 v[158:161], v150 offset:1024
	ds_read_b128 v[164:167], v150 offset:2048
	ds_read_b128 v[168:171], v150 offset:3072
	ds_read_b128 v[172:175], v151
	ds_read_b128 v[176:179], v151 offset:1024
	ds_read_b128 v[180:183], v151 offset:2048
	ds_read_b128 v[184:187], v151 offset:3072
	s_add_u32 s34, s30, 0xfffc0080
	s_addc_u32 s35, s31, -1
	s_cmp_eq_u32 s62, 12
	s_cselect_b32 s37, s23, s35
	s_cselect_b32 s36, s58, s34
	s_cselect_b32 s35, s21, s61
	s_cselect_b32 s34, s59, s60
	v_lshl_add_u64 v[146:147], s[30:31], 0, v[138:139]
	s_add_i32 m0, s29, 0xc000
	ds_read_b128 v[188:191], v152
	ds_read_b128 v[192:195], v152 offset:1024
	ds_read_b128 v[196:199], v152 offset:2048
	ds_read_b128 v[200:203], v152 offset:3072
	ds_read_b128 v[204:207], v152 offset:4096
	ds_read_b128 v[208:211], v152 offset:5120
	ds_read_b128 v[212:215], v152 offset:6144
	ds_read_b128 v[216:219], v152 offset:7168
	global_load_lds_dwordx4 v[146:147], off
	v_lshl_add_u64 v[146:147], s[30:31], 0, v[140:141]
	s_add_i32 m0, s29, 0xe000
	s_nop 0
	global_load_lds_dwordx4 v[146:147], off
	s_waitcnt vmcnt(8)
	s_waitcnt lgkmcnt(0)
	s_barrier
	s_setprio 1
	s_waitcnt lgkmcnt(0)
	v_mfma_f32_16x16x32_f16 v[126:129], v[154:157], v[188:191], v[126:129]
	v_mfma_f32_16x16x32_f16 v[122:125], v[164:167], v[188:191], v[122:125]
	v_mfma_f32_16x16x32_f16 v[118:121], v[154:157], v[196:199], v[118:121]
	v_mfma_f32_16x16x32_f16 v[110:113], v[164:167], v[196:199], v[110:113]
	v_mfma_f32_16x16x32_f16 v[102:105], v[154:157], v[204:207], v[102:105]
	v_mfma_f32_16x16x32_f16 v[94:97], v[164:167], v[204:207], v[94:97]
	v_mfma_f32_16x16x32_f16 v[86:89], v[154:157], v[212:215], v[86:89]
	v_mfma_f32_16x16x32_f16 v[78:81], v[164:167], v[212:215], v[78:81]
	v_mfma_f32_16x16x32_f16 v[126:129], v[158:161], v[192:195], v[126:129]
	v_mfma_f32_16x16x32_f16 v[122:125], v[168:171], v[192:195], v[122:125]
	v_mfma_f32_16x16x32_f16 v[118:121], v[158:161], v[200:203], v[118:121]
	v_mfma_f32_16x16x32_f16 v[110:113], v[168:171], v[200:203], v[110:113]
	v_mfma_f32_16x16x32_f16 v[102:105], v[158:161], v[208:211], v[102:105]
	v_mfma_f32_16x16x32_f16 v[94:97], v[168:171], v[208:211], v[94:97]
	v_mfma_f32_16x16x32_f16 v[86:89], v[158:161], v[216:219], v[86:89]
	v_mfma_f32_16x16x32_f16 v[78:81], v[168:171], v[216:219], v[78:81]
	s_setprio 0
	s_setprio 1
	v_mfma_f32_16x16x32_f16 v[114:117], v[172:175], v[188:191], v[114:117]
	v_mfma_f32_16x16x32_f16 v[106:109], v[180:183], v[188:191], v[106:109]
	v_mfma_f32_16x16x32_f16 v[98:101], v[172:175], v[196:199], v[98:101]
	v_mfma_f32_16x16x32_f16 v[90:93], v[180:183], v[196:199], v[90:93]
	v_mfma_f32_16x16x32_f16 v[82:85], v[172:175], v[204:207], v[82:85]
	v_mfma_f32_16x16x32_f16 v[74:77], v[180:183], v[204:207], v[74:77]
	v_mfma_f32_16x16x32_f16 v[70:73], v[172:175], v[212:215], v[70:73]
	v_mfma_f32_16x16x32_f16 v[66:69], v[180:183], v[212:215], v[66:69]
	v_mfma_f32_16x16x32_f16 v[114:117], v[176:179], v[192:195], v[114:117]
	v_mfma_f32_16x16x32_f16 v[106:109], v[184:187], v[192:195], v[106:109]
	v_mfma_f32_16x16x32_f16 v[98:101], v[176:179], v[200:203], v[98:101]
	v_mfma_f32_16x16x32_f16 v[90:93], v[184:187], v[200:203], v[90:93]
	v_mfma_f32_16x16x32_f16 v[82:85], v[176:179], v[208:211], v[82:85]
	v_mfma_f32_16x16x32_f16 v[74:77], v[184:187], v[208:211], v[74:77]
	v_mfma_f32_16x16x32_f16 v[70:73], v[176:179], v[216:219], v[70:73]
	v_mfma_f32_16x16x32_f16 v[66:69], v[184:187], v[216:219], v[66:69]
	s_setprio 0
	s_barrier
	s_add_i32 s63, s51, s42
	v_lshl_add_u64 v[146:147], s[34:35], 0, v[132:133]
	s_mov_b32 m0, s63
	ds_read_b128 v[188:191], v152 offset:16384
	ds_read_b128 v[192:195], v152 offset:17408
	ds_read_b128 v[196:199], v152 offset:18432
	ds_read_b128 v[200:203], v152 offset:19456
	ds_read_b128 v[204:207], v152 offset:20480
	ds_read_b128 v[208:211], v152 offset:21504
	ds_read_b128 v[212:215], v152 offset:22528
	ds_read_b128 v[216:219], v152 offset:23552
	global_load_lds_dwordx4 v[146:147], off
	s_add_i32 m0, s63, 0x2000
	s_add_u32 s64, s34, 0x40000
	v_lshl_add_u64 v[220:221], s[34:35], 0, v[136:137]
	s_addc_u32 s65, s35, 0
	s_add_i32 s63, s52, s42
	global_load_lds_dwordx4 v[220:221], off
	v_lshl_add_u64 v[222:223], s[64:65], 0, v[132:133]
	s_mov_b32 m0, s63
	v_lshl_add_u64 v[224:225], s[36:37], 0, v[134:135]
	global_load_lds_dwordx4 v[222:223], off
	v_lshl_add_u64 v[222:223], s[64:65], 0, v[136:137]
	s_add_i32 m0, s63, 0x2000
	s_nop 0
	global_load_lds_dwordx4 v[222:223], off
	v_lshl_add_u64 v[222:223], s[36:37], 0, v[130:131]
	s_mov_b32 m0, s29
	s_nop 0
	global_load_lds_dwordx4 v[222:223], off
	s_mov_b32 m0, s43
	s_nop 0
	global_load_lds_dwordx4 v[224:225], off
	s_waitcnt vmcnt(8)
	s_waitcnt lgkmcnt(0)
	s_barrier
; #define PG8_STAGE(bufoff, gbase, voff) do { _Pragma("unroll") for (int _i = 0; _i < 2; ++_i) \
;         __builtin_amdgcn_global_load_lds((const unsigned*)((const char*)(gbase) + (voff)[_i]), (PG8_LAS unsigned*)(lds + (bufoff) + ldsw + _i * 8192), 16, 0, 0); } while (0)
; #define PG8_LDA(dst, b, h) do { _Pragma("unroll") for (int m = 0; m < 4; ++m) _Pragma("unroll") for (int k = 0; k < 2; ++k) dst[m][k] = *(const PG8_LAS bf16x8*)(lds + PG8_SA(b, h) + aoff + m * 2048 + k * 1024); } while (0)
; #define PG8_LDB(dst, b, h) do { _Pragma("unroll") for (int n = 0; n < 2; ++n) _Pragma("unroll") for (int k = 0; k < 2; ++k) dst[n][k] = *(const PG8_LAS bf16x8*)(lds + PG8_SB(b, h) + boff + n * 2048 + k * 1024); } while (0)
; #define PG8_MMA(ai, bj, At, Bt) do { __builtin_amdgcn_s_setprio(1); _Pragma("unroll") for (int m = 0; m < 4; ++m) _Pragma("unroll") for (int n = 0; n < 2; ++n) _Pragma("unroll") for (int k = 0; k < 2; ++k) \
;         acc[ai][bj][m][n] = __builtin_amdgcn_mfma_f32_16x16x32_f16(H8(Bt[n][k]), H8(At[m][k]), acc[ai][bj][m][n], 0, 0, 0); __builtin_amdgcn_s_setprio(0); } while (0)
; #define PG8_WAIT_V(n) asm volatile("s_waitcnt vmcnt(" #n ")" ::: "memory")
; #define PG8_WAIT_L(n) asm volatile("s_waitcnt lgkmcnt(" #n ")" ::: "memory")
; #define PG8_BAR __builtin_amdgcn_s_barrier()
; #define PG8_SCHED __builtin_amdgcn_sched_barrier(0)
; template <class Epi, class Sched, bool ALIGN_EPI = false, bool SP2 = false>
; __device__ __forceinline__ void gemm_phase(PG8_LAS unsigned char* lds, const Gemm g, const Sched& S, const Epi& E) {
;     ...
;             PG8_LDA(At, 0, 1); PG8_STAGE(PG8_SB(0, 0), b2, voffB); PG8_STAGE(PG8_SB(0, 1), b2 + hstep, voffB); PG8_STAGE(PG8_SA(0, 0), a2, voffA);
;             PG8_WAIT_V(8); PG8_WAIT_L(0); PG8_BAR; PG8_MMA(1, 0, At, B0); PG8_MMA(1, 1, At, B1); PG8_BAR; PG8_SCHED;
;             PG8_LDB(B0, 1, 0); PG8_LDB(B1, 1, 1); PG8_SCHED; PG8_LDA(At, 1, 0); PG8_STAGE(PG8_SA(0, 1), a2 + hstep, voffA);
;             PG8_WAIT_V(8); PG8_WAIT_L(0); PG8_BAR; PG8_MMA(0, 0, At, B0); PG8_MMA(0, 1, At, B1); PG8_BAR; PG8_SCHED;
	s_setprio 1
	s_waitcnt lgkmcnt(0)
	v_mfma_f32_16x16x32_f16 v[62:65], v[154:157], v[188:191], v[62:65]
	v_mfma_f32_16x16x32_f16 v[58:61], v[164:167], v[188:191], v[58:61]
	v_mfma_f32_16x16x32_f16 v[54:57], v[154:157], v[196:199], v[54:57]
	v_mfma_f32_16x16x32_f16 v[46:49], v[164:167], v[196:199], v[46:49]
	v_mfma_f32_16x16x32_f16 v[38:41], v[154:157], v[204:207], v[38:41]
	v_mfma_f32_16x16x32_f16 v[30:33], v[164:167], v[204:207], v[30:33]
	v_mfma_f32_16x16x32_f16 v[22:25], v[154:157], v[212:215], v[22:25]
	v_mfma_f32_16x16x32_f16 v[14:17], v[164:167], v[212:215], v[14:17]
	v_mfma_f32_16x16x32_f16 v[62:65], v[158:161], v[192:195], v[62:65]
	v_mfma_f32_16x16x32_f16 v[58:61], v[168:171], v[192:195], v[58:61]
	v_mfma_f32_16x16x32_f16 v[54:57], v[158:161], v[200:203], v[54:57]
	v_mfma_f32_16x16x32_f16 v[46:49], v[168:171], v[200:203], v[46:49]
	v_mfma_f32_16x16x32_f16 v[38:41], v[158:161], v[208:211], v[38:41]
	v_mfma_f32_16x16x32_f16 v[30:33], v[168:171], v[208:211], v[30:33]
	v_mfma_f32_16x16x32_f16 v[22:25], v[158:161], v[216:219], v[22:25]
	v_mfma_f32_16x16x32_f16 v[14:17], v[168:171], v[216:219], v[14:17]
	s_setprio 0
	s_setprio 1
	v_mfma_f32_16x16x32_f16 v[50:53], v[172:175], v[188:191], v[50:53]
	v_mfma_f32_16x16x32_f16 v[42:45], v[180:183], v[188:191], v[42:45]
	v_mfma_f32_16x16x32_f16 v[34:37], v[172:175], v[196:199], v[34:37]
	v_mfma_f32_16x16x32_f16 v[26:29], v[180:183], v[196:199], v[26:29]
	v_mfma_f32_16x16x32_f16 v[18:21], v[172:175], v[204:207], v[18:21]
	v_mfma_f32_16x16x32_f16 v[10:13], v[180:183], v[204:207], v[10:13]
	v_mfma_f32_16x16x32_f16 v[6:9], v[172:175], v[212:215], v[6:9]
	v_mfma_f32_16x16x32_f16 v[2:5], v[180:183], v[212:215], v[2:5]
	v_mfma_f32_16x16x32_f16 v[50:53], v[176:179], v[192:195], v[50:53]
	v_mfma_f32_16x16x32_f16 v[42:45], v[184:187], v[192:195], v[42:45]
	v_mfma_f32_16x16x32_f16 v[34:37], v[176:179], v[200:203], v[34:37]
	v_mfma_f32_16x16x32_f16 v[26:29], v[184:187], v[200:203], v[26:29]
	v_mfma_f32_16x16x32_f16 v[18:21], v[176:179], v[208:211], v[18:21]
	v_mfma_f32_16x16x32_f16 v[10:13], v[184:187], v[208:211], v[10:13]
	v_mfma_f32_16x16x32_f16 v[6:9], v[176:179], v[216:219], v[6:9]
	v_mfma_f32_16x16x32_f16 v[2:5], v[184:187], v[216:219], v[2:5]
	s_setprio 0
	s_barrier
	s_add_i32 s63, 0, 0x18000
	v_add_u32_e32 v153, s63, v148
	s_add_i32 s64, 0, 0x1c000
	ds_read_b128 v[154:157], v153
	ds_read_b128 v[158:161], v153 offset:1024
	ds_read_b128 v[164:167], v153 offset:2048
	ds_read_b128 v[168:171], v153 offset:3072
	v_add_u32_e32 v153, s64, v148
	ds_read_b128 v[172:175], v153
	ds_read_b128 v[176:179], v153 offset:1024
	ds_read_b128 v[180:183], v153 offset:2048
	ds_read_b128 v[184:187], v153 offset:3072
	s_add_u32 s36, s36, 0x40000
	s_addc_u32 s37, s37, 0
	s_mov_b32 m0, s44
	v_lshl_add_u64 v[226:227], s[36:37], 0, v[130:131]
	ds_read_b128 v[188:191], v152 offset:32768
	ds_read_b128 v[192:195], v152 offset:33792
	ds_read_b128 v[196:199], v152 offset:34816
	ds_read_b128 v[200:203], v152 offset:35840
	ds_read_b128 v[204:207], v152 offset:36864
	ds_read_b128 v[208:211], v152 offset:37888
	ds_read_b128 v[212:215], v152 offset:38912
	ds_read_b128 v[216:219], v152 offset:39936
	global_load_lds_dwordx4 v[226:227], off
	v_lshl_add_u64 v[226:227], s[36:37], 0, v[134:135]
	s_mov_b32 m0, s45
	s_nop 0
	global_load_lds_dwordx4 v[226:227], off
	s_waitcnt vmcnt(8)
	s_waitcnt lgkmcnt(0)
	s_barrier
	s_setprio 1
	s_waitcnt lgkmcnt(0)
	v_mfma_f32_16x16x32_f16 v[126:129], v[154:157], v[188:191], v[126:129]
	v_mfma_f32_16x16x32_f16 v[122:125], v[164:167], v[188:191], v[122:125]
	v_mfma_f32_16x16x32_f16 v[118:121], v[154:157], v[196:199], v[118:121]
	v_mfma_f32_16x16x32_f16 v[110:113], v[164:167], v[196:199], v[110:113]
	v_mfma_f32_16x16x32_f16 v[102:105], v[154:157], v[204:207], v[102:105]
	v_mfma_f32_16x16x32_f16 v[94:97], v[164:167], v[204:207], v[94:97]
	v_mfma_f32_16x16x32_f16 v[86:89], v[154:157], v[212:215], v[86:89]
	v_mfma_f32_16x16x32_f16 v[78:81], v[164:167], v[212:215], v[78:81]
	v_mfma_f32_16x16x32_f16 v[126:129], v[158:161], v[192:195], v[126:129]
	v_mfma_f32_16x16x32_f16 v[122:125], v[168:171], v[192:195], v[122:125]
	v_mfma_f32_16x16x32_f16 v[118:121], v[158:161], v[200:203], v[118:121]
	v_mfma_f32_16x16x32_f16 v[110:113], v[168:171], v[200:203], v[110:113]
	v_mfma_f32_16x16x32_f16 v[102:105], v[158:161], v[208:211], v[102:105]
	v_mfma_f32_16x16x32_f16 v[94:97], v[168:171], v[208:211], v[94:97]
	v_mfma_f32_16x16x32_f16 v[86:89], v[158:161], v[216:219], v[86:89]
	v_mfma_f32_16x16x32_f16 v[78:81], v[168:171], v[216:219], v[78:81]
	s_setprio 0
	s_setprio 1
	v_mfma_f32_16x16x32_f16 v[114:117], v[172:175], v[188:191], v[114:117]
	v_mfma_f32_16x16x32_f16 v[106:109], v[180:183], v[188:191], v[106:109]
	v_mfma_f32_16x16x32_f16 v[98:101], v[172:175], v[196:199], v[98:101]
	v_mfma_f32_16x16x32_f16 v[90:93], v[180:183], v[196:199], v[90:93]
	v_mfma_f32_16x16x32_f16 v[82:85], v[172:175], v[204:207], v[82:85]
	v_mfma_f32_16x16x32_f16 v[74:77], v[180:183], v[204:207], v[74:77]
	v_mfma_f32_16x16x32_f16 v[70:73], v[172:175], v[212:215], v[70:73]
	v_mfma_f32_16x16x32_f16 v[66:69], v[180:183], v[212:215], v[66:69]
	v_mfma_f32_16x16x32_f16 v[114:117], v[176:179], v[192:195], v[114:117]
	v_mfma_f32_16x16x32_f16 v[106:109], v[184:187], v[192:195], v[106:109]
	v_mfma_f32_16x16x32_f16 v[98:101], v[176:179], v[200:203], v[98:101]
	v_mfma_f32_16x16x32_f16 v[90:93], v[184:187], v[200:203], v[90:93]
	v_mfma_f32_16x16x32_f16 v[82:85], v[176:179], v[208:211], v[82:85]
	v_mfma_f32_16x16x32_f16 v[74:77], v[184:187], v[208:211], v[74:77]
	v_mfma_f32_16x16x32_f16 v[70:73], v[176:179], v[216:219], v[70:73]
	v_mfma_f32_16x16x32_f16 v[66:69], v[184:187], v[216:219], v[66:69]
	s_setprio 0
	s_barrier
; #define PG8_STAGE(bufoff, gbase, voff) do { _Pragma("unroll") for (int _i = 0; _i < 2; ++_i) \
;         __builtin_amdgcn_global_load_lds((const unsigned*)((const char*)(gbase) + (voff)[_i]), (PG8_LAS unsigned*)(lds + (bufoff) + ldsw + _i * 8192), 16, 0, 0); } while (0)
; #define PG8_LDA(dst, b, h) do { _Pragma("unroll") for (int m = 0; m < 4; ++m) _Pragma("unroll") for (int k = 0; k < 2; ++k) dst[m][k] = *(const PG8_LAS bf16x8*)(lds + PG8_SA(b, h) + aoff + m * 2048 + k * 1024); } while (0)
; #define PG8_LDB(dst, b, h) do { _Pragma("unroll") for (int n = 0; n < 2; ++n) _Pragma("unroll") for (int k = 0; k < 2; ++k) dst[n][k] = *(const PG8_LAS bf16x8*)(lds + PG8_SB(b, h) + boff + n * 2048 + k * 1024); } while (0)
; template <class Epi, class Sched, bool ALIGN_EPI = false, bool SP2 = false>
; __device__ __forceinline__ void gemm_phase(PG8_LAS unsigned char* lds, const Gemm g, const Sched& S, const Epi& E) {
;     ...
;         for (int t = 0; t < nt; t += 2) {
;             const bool last = (t == nt - 2);
;             const char* a1 = cA + (size_t)(t + 1) * kstep;
;             const char* a2 = last ? nA : cA + (size_t)(t + 2) * kstep; const char* b2 = last ? nB : cB + (size_t)(t + 2) * kstep;
;             const char* a3 = a2 + kstep; const char* b3 = b2 + kstep;
;             if (last && has_next) S.a_ready(nxt);
;             if constexpr (SP2) {
;             PG8_LDB(B0, 0, 0); PG8_LDB(B1, 0, 1); PG8_SCHED; PG8_LDA(At, 0, 0); PG8_STAGE(PG8_SA(1, 1), a1 + hstep, voffA);
;             PG8_WAIT_V(8); PG8_WAIT_L(0); PG8_BAR; PG8_MMA(0, 0, At, B0); PG8_MMA(0, 1, At, B1); PG8_BAR; PG8_SCHED;
;             PG8_LDA(At, 0, 1); PG8_STAGE(PG8_SB(0, 0), b2, voffB); PG8_STAGE(PG8_SB(0, 1), b2 + hstep, voffB); PG8_STAGE(PG8_SA(0, 0), a2, voffA);
;             PG8_WAIT_V(8); PG8_WAIT_L(0); PG8_BAR; PG8_MMA(1, 0, At, B0); PG8_MMA(1, 1, At, B1); PG8_BAR; PG8_SCHED;
;             PG8_LDB(B0, 1, 0); PG8_LDB(B1, 1, 1); PG8_SCHED; PG8_LDA(At, 1, 0); PG8_STAGE(PG8_SA(0, 1), a2 + hstep, voffA);
;             PG8_WAIT_V(8); PG8_WAIT_L(0); PG8_BAR; PG8_MMA(0, 0, At, B0); PG8_MMA(0, 1, At, B1); PG8_BAR; PG8_SCHED;
;             PG8_LDA(At, 1, 1); PG8_STAGE(PG8_SB(1, 0), b3, voffB); PG8_STAGE(PG8_SB(1, 1), b3 + hstep, voffB); PG8_STAGE(PG8_SA(1, 0), a3, voffA);
;             PG8_WAIT_V(8); PG8_WAIT_L(0); PG8_BAR; PG8_MMA(1, 0, At, B0); PG8_MMA(1, 1, At, B1); PG8_BAR; PG8_SCHED;
	s_add_i32 s36, s63, s42
	v_lshl_add_u64 v[146:147], v[146:147], 0, s[10:11]
	s_mov_b32 m0, s36
	ds_read_b128 v[188:191], v152 offset:49152
	ds_read_b128 v[192:195], v152 offset:50176
	ds_read_b128 v[196:199], v152 offset:51200
	ds_read_b128 v[200:203], v152 offset:52224
	ds_read_b128 v[204:207], v152 offset:53248
	ds_read_b128 v[208:211], v152 offset:54272
	ds_read_b128 v[212:215], v152 offset:55296
	ds_read_b128 v[216:219], v152 offset:56320
	global_load_lds_dwordx4 v[146:147], off
	s_add_i32 m0, s36, 0x2000
	s_add_u32 s34, s34, 0x40080
	v_lshl_add_u64 v[146:147], v[220:221], 0, s[10:11]
	s_addc_u32 s35, s35, 0
	s_add_i32 s36, s64, s42
	global_load_lds_dwordx4 v[146:147], off
	v_lshl_add_u64 v[146:147], s[34:35], 0, v[132:133]
	s_mov_b32 m0, s36
	s_nop 0
	global_load_lds_dwordx4 v[146:147], off
	v_lshl_add_u64 v[146:147], s[34:35], 0, v[136:137]
	s_add_i32 m0, s36, 0x2000
	s_nop 0
	global_load_lds_dwordx4 v[146:147], off
	v_lshl_add_u64 v[146:147], v[222:223], 0, s[10:11]
	s_mov_b32 m0, s47
	s_nop 0
	global_load_lds_dwordx4 v[146:147], off
	v_lshl_add_u64 v[146:147], v[224:225], 0, s[10:11]
	s_mov_b32 m0, s48
	s_nop 0
	global_load_lds_dwordx4 v[146:147], off
	s_waitcnt vmcnt(8)
	s_waitcnt lgkmcnt(0)
	s_barrier
	s_setprio 1
	s_waitcnt lgkmcnt(0)
	v_mfma_f32_16x16x32_f16 v[62:65], v[154:157], v[188:191], v[62:65]
	v_mfma_f32_16x16x32_f16 v[58:61], v[164:167], v[188:191], v[58:61]
	v_mfma_f32_16x16x32_f16 v[54:57], v[154:157], v[196:199], v[54:57]
	v_mfma_f32_16x16x32_f16 v[46:49], v[164:167], v[196:199], v[46:49]
	v_mfma_f32_16x16x32_f16 v[38:41], v[154:157], v[204:207], v[38:41]
	v_mfma_f32_16x16x32_f16 v[30:33], v[164:167], v[204:207], v[30:33]
	v_mfma_f32_16x16x32_f16 v[22:25], v[154:157], v[212:215], v[22:25]
	v_mfma_f32_16x16x32_f16 v[14:17], v[164:167], v[212:215], v[14:17]
	v_mfma_f32_16x16x32_f16 v[62:65], v[158:161], v[192:195], v[62:65]
	v_mfma_f32_16x16x32_f16 v[58:61], v[168:171], v[192:195], v[58:61]
	v_mfma_f32_16x16x32_f16 v[54:57], v[158:161], v[200:203], v[54:57]
	v_mfma_f32_16x16x32_f16 v[46:49], v[168:171], v[200:203], v[46:49]
	v_mfma_f32_16x16x32_f16 v[38:41], v[158:161], v[208:211], v[38:41]
	v_mfma_f32_16x16x32_f16 v[30:33], v[168:171], v[208:211], v[30:33]
	v_mfma_f32_16x16x32_f16 v[22:25], v[158:161], v[216:219], v[22:25]
	v_mfma_f32_16x16x32_f16 v[14:17], v[168:171], v[216:219], v[14:17]
	s_setprio 0
	s_setprio 1
	v_mfma_f32_16x16x32_f16 v[50:53], v[172:175], v[188:191], v[50:53]
	v_mfma_f32_16x16x32_f16 v[42:45], v[180:183], v[188:191], v[42:45]
	v_mfma_f32_16x16x32_f16 v[34:37], v[172:175], v[196:199], v[34:37]
	v_mfma_f32_16x16x32_f16 v[26:29], v[180:183], v[196:199], v[26:29]
	v_mfma_f32_16x16x32_f16 v[18:21], v[172:175], v[204:207], v[18:21]
	v_mfma_f32_16x16x32_f16 v[10:13], v[180:183], v[204:207], v[10:13]
	v_mfma_f32_16x16x32_f16 v[6:9], v[172:175], v[212:215], v[6:9]
	v_mfma_f32_16x16x32_f16 v[2:5], v[180:183], v[212:215], v[2:5]
	v_mfma_f32_16x16x32_f16 v[50:53], v[176:179], v[192:195], v[50:53]
	v_mfma_f32_16x16x32_f16 v[42:45], v[184:187], v[192:195], v[42:45]
	v_mfma_f32_16x16x32_f16 v[34:37], v[176:179], v[200:203], v[34:37]
	v_mfma_f32_16x16x32_f16 v[26:29], v[184:187], v[200:203], v[26:29]
	v_mfma_f32_16x16x32_f16 v[18:21], v[176:179], v[208:211], v[18:21]
	v_mfma_f32_16x16x32_f16 v[10:13], v[184:187], v[208:211], v[10:13]
	v_mfma_f32_16x16x32_f16 v[6:9], v[176:179], v[216:219], v[6:9]
	v_mfma_f32_16x16x32_f16 v[2:5], v[184:187], v[216:219], v[2:5]
	s_setprio 0
	s_add_i32 s62, s62, 2
	s_add_u32 s30, s30, 0x100
	s_addc_u32 s31, s31, 0
	s_add_u32 s60, s60, 0x100
	s_addc_u32 s61, s61, 0
	s_cmp_gt_u32 s62, 13
	s_barrier
	s_cbranch_scc0 .LBB0_857
	s_and_b64 vcc, exec, s[12:13]
	s_cbranch_vccz .LBB0_860
	s_barrier

; #define PG8_STAGE(bufoff, gbase, voff) do { _Pragma("unroll") for (int _i = 0; _i < 2; ++_i) \
;         __builtin_amdgcn_global_load_lds((const unsigned*)((const char*)(gbase) + (voff)[_i]), (PG8_LAS unsigned*)(lds + (bufoff) + ldsw + _i * 8192), 16, 0, 0); } while (0)
; #define PG8_LDA(dst, b, h) do { _Pragma("unroll") for (int m = 0; m < 4; ++m) _Pragma("unroll") for (int k = 0; k < 2; ++k) dst[m][k] = *(const PG8_LAS bf16x8*)(lds + PG8_SA(b, h) + aoff + m * 2048 + k * 1024); } while (0)
; #define PG8_LDB(dst, b, h) do { _Pragma("unroll") for (int n = 0; n < 2; ++n) _Pragma("unroll") for (int k = 0; k < 2; ++k) dst[n][k] = *(const PG8_LAS bf16x8*)(lds + PG8_SB(b, h) + boff + n * 2048 + k * 1024); } while (0)
; #define PG8_MMA(ai, bj, At, Bt) do { __builtin_amdgcn_s_setprio(1); _Pragma("unroll") for (int m = 0; m < 4; ++m) _Pragma("unroll") for (int n = 0; n < 2; ++n) _Pragma("unroll") for (int k = 0; k < 2; ++k) \
;         acc[ai][bj][m][n] = __builtin_amdgcn_mfma_f32_16x16x32_f16(H8(Bt[n][k]), H8(At[m][k]), acc[ai][bj][m][n], 0, 0, 0); __builtin_amdgcn_s_setprio(0); } while (0)
; #define PG8_WAIT_V(n) asm volatile("s_waitcnt vmcnt(" #n ")" ::: "memory")
; #define PG8_WAIT_L(n) asm volatile("s_waitcnt lgkmcnt(" #n ")" ::: "memory")
; #define PG8_BAR __builtin_amdgcn_s_barrier()
; #define PG8_SCHED __builtin_amdgcn_sched_barrier(0)
; template <class Epi, class Sched, bool ALIGN_EPI = false, bool SP2 = false>
; __device__ __forceinline__ void gemm_phase(PG8_LAS unsigned char* lds, const Gemm g, const Sched& S, const Epi& E) {
;     ...
;             const bool last = (t == nt - 2);
;             const char* a1 = cA + (size_t)(t + 1) * kstep;
;             const char* a2 = last ? nA : cA + (size_t)(t + 2) * kstep; const char* b2 = last ? nB : cB + (size_t)(t + 2) * kstep;
;             const char* a3 = a2 + kstep; const char* b3 = b2 + kstep;
;             if (last && has_next) S.a_ready(nxt);
;             if constexpr (SP2) {
;             PG8_LDB(B0, 0, 0); PG8_LDB(B1, 0, 1); PG8_SCHED; PG8_LDA(At, 0, 0); PG8_STAGE(PG8_SA(1, 1), a1 + hstep, voffA);
;             PG8_WAIT_V(8); PG8_WAIT_L(0); PG8_BAR; PG8_MMA(0, 0, At, B0); PG8_MMA(0, 1, At, B1); PG8_BAR; PG8_SCHED;
;             PG8_LDA(At, 0, 1); PG8_STAGE(PG8_SB(0, 0), b2, voffB); PG8_STAGE(PG8_SB(0, 1), b2 + hstep, voffB); PG8_STAGE(PG8_SA(0, 0), a2, voffA);
.LBB0_1014:
	ds_read_b128 v[146:149], v154
	ds_read_b128 v[158:161], v154 offset:1024
	ds_read_b128 v[164:167], v154 offset:2048
	ds_read_b128 v[168:171], v154 offset:3072
	ds_read_b128 v[172:175], v155
	ds_read_b128 v[176:179], v155 offset:1024
	ds_read_b128 v[180:183], v155 offset:2048
	ds_read_b128 v[184:187], v155 offset:3072
	s_add_u32 s26, s24, 0xfffc0080
	s_addc_u32 s27, s25, -1
	s_cmp_eq_u32 s52, 12
	s_cselect_b32 s29, s17, s27
	s_cselect_b32 s28, s48, s26
	s_cselect_b32 s27, s15, s51
	s_cselect_b32 s26, s49, s50
	v_lshl_add_u64 v[150:151], s[24:25], 0, v[138:139]
	s_add_i32 m0, s23, 0xc000
	ds_read_b128 v[188:191], v156
	ds_read_b128 v[192:195], v156 offset:1024
	ds_read_b128 v[196:199], v156 offset:2048
	ds_read_b128 v[200:203], v156 offset:3072
	ds_read_b128 v[204:207], v156 offset:4096
	ds_read_b128 v[208:211], v156 offset:5120
	ds_read_b128 v[212:215], v156 offset:6144
	ds_read_b128 v[216:219], v156 offset:7168
	global_load_lds_dwordx4 v[150:151], off
	v_lshl_add_u64 v[150:151], s[24:25], 0, v[140:141]
	s_add_i32 m0, s23, 0xe000
	s_nop 0
	global_load_lds_dwordx4 v[150:151], off
	s_waitcnt vmcnt(8)
	s_waitcnt lgkmcnt(0)
	s_barrier
	s_setprio 1
	s_waitcnt lgkmcnt(0)
	v_mfma_f32_16x16x32_f16 v[118:121], v[146:149], v[188:191], v[118:121]
	v_mfma_f32_16x16x32_f16 v[114:117], v[164:167], v[188:191], v[114:117]
	v_mfma_f32_16x16x32_f16 v[102:105], v[146:149], v[196:199], v[102:105]
	v_mfma_f32_16x16x32_f16 v[98:101], v[164:167], v[196:199], v[98:101]
	v_mfma_f32_16x16x32_f16 v[86:89], v[146:149], v[204:207], v[86:89]
	v_mfma_f32_16x16x32_f16 v[82:85], v[164:167], v[204:207], v[82:85]
	v_mfma_f32_16x16x32_f16 v[70:73], v[146:149], v[212:215], v[70:73]
	v_mfma_f32_16x16x32_f16 v[66:69], v[164:167], v[212:215], v[66:69]
	v_mfma_f32_16x16x32_f16 v[118:121], v[158:161], v[192:195], v[118:121]
	v_mfma_f32_16x16x32_f16 v[114:117], v[168:171], v[192:195], v[114:117]
	v_mfma_f32_16x16x32_f16 v[102:105], v[158:161], v[200:203], v[102:105]
	v_mfma_f32_16x16x32_f16 v[98:101], v[168:171], v[200:203], v[98:101]
	v_mfma_f32_16x16x32_f16 v[86:89], v[158:161], v[208:211], v[86:89]
	v_mfma_f32_16x16x32_f16 v[82:85], v[168:171], v[208:211], v[82:85]
	v_mfma_f32_16x16x32_f16 v[70:73], v[158:161], v[216:219], v[70:73]
	v_mfma_f32_16x16x32_f16 v[66:69], v[168:171], v[216:219], v[66:69]
	s_setprio 0
	s_setprio 1
	v_mfma_f32_16x16x32_f16 v[126:129], v[172:175], v[188:191], v[126:129]
	v_mfma_f32_16x16x32_f16 v[122:125], v[180:183], v[188:191], v[122:125]
	v_mfma_f32_16x16x32_f16 v[110:113], v[172:175], v[196:199], v[110:113]
	v_mfma_f32_16x16x32_f16 v[106:109], v[180:183], v[196:199], v[106:109]
	v_mfma_f32_16x16x32_f16 v[94:97], v[172:175], v[204:207], v[94:97]
	v_mfma_f32_16x16x32_f16 v[90:93], v[180:183], v[204:207], v[90:93]
	v_mfma_f32_16x16x32_f16 v[78:81], v[172:175], v[212:215], v[78:81]
	v_mfma_f32_16x16x32_f16 v[74:77], v[180:183], v[212:215], v[74:77]
	v_mfma_f32_16x16x32_f16 v[126:129], v[176:179], v[192:195], v[126:129]
	v_mfma_f32_16x16x32_f16 v[122:125], v[184:187], v[192:195], v[122:125]
	v_mfma_f32_16x16x32_f16 v[110:113], v[176:179], v[200:203], v[110:113]
	v_mfma_f32_16x16x32_f16 v[106:109], v[184:187], v[200:203], v[106:109]
	v_mfma_f32_16x16x32_f16 v[94:97], v[176:179], v[208:211], v[94:97]
	v_mfma_f32_16x16x32_f16 v[90:93], v[184:187], v[208:211], v[90:93]
	v_mfma_f32_16x16x32_f16 v[78:81], v[176:179], v[216:219], v[78:81]
	v_mfma_f32_16x16x32_f16 v[74:77], v[184:187], v[216:219], v[74:77]
	s_setprio 0
	s_barrier
	s_add_i32 s53, s44, s33
	v_lshl_add_u64 v[150:151], s[26:27], 0, v[134:135]
	s_mov_b32 m0, s53
	ds_read_b128 v[188:191], v156 offset:16384
	ds_read_b128 v[192:195], v156 offset:17408
	ds_read_b128 v[196:199], v156 offset:18432
	ds_read_b128 v[200:203], v156 offset:19456
	ds_read_b128 v[204:207], v156 offset:20480
	ds_read_b128 v[208:211], v156 offset:21504
	ds_read_b128 v[212:215], v156 offset:22528
	ds_read_b128 v[216:219], v156 offset:23552
	global_load_lds_dwordx4 v[150:151], off
	s_add_i32 m0, s53, 0x2000
	s_add_u32 s54, s26, 0x40000
	v_lshl_add_u64 v[220:221], s[26:27], 0, v[130:131]
	s_addc_u32 s55, s27, 0
	s_add_i32 s53, s45, s33
	global_load_lds_dwordx4 v[220:221], off
	v_lshl_add_u64 v[222:223], s[54:55], 0, v[134:135]
	s_mov_b32 m0, s53
	v_lshl_add_u64 v[224:225], s[28:29], 0, v[132:133]
	global_load_lds_dwordx4 v[222:223], off
	v_lshl_add_u64 v[222:223], s[54:55], 0, v[130:131]
	s_add_i32 m0, s53, 0x2000
	s_nop 0
	global_load_lds_dwordx4 v[222:223], off
	v_lshl_add_u64 v[222:223], s[28:29], 0, v[136:137]
	s_mov_b32 m0, s23
	s_nop 0
	global_load_lds_dwordx4 v[222:223], off
	s_mov_b32 m0, s36
	s_nop 0
	global_load_lds_dwordx4 v[224:225], off
	s_waitcnt vmcnt(8)
	s_waitcnt lgkmcnt(0)
	s_barrier
; #define PG8_STAGE(bufoff, gbase, voff) do { _Pragma("unroll") for (int _i = 0; _i < 2; ++_i) \
;         __builtin_amdgcn_global_load_lds((const unsigned*)((const char*)(gbase) + (voff)[_i]), (PG8_LAS unsigned*)(lds + (bufoff) + ldsw + _i * 8192), 16, 0, 0); } while (0)
; #define PG8_LDA(dst, b, h) do { _Pragma("unroll") for (int m = 0; m < 4; ++m) _Pragma("unroll") for (int k = 0; k < 2; ++k) dst[m][k] = *(const PG8_LAS bf16x8*)(lds + PG8_SA(b, h) + aoff + m * 2048 + k * 1024); } while (0)
; #define PG8_LDB(dst, b, h) do { _Pragma("unroll") for (int n = 0; n < 2; ++n) _Pragma("unroll") for (int k = 0; k < 2; ++k) dst[n][k] = *(const PG8_LAS bf16x8*)(lds + PG8_SB(b, h) + boff + n * 2048 + k * 1024); } while (0)
; #define PG8_MMA(ai, bj, At, Bt) do { __builtin_amdgcn_s_setprio(1); _Pragma("unroll") for (int m = 0; m < 4; ++m) _Pragma("unroll") for (int n = 0; n < 2; ++n) _Pragma("unroll") for (int k = 0; k < 2; ++k) \
;         acc[ai][bj][m][n] = __builtin_amdgcn_mfma_f32_16x16x32_f16(H8(Bt[n][k]), H8(At[m][k]), acc[ai][bj][m][n], 0, 0, 0); __builtin_amdgcn_s_setprio(0); } while (0)
; #define PG8_WAIT_V(n) asm volatile("s_waitcnt vmcnt(" #n ")" ::: "memory")
; #define PG8_WAIT_L(n) asm volatile("s_waitcnt lgkmcnt(" #n ")" ::: "memory")
; #define PG8_BAR __builtin_amdgcn_s_barrier()
; #define PG8_SCHED __builtin_amdgcn_sched_barrier(0)
; template <class Epi, class Sched, bool ALIGN_EPI = false, bool SP2 = false>
; __device__ __forceinline__ void gemm_phase(PG8_LAS unsigned char* lds, const Gemm g, const Sched& S, const Epi& E) {
;     ...
;             PG8_LDA(At, 0, 1); PG8_STAGE(PG8_SB(0, 0), b2, voffB); PG8_STAGE(PG8_SB(0, 1), b2 + hstep, voffB); PG8_STAGE(PG8_SA(0, 0), a2, voffA);
;             PG8_WAIT_V(8); PG8_WAIT_L(0); PG8_BAR; PG8_MMA(1, 0, At, B0); PG8_MMA(1, 1, At, B1); PG8_BAR; PG8_SCHED;
;             PG8_LDB(B0, 1, 0); PG8_LDB(B1, 1, 1); PG8_SCHED; PG8_LDA(At, 1, 0); PG8_STAGE(PG8_SA(0, 1), a2 + hstep, voffA);
;             PG8_WAIT_V(8); PG8_WAIT_L(0); PG8_BAR; PG8_MMA(0, 0, At, B0); PG8_MMA(0, 1, At, B1); PG8_BAR; PG8_SCHED;
	s_setprio 1
	s_waitcnt lgkmcnt(0)
	v_mfma_f32_16x16x32_f16 v[54:57], v[146:149], v[188:191], v[54:57]
	v_mfma_f32_16x16x32_f16 v[50:53], v[164:167], v[188:191], v[50:53]
	v_mfma_f32_16x16x32_f16 v[38:41], v[146:149], v[196:199], v[38:41]
	v_mfma_f32_16x16x32_f16 v[34:37], v[164:167], v[196:199], v[34:37]
	v_mfma_f32_16x16x32_f16 v[22:25], v[146:149], v[204:207], v[22:25]
	v_mfma_f32_16x16x32_f16 v[18:21], v[164:167], v[204:207], v[18:21]
	v_mfma_f32_16x16x32_f16 v[6:9], v[146:149], v[212:215], v[6:9]
	v_mfma_f32_16x16x32_f16 v[2:5], v[164:167], v[212:215], v[2:5]
	v_mfma_f32_16x16x32_f16 v[54:57], v[158:161], v[192:195], v[54:57]
	v_mfma_f32_16x16x32_f16 v[50:53], v[168:171], v[192:195], v[50:53]
	v_mfma_f32_16x16x32_f16 v[38:41], v[158:161], v[200:203], v[38:41]
	v_mfma_f32_16x16x32_f16 v[34:37], v[168:171], v[200:203], v[34:37]
	v_mfma_f32_16x16x32_f16 v[22:25], v[158:161], v[208:211], v[22:25]
	v_mfma_f32_16x16x32_f16 v[18:21], v[168:171], v[208:211], v[18:21]
	v_mfma_f32_16x16x32_f16 v[6:9], v[158:161], v[216:219], v[6:9]
	v_mfma_f32_16x16x32_f16 v[2:5], v[168:171], v[216:219], v[2:5]
	s_setprio 0
	s_setprio 1
	v_mfma_f32_16x16x32_f16 v[62:65], v[172:175], v[188:191], v[62:65]
	v_mfma_f32_16x16x32_f16 v[58:61], v[180:183], v[188:191], v[58:61]
	v_mfma_f32_16x16x32_f16 v[46:49], v[172:175], v[196:199], v[46:49]
	v_mfma_f32_16x16x32_f16 v[42:45], v[180:183], v[196:199], v[42:45]
	v_mfma_f32_16x16x32_f16 v[30:33], v[172:175], v[204:207], v[30:33]
	v_mfma_f32_16x16x32_f16 v[26:29], v[180:183], v[204:207], v[26:29]
	v_mfma_f32_16x16x32_f16 v[14:17], v[172:175], v[212:215], v[14:17]
	v_mfma_f32_16x16x32_f16 v[10:13], v[180:183], v[212:215], v[10:13]
	v_mfma_f32_16x16x32_f16 v[62:65], v[176:179], v[192:195], v[62:65]
	v_mfma_f32_16x16x32_f16 v[58:61], v[184:187], v[192:195], v[58:61]
	v_mfma_f32_16x16x32_f16 v[46:49], v[176:179], v[200:203], v[46:49]
	v_mfma_f32_16x16x32_f16 v[42:45], v[184:187], v[200:203], v[42:45]
	v_mfma_f32_16x16x32_f16 v[30:33], v[176:179], v[208:211], v[30:33]
	v_mfma_f32_16x16x32_f16 v[26:29], v[184:187], v[208:211], v[26:29]
	v_mfma_f32_16x16x32_f16 v[14:17], v[176:179], v[216:219], v[14:17]
	v_mfma_f32_16x16x32_f16 v[10:13], v[184:187], v[216:219], v[10:13]
	s_setprio 0
	s_barrier
	s_add_i32 s53, 0, 0x18000
	v_add_u32_e32 v157, s53, v152
	s_add_i32 s54, 0, 0x1c000
	ds_read_b128 v[146:149], v157
	ds_read_b128 v[158:161], v157 offset:1024
	ds_read_b128 v[164:167], v157 offset:2048
	ds_read_b128 v[168:171], v157 offset:3072
	v_add_u32_e32 v157, s54, v152
	ds_read_b128 v[172:175], v157
	ds_read_b128 v[176:179], v157 offset:1024
	ds_read_b128 v[180:183], v157 offset:2048
	ds_read_b128 v[184:187], v157 offset:3072
	s_add_u32 s28, s28, 0x40000
	s_addc_u32 s29, s29, 0
	s_mov_b32 m0, s37
	v_lshl_add_u64 v[226:227], s[28:29], 0, v[136:137]
	ds_read_b128 v[188:191], v156 offset:32768
	ds_read_b128 v[192:195], v156 offset:33792
	ds_read_b128 v[196:199], v156 offset:34816
	ds_read_b128 v[200:203], v156 offset:35840
	ds_read_b128 v[204:207], v156 offset:36864
	ds_read_b128 v[208:211], v156 offset:37888
	ds_read_b128 v[212:215], v156 offset:38912
	ds_read_b128 v[216:219], v156 offset:39936
	global_load_lds_dwordx4 v[226:227], off
	v_lshl_add_u64 v[226:227], s[28:29], 0, v[132:133]
	s_mov_b32 m0, s38
	s_nop 0
	global_load_lds_dwordx4 v[226:227], off
	s_waitcnt vmcnt(8)
	s_waitcnt lgkmcnt(0)
	s_barrier
	s_setprio 1
	s_waitcnt lgkmcnt(0)
	v_mfma_f32_16x16x32_f16 v[118:121], v[146:149], v[188:191], v[118:121]
	v_mfma_f32_16x16x32_f16 v[114:117], v[164:167], v[188:191], v[114:117]
	v_mfma_f32_16x16x32_f16 v[102:105], v[146:149], v[196:199], v[102:105]
	v_mfma_f32_16x16x32_f16 v[98:101], v[164:167], v[196:199], v[98:101]
	v_mfma_f32_16x16x32_f16 v[86:89], v[146:149], v[204:207], v[86:89]
	v_mfma_f32_16x16x32_f16 v[82:85], v[164:167], v[204:207], v[82:85]
	v_mfma_f32_16x16x32_f16 v[70:73], v[146:149], v[212:215], v[70:73]
	v_mfma_f32_16x16x32_f16 v[66:69], v[164:167], v[212:215], v[66:69]
	v_mfma_f32_16x16x32_f16 v[118:121], v[158:161], v[192:195], v[118:121]
	v_mfma_f32_16x16x32_f16 v[114:117], v[168:171], v[192:195], v[114:117]
	v_mfma_f32_16x16x32_f16 v[102:105], v[158:161], v[200:203], v[102:105]
	v_mfma_f32_16x16x32_f16 v[98:101], v[168:171], v[200:203], v[98:101]
	v_mfma_f32_16x16x32_f16 v[86:89], v[158:161], v[208:211], v[86:89]
	v_mfma_f32_16x16x32_f16 v[82:85], v[168:171], v[208:211], v[82:85]
	v_mfma_f32_16x16x32_f16 v[70:73], v[158:161], v[216:219], v[70:73]
	v_mfma_f32_16x16x32_f16 v[66:69], v[168:171], v[216:219], v[66:69]
	s_setprio 0
	s_setprio 1
	v_mfma_f32_16x16x32_f16 v[126:129], v[172:175], v[188:191], v[126:129]
	v_mfma_f32_16x16x32_f16 v[122:125], v[180:183], v[188:191], v[122:125]
	v_mfma_f32_16x16x32_f16 v[110:113], v[172:175], v[196:199], v[110:113]
	v_mfma_f32_16x16x32_f16 v[106:109], v[180:183], v[196:199], v[106:109]
	v_mfma_f32_16x16x32_f16 v[94:97], v[172:175], v[204:207], v[94:97]
	v_mfma_f32_16x16x32_f16 v[90:93], v[180:183], v[204:207], v[90:93]
	v_mfma_f32_16x16x32_f16 v[78:81], v[172:175], v[212:215], v[78:81]
	v_mfma_f32_16x16x32_f16 v[74:77], v[180:183], v[212:215], v[74:77]
	v_mfma_f32_16x16x32_f16 v[126:129], v[176:179], v[192:195], v[126:129]
	v_mfma_f32_16x16x32_f16 v[122:125], v[184:187], v[192:195], v[122:125]
	v_mfma_f32_16x16x32_f16 v[110:113], v[176:179], v[200:203], v[110:113]
	v_mfma_f32_16x16x32_f16 v[106:109], v[184:187], v[200:203], v[106:109]
	v_mfma_f32_16x16x32_f16 v[94:97], v[176:179], v[208:211], v[94:97]
	v_mfma_f32_16x16x32_f16 v[90:93], v[184:187], v[208:211], v[90:93]
	v_mfma_f32_16x16x32_f16 v[78:81], v[176:179], v[216:219], v[78:81]
	v_mfma_f32_16x16x32_f16 v[74:77], v[184:187], v[216:219], v[74:77]
	s_setprio 0
	s_barrier
; #define PG8_STAGE(bufoff, gbase, voff) do { _Pragma("unroll") for (int _i = 0; _i < 2; ++_i) \
;         __builtin_amdgcn_global_load_lds((const unsigned*)((const char*)(gbase) + (voff)[_i]), (PG8_LAS unsigned*)(lds + (bufoff) + ldsw + _i * 8192), 16, 0, 0); } while (0)
; #define PG8_LDA(dst, b, h) do { _Pragma("unroll") for (int m = 0; m < 4; ++m) _Pragma("unroll") for (int k = 0; k < 2; ++k) dst[m][k] = *(const PG8_LAS bf16x8*)(lds + PG8_SA(b, h) + aoff + m * 2048 + k * 1024); } while (0)
; #define PG8_LDB(dst, b, h) do { _Pragma("unroll") for (int n = 0; n < 2; ++n) _Pragma("unroll") for (int k = 0; k < 2; ++k) dst[n][k] = *(const PG8_LAS bf16x8*)(lds + PG8_SB(b, h) + boff + n * 2048 + k * 1024); } while (0)
; template <class Epi, class Sched, bool ALIGN_EPI = false, bool SP2 = false>
; __device__ __forceinline__ void gemm_phase(PG8_LAS unsigned char* lds, const Gemm g, const Sched& S, const Epi& E) {
;     ...
;         for (int t = 0; t < nt; t += 2) {
;             const bool last = (t == nt - 2);
;             const char* a1 = cA + (size_t)(t + 1) * kstep;
;             const char* a2 = last ? nA : cA + (size_t)(t + 2) * kstep; const char* b2 = last ? nB : cB + (size_t)(t + 2) * kstep;
;             const char* a3 = a2 + kstep; const char* b3 = b2 + kstep;
;             if (last && has_next) S.a_ready(nxt);
;             if constexpr (SP2) {
;             PG8_LDB(B0, 0, 0); PG8_LDB(B1, 0, 1); PG8_SCHED; PG8_LDA(At, 0, 0); PG8_STAGE(PG8_SA(1, 1), a1 + hstep, voffA);
;             PG8_WAIT_V(8); PG8_WAIT_L(0); PG8_BAR; PG8_MMA(0, 0, At, B0); PG8_MMA(0, 1, At, B1); PG8_BAR; PG8_SCHED;
;             PG8_LDA(At, 0, 1); PG8_STAGE(PG8_SB(0, 0), b2, voffB); PG8_STAGE(PG8_SB(0, 1), b2 + hstep, voffB); PG8_STAGE(PG8_SA(0, 0), a2, voffA);
;             PG8_WAIT_V(8); PG8_WAIT_L(0); PG8_BAR; PG8_MMA(1, 0, At, B0); PG8_MMA(1, 1, At, B1); PG8_BAR; PG8_SCHED;
;             PG8_LDB(B0, 1, 0); PG8_LDB(B1, 1, 1); PG8_SCHED; PG8_LDA(At, 1, 0); PG8_STAGE(PG8_SA(0, 1), a2 + hstep, voffA);
;             PG8_WAIT_V(8); PG8_WAIT_L(0); PG8_BAR; PG8_MMA(0, 0, At, B0); PG8_MMA(0, 1, At, B1); PG8_BAR; PG8_SCHED;
;             PG8_LDA(At, 1, 1); PG8_STAGE(PG8_SB(1, 0), b3, voffB); PG8_STAGE(PG8_SB(1, 1), b3 + hstep, voffB); PG8_STAGE(PG8_SA(1, 0), a3, voffA);
;             PG8_WAIT_V(8); PG8_WAIT_L(0); PG8_BAR; PG8_MMA(1, 0, At, B0); PG8_MMA(1, 1, At, B1); PG8_BAR; PG8_SCHED;
	s_add_i32 s28, s53, s33
	v_lshl_add_u64 v[150:151], v[150:151], 0, s[10:11]
	s_mov_b32 m0, s28
	ds_read_b128 v[188:191], v156 offset:49152
	ds_read_b128 v[192:195], v156 offset:50176
	ds_read_b128 v[196:199], v156 offset:51200
	ds_read_b128 v[200:203], v156 offset:52224
	ds_read_b128 v[204:207], v156 offset:53248
	ds_read_b128 v[208:211], v156 offset:54272
	ds_read_b128 v[212:215], v156 offset:55296
	ds_read_b128 v[216:219], v156 offset:56320
	global_load_lds_dwordx4 v[150:151], off
	s_add_i32 m0, s28, 0x2000
	s_add_u32 s26, s26, 0x40080
	v_lshl_add_u64 v[150:151], v[220:221], 0, s[10:11]
	s_addc_u32 s27, s27, 0
	s_add_i32 s28, s54, s33
	global_load_lds_dwordx4 v[150:151], off
	v_lshl_add_u64 v[150:151], s[26:27], 0, v[134:135]
	s_mov_b32 m0, s28
	s_nop 0
	global_load_lds_dwordx4 v[150:151], off
	v_lshl_add_u64 v[150:151], s[26:27], 0, v[130:131]
	s_add_i32 m0, s28, 0x2000
	s_nop 0
	global_load_lds_dwordx4 v[150:151], off
	v_lshl_add_u64 v[150:151], v[222:223], 0, s[10:11]
	s_mov_b32 m0, s40
	s_nop 0
	global_load_lds_dwordx4 v[150:151], off
	v_lshl_add_u64 v[150:151], v[224:225], 0, s[10:11]
	s_mov_b32 m0, s41
	s_nop 0
	global_load_lds_dwordx4 v[150:151], off
	s_waitcnt vmcnt(8)
	s_waitcnt lgkmcnt(0)
	s_barrier
	s_setprio 1
	s_waitcnt lgkmcnt(0)
	v_mfma_f32_16x16x32_f16 v[54:57], v[146:149], v[188:191], v[54:57]
	v_mfma_f32_16x16x32_f16 v[50:53], v[164:167], v[188:191], v[50:53]
	v_mfma_f32_16x16x32_f16 v[38:41], v[146:149], v[196:199], v[38:41]
	v_mfma_f32_16x16x32_f16 v[34:37], v[164:167], v[196:199], v[34:37]
	v_mfma_f32_16x16x32_f16 v[22:25], v[146:149], v[204:207], v[22:25]
	v_mfma_f32_16x16x32_f16 v[18:21], v[164:167], v[204:207], v[18:21]
	v_mfma_f32_16x16x32_f16 v[6:9], v[146:149], v[212:215], v[6:9]
	v_mfma_f32_16x16x32_f16 v[2:5], v[164:167], v[212:215], v[2:5]
	v_mfma_f32_16x16x32_f16 v[54:57], v[158:161], v[192:195], v[54:57]
	v_mfma_f32_16x16x32_f16 v[50:53], v[168:171], v[192:195], v[50:53]
	v_mfma_f32_16x16x32_f16 v[38:41], v[158:161], v[200:203], v[38:41]
	v_mfma_f32_16x16x32_f16 v[34:37], v[168:171], v[200:203], v[34:37]
	v_mfma_f32_16x16x32_f16 v[22:25], v[158:161], v[208:211], v[22:25]
	v_mfma_f32_16x16x32_f16 v[18:21], v[168:171], v[208:211], v[18:21]
	v_mfma_f32_16x16x32_f16 v[6:9], v[158:161], v[216:219], v[6:9]
	v_mfma_f32_16x16x32_f16 v[2:5], v[168:171], v[216:219], v[2:5]
	s_setprio 0
	s_setprio 1
	v_mfma_f32_16x16x32_f16 v[62:65], v[172:175], v[188:191], v[62:65]
	v_mfma_f32_16x16x32_f16 v[58:61], v[180:183], v[188:191], v[58:61]
	v_mfma_f32_16x16x32_f16 v[46:49], v[172:175], v[196:199], v[46:49]
	v_mfma_f32_16x16x32_f16 v[42:45], v[180:183], v[196:199], v[42:45]
	v_mfma_f32_16x16x32_f16 v[30:33], v[172:175], v[204:207], v[30:33]
	v_mfma_f32_16x16x32_f16 v[26:29], v[180:183], v[204:207], v[26:29]
	v_mfma_f32_16x16x32_f16 v[14:17], v[172:175], v[212:215], v[14:17]
	v_mfma_f32_16x16x32_f16 v[10:13], v[180:183], v[212:215], v[10:13]
	v_mfma_f32_16x16x32_f16 v[62:65], v[176:179], v[192:195], v[62:65]
	v_mfma_f32_16x16x32_f16 v[58:61], v[184:187], v[192:195], v[58:61]
	v_mfma_f32_16x16x32_f16 v[46:49], v[176:179], v[200:203], v[46:49]
	v_mfma_f32_16x16x32_f16 v[42:45], v[184:187], v[200:203], v[42:45]
	v_mfma_f32_16x16x32_f16 v[30:33], v[176:179], v[208:211], v[30:33]
	v_mfma_f32_16x16x32_f16 v[26:29], v[184:187], v[208:211], v[26:29]
	v_mfma_f32_16x16x32_f16 v[14:17], v[176:179], v[216:219], v[14:17]
	v_mfma_f32_16x16x32_f16 v[10:13], v[184:187], v[216:219], v[10:13]
	s_setprio 0
	s_add_i32 s52, s52, 2
	s_add_u32 s24, s24, 0x100
	s_addc_u32 s25, s25, 0
	s_add_u32 s50, s50, 0x100
	s_addc_u32 s51, s51, 0
	s_cmp_gt_u32 s52, 13
	s_barrier
	s_cbranch_scc0 .LBB0_1014
	s_and_b64 vcc, exec, s[12:13]
	s_cbranch_vccz .LBB0_1017
	s_barrier

; #define PG8_STAGE(bufoff, gbase, voff) do { _Pragma("unroll") for (int _i = 0; _i < 2; ++_i) \
;         __builtin_amdgcn_global_load_lds((const unsigned*)((const char*)(gbase) + (voff)[_i]), (PG8_LAS unsigned*)(lds + (bufoff) + ldsw + _i * 8192), 16, 0, 0); } while (0)
; #define PG8_LDA(dst, b, h) do { _Pragma("unroll") for (int m = 0; m < 4; ++m) _Pragma("unroll") for (int k = 0; k < 2; ++k) dst[m][k] = *(const PG8_LAS bf16x8*)(lds + PG8_SA(b, h) + aoff + m * 2048 + k * 1024); } while (0)
; #define PG8_LDB(dst, b, h) do { _Pragma("unroll") for (int n = 0; n < 2; ++n) _Pragma("unroll") for (int k = 0; k < 2; ++k) dst[n][k] = *(const PG8_LAS bf16x8*)(lds + PG8_SB(b, h) + boff + n * 2048 + k * 1024); } while (0)
; #define PG8_MMA(ai, bj, At, Bt) do { __builtin_amdgcn_s_setprio(1); _Pragma("unroll") for (int m = 0; m < 4; ++m) _Pragma("unroll") for (int n = 0; n < 2; ++n) _Pragma("unroll") for (int k = 0; k < 2; ++k) \
;         acc[ai][bj][m][n] = __builtin_amdgcn_mfma_f32_16x16x32_f16(H8(Bt[n][k]), H8(At[m][k]), acc[ai][bj][m][n], 0, 0, 0); __builtin_amdgcn_s_setprio(0); } while (0)
; #define PG8_WAIT_V(n) asm volatile("s_waitcnt vmcnt(" #n ")" ::: "memory")
; #define PG8_WAIT_L(n) asm volatile("s_waitcnt lgkmcnt(" #n ")" ::: "memory")
; #define PG8_BAR __builtin_amdgcn_s_barrier()
; #define PG8_SCHED __builtin_amdgcn_sched_barrier(0)
; template <class Epi, class Sched, bool ALIGN_EPI = false, bool SP2 = false>
; __device__ __forceinline__ void gemm_phase(PG8_LAS unsigned char* lds, const Gemm g, const Sched& S, const Epi& E) {
;     ...
;             const bool last = (t == nt - 2);
;             const char* a1 = cA + (size_t)(t + 1) * kstep;
;             const char* a2 = last ? nA : cA + (size_t)(t + 2) * kstep; const char* b2 = last ? nB : cB + (size_t)(t + 2) * kstep;
;             const char* a3 = a2 + kstep; const char* b3 = b2 + kstep;
;             if (last && has_next) S.a_ready(nxt);
;             if constexpr (SP2) {
;             PG8_LDB(B0, 0, 0); PG8_LDB(B1, 0, 1); PG8_SCHED; PG8_LDA(At, 0, 0); PG8_STAGE(PG8_SA(1, 1), a1 + hstep, voffA);
;             PG8_WAIT_V(8); PG8_WAIT_L(0); PG8_BAR; PG8_MMA(0, 0, At, B0); PG8_MMA(0, 1, At, B1); PG8_BAR; PG8_SCHED;
;             PG8_LDA(At, 0, 1); PG8_STAGE(PG8_SB(0, 0), b2, voffB); PG8_STAGE(PG8_SB(0, 1), b2 + hstep, voffB); PG8_STAGE(PG8_SA(0, 0), a2, voffA);
.LBB0_1109:
	ds_read_b128 v[154:157], v150
	ds_read_b128 v[158:161], v150 offset:1024
	ds_read_b128 v[164:167], v150 offset:2048
	ds_read_b128 v[168:171], v150 offset:3072
	ds_read_b128 v[172:175], v151
	ds_read_b128 v[176:179], v151 offset:1024
	ds_read_b128 v[180:183], v151 offset:2048
	ds_read_b128 v[184:187], v151 offset:3072
	s_add_u32 s26, s24, 0xfff50080
	s_addc_u32 s27, s25, -1
	s_cmp_eq_u32 s58, 40
	s_cselect_b32 s29, s5, s27
	s_cselect_b32 s28, s4, s26
	s_cselect_b32 s27, s23, s57
	s_cselect_b32 s26, s22, s56
	v_lshl_add_u64 v[146:147], s[24:25], 0, v[138:139]
	s_add_i32 m0, s37, 0xc000
	ds_read_b128 v[188:191], v152
	ds_read_b128 v[192:195], v152 offset:1024
	ds_read_b128 v[196:199], v152 offset:2048
	ds_read_b128 v[200:203], v152 offset:3072
	ds_read_b128 v[204:207], v152 offset:4096
	ds_read_b128 v[208:211], v152 offset:5120
	ds_read_b128 v[212:215], v152 offset:6144
	ds_read_b128 v[216:219], v152 offset:7168
	global_load_lds_dwordx4 v[146:147], off
	v_lshl_add_u64 v[146:147], s[24:25], 0, v[140:141]
	s_add_i32 m0, s37, 0xe000
	s_nop 0
	global_load_lds_dwordx4 v[146:147], off
	s_waitcnt vmcnt(8)
	s_waitcnt lgkmcnt(0)
	s_barrier
	s_setprio 1
	s_waitcnt lgkmcnt(0)
	v_mfma_f32_16x16x32_f16 v[126:129], v[154:157], v[188:191], v[126:129]
	v_mfma_f32_16x16x32_f16 v[122:125], v[164:167], v[188:191], v[122:125]
	v_mfma_f32_16x16x32_f16 v[118:121], v[154:157], v[196:199], v[118:121]
	v_mfma_f32_16x16x32_f16 v[110:113], v[164:167], v[196:199], v[110:113]
	v_mfma_f32_16x16x32_f16 v[102:105], v[154:157], v[204:207], v[102:105]
	v_mfma_f32_16x16x32_f16 v[94:97], v[164:167], v[204:207], v[94:97]
	v_mfma_f32_16x16x32_f16 v[86:89], v[154:157], v[212:215], v[86:89]
	v_mfma_f32_16x16x32_f16 v[78:81], v[164:167], v[212:215], v[78:81]
	v_mfma_f32_16x16x32_f16 v[126:129], v[158:161], v[192:195], v[126:129]
	v_mfma_f32_16x16x32_f16 v[122:125], v[168:171], v[192:195], v[122:125]
	v_mfma_f32_16x16x32_f16 v[118:121], v[158:161], v[200:203], v[118:121]
	v_mfma_f32_16x16x32_f16 v[110:113], v[168:171], v[200:203], v[110:113]
	v_mfma_f32_16x16x32_f16 v[102:105], v[158:161], v[208:211], v[102:105]
	v_mfma_f32_16x16x32_f16 v[94:97], v[168:171], v[208:211], v[94:97]
	v_mfma_f32_16x16x32_f16 v[86:89], v[158:161], v[216:219], v[86:89]
	v_mfma_f32_16x16x32_f16 v[78:81], v[168:171], v[216:219], v[78:81]
	s_setprio 0
	s_setprio 1
	v_mfma_f32_16x16x32_f16 v[114:117], v[172:175], v[188:191], v[114:117]
	v_mfma_f32_16x16x32_f16 v[106:109], v[180:183], v[188:191], v[106:109]
	v_mfma_f32_16x16x32_f16 v[98:101], v[172:175], v[196:199], v[98:101]
	v_mfma_f32_16x16x32_f16 v[90:93], v[180:183], v[196:199], v[90:93]
	v_mfma_f32_16x16x32_f16 v[82:85], v[172:175], v[204:207], v[82:85]
	v_mfma_f32_16x16x32_f16 v[74:77], v[180:183], v[204:207], v[74:77]
	v_mfma_f32_16x16x32_f16 v[70:73], v[172:175], v[212:215], v[70:73]
	v_mfma_f32_16x16x32_f16 v[66:69], v[180:183], v[212:215], v[66:69]
	v_mfma_f32_16x16x32_f16 v[114:117], v[176:179], v[192:195], v[114:117]
	v_mfma_f32_16x16x32_f16 v[106:109], v[184:187], v[192:195], v[106:109]
	v_mfma_f32_16x16x32_f16 v[98:101], v[176:179], v[200:203], v[98:101]
	v_mfma_f32_16x16x32_f16 v[90:93], v[184:187], v[200:203], v[90:93]
	v_mfma_f32_16x16x32_f16 v[82:85], v[176:179], v[208:211], v[82:85]
	v_mfma_f32_16x16x32_f16 v[74:77], v[184:187], v[208:211], v[74:77]
	v_mfma_f32_16x16x32_f16 v[70:73], v[176:179], v[216:219], v[70:73]
	v_mfma_f32_16x16x32_f16 v[66:69], v[184:187], v[216:219], v[66:69]
	s_setprio 0
	s_barrier
	s_add_i32 s59, s46, s36
	v_lshl_add_u64 v[146:147], s[26:27], 0, v[132:133]
	s_mov_b32 m0, s59
	ds_read_b128 v[188:191], v152 offset:16384
	ds_read_b128 v[192:195], v152 offset:17408
	ds_read_b128 v[196:199], v152 offset:18432
	ds_read_b128 v[200:203], v152 offset:19456
	ds_read_b128 v[204:207], v152 offset:20480
	ds_read_b128 v[208:211], v152 offset:21504
	ds_read_b128 v[212:215], v152 offset:22528
	ds_read_b128 v[216:219], v152 offset:23552
	global_load_lds_dwordx4 v[146:147], off
	s_add_i32 m0, s59, 0x2000
	s_add_u32 s60, s26, 0xb0000
	v_lshl_add_u64 v[220:221], s[26:27], 0, v[136:137]
	s_addc_u32 s61, s27, 0
	s_add_i32 s59, s47, s36
	global_load_lds_dwordx4 v[220:221], off
	v_lshl_add_u64 v[222:223], s[60:61], 0, v[132:133]
	s_mov_b32 m0, s59
	v_lshl_add_u64 v[224:225], s[28:29], 0, v[134:135]
	global_load_lds_dwordx4 v[222:223], off
	v_lshl_add_u64 v[222:223], s[60:61], 0, v[136:137]
	s_add_i32 m0, s59, 0x2000
	s_nop 0
	global_load_lds_dwordx4 v[222:223], off
	v_lshl_add_u64 v[222:223], s[28:29], 0, v[130:131]
	s_mov_b32 m0, s37
	s_nop 0
	global_load_lds_dwordx4 v[222:223], off
	s_mov_b32 m0, s38
	s_nop 0
	global_load_lds_dwordx4 v[224:225], off
	s_waitcnt vmcnt(8)
	s_waitcnt lgkmcnt(0)
	s_barrier
; #define PG8_STAGE(bufoff, gbase, voff) do { _Pragma("unroll") for (int _i = 0; _i < 2; ++_i) \
;         __builtin_amdgcn_global_load_lds((const unsigned*)((const char*)(gbase) + (voff)[_i]), (PG8_LAS unsigned*)(lds + (bufoff) + ldsw + _i * 8192), 16, 0, 0); } while (0)
; #define PG8_LDA(dst, b, h) do { _Pragma("unroll") for (int m = 0; m < 4; ++m) _Pragma("unroll") for (int k = 0; k < 2; ++k) dst[m][k] = *(const PG8_LAS bf16x8*)(lds + PG8_SA(b, h) + aoff + m * 2048 + k * 1024); } while (0)
; #define PG8_LDB(dst, b, h) do { _Pragma("unroll") for (int n = 0; n < 2; ++n) _Pragma("unroll") for (int k = 0; k < 2; ++k) dst[n][k] = *(const PG8_LAS bf16x8*)(lds + PG8_SB(b, h) + boff + n * 2048 + k * 1024); } while (0)
; #define PG8_MMA(ai, bj, At, Bt) do { __builtin_amdgcn_s_setprio(1); _Pragma("unroll") for (int m = 0; m < 4; ++m) _Pragma("unroll") for (int n = 0; n < 2; ++n) _Pragma("unroll") for (int k = 0; k < 2; ++k) \
;         acc[ai][bj][m][n] = __builtin_amdgcn_mfma_f32_16x16x32_f16(H8(Bt[n][k]), H8(At[m][k]), acc[ai][bj][m][n], 0, 0, 0); __builtin_amdgcn_s_setprio(0); } while (0)
; #define PG8_WAIT_V(n) asm volatile("s_waitcnt vmcnt(" #n ")" ::: "memory")
; #define PG8_WAIT_L(n) asm volatile("s_waitcnt lgkmcnt(" #n ")" ::: "memory")
; #define PG8_BAR __builtin_amdgcn_s_barrier()
; #define PG8_SCHED __builtin_amdgcn_sched_barrier(0)
; template <class Epi, class Sched, bool ALIGN_EPI = false, bool SP2 = false>
; __device__ __forceinline__ void gemm_phase(PG8_LAS unsigned char* lds, const Gemm g, const Sched& S, const Epi& E) {
;     ...
;             PG8_LDA(At, 0, 1); PG8_STAGE(PG8_SB(0, 0), b2, voffB); PG8_STAGE(PG8_SB(0, 1), b2 + hstep, voffB); PG8_STAGE(PG8_SA(0, 0), a2, voffA);
;             PG8_WAIT_V(8); PG8_WAIT_L(0); PG8_BAR; PG8_MMA(1, 0, At, B0); PG8_MMA(1, 1, At, B1); PG8_BAR; PG8_SCHED;
;             PG8_LDB(B0, 1, 0); PG8_LDB(B1, 1, 1); PG8_SCHED; PG8_LDA(At, 1, 0); PG8_STAGE(PG8_SA(0, 1), a2 + hstep, voffA);
;             PG8_WAIT_V(8); PG8_WAIT_L(0); PG8_BAR; PG8_MMA(0, 0, At, B0); PG8_MMA(0, 1, At, B1); PG8_BAR; PG8_SCHED;
	s_setprio 1
	s_waitcnt lgkmcnt(0)
	v_mfma_f32_16x16x32_f16 v[62:65], v[154:157], v[188:191], v[62:65]
	v_mfma_f32_16x16x32_f16 v[58:61], v[164:167], v[188:191], v[58:61]
	v_mfma_f32_16x16x32_f16 v[54:57], v[154:157], v[196:199], v[54:57]
	v_mfma_f32_16x16x32_f16 v[46:49], v[164:167], v[196:199], v[46:49]
	v_mfma_f32_16x16x32_f16 v[38:41], v[154:157], v[204:207], v[38:41]
	v_mfma_f32_16x16x32_f16 v[30:33], v[164:167], v[204:207], v[30:33]
	v_mfma_f32_16x16x32_f16 v[22:25], v[154:157], v[212:215], v[22:25]
	v_mfma_f32_16x16x32_f16 v[14:17], v[164:167], v[212:215], v[14:17]
	v_mfma_f32_16x16x32_f16 v[62:65], v[158:161], v[192:195], v[62:65]
	v_mfma_f32_16x16x32_f16 v[58:61], v[168:171], v[192:195], v[58:61]
	v_mfma_f32_16x16x32_f16 v[54:57], v[158:161], v[200:203], v[54:57]
	v_mfma_f32_16x16x32_f16 v[46:49], v[168:171], v[200:203], v[46:49]
	v_mfma_f32_16x16x32_f16 v[38:41], v[158:161], v[208:211], v[38:41]
	v_mfma_f32_16x16x32_f16 v[30:33], v[168:171], v[208:211], v[30:33]
	v_mfma_f32_16x16x32_f16 v[22:25], v[158:161], v[216:219], v[22:25]
	v_mfma_f32_16x16x32_f16 v[14:17], v[168:171], v[216:219], v[14:17]
	s_setprio 0
	s_setprio 1
	v_mfma_f32_16x16x32_f16 v[50:53], v[172:175], v[188:191], v[50:53]
	v_mfma_f32_16x16x32_f16 v[42:45], v[180:183], v[188:191], v[42:45]
	v_mfma_f32_16x16x32_f16 v[34:37], v[172:175], v[196:199], v[34:37]
	v_mfma_f32_16x16x32_f16 v[26:29], v[180:183], v[196:199], v[26:29]
	v_mfma_f32_16x16x32_f16 v[18:21], v[172:175], v[204:207], v[18:21]
	v_mfma_f32_16x16x32_f16 v[10:13], v[180:183], v[204:207], v[10:13]
	v_mfma_f32_16x16x32_f16 v[6:9], v[172:175], v[212:215], v[6:9]
	v_mfma_f32_16x16x32_f16 v[2:5], v[180:183], v[212:215], v[2:5]
	v_mfma_f32_16x16x32_f16 v[50:53], v[176:179], v[192:195], v[50:53]
	v_mfma_f32_16x16x32_f16 v[42:45], v[184:187], v[192:195], v[42:45]
	v_mfma_f32_16x16x32_f16 v[34:37], v[176:179], v[200:203], v[34:37]
	v_mfma_f32_16x16x32_f16 v[26:29], v[184:187], v[200:203], v[26:29]
	v_mfma_f32_16x16x32_f16 v[18:21], v[176:179], v[208:211], v[18:21]
	v_mfma_f32_16x16x32_f16 v[10:13], v[184:187], v[208:211], v[10:13]
	v_mfma_f32_16x16x32_f16 v[6:9], v[176:179], v[216:219], v[6:9]
	v_mfma_f32_16x16x32_f16 v[2:5], v[184:187], v[216:219], v[2:5]
	s_setprio 0
	s_barrier
	s_add_i32 s59, 0, 0x18000
	v_add_u32_e32 v153, s59, v148
	s_add_i32 s60, 0, 0x1c000
	ds_read_b128 v[154:157], v153
	ds_read_b128 v[158:161], v153 offset:1024
	ds_read_b128 v[164:167], v153 offset:2048
	ds_read_b128 v[168:171], v153 offset:3072
	v_add_u32_e32 v153, s60, v148
	ds_read_b128 v[172:175], v153
	ds_read_b128 v[176:179], v153 offset:1024
	ds_read_b128 v[180:183], v153 offset:2048
	ds_read_b128 v[184:187], v153 offset:3072
	s_add_u32 s28, s28, 0xb0000
	s_addc_u32 s29, s29, 0
	s_mov_b32 m0, s39
	v_lshl_add_u64 v[226:227], s[28:29], 0, v[130:131]
	ds_read_b128 v[188:191], v152 offset:32768
	ds_read_b128 v[192:195], v152 offset:33792
	ds_read_b128 v[196:199], v152 offset:34816
	ds_read_b128 v[200:203], v152 offset:35840
	ds_read_b128 v[204:207], v152 offset:36864
	ds_read_b128 v[208:211], v152 offset:37888
	ds_read_b128 v[212:215], v152 offset:38912
	ds_read_b128 v[216:219], v152 offset:39936
	global_load_lds_dwordx4 v[226:227], off
	v_lshl_add_u64 v[226:227], s[28:29], 0, v[134:135]
	s_mov_b32 m0, s40
	s_nop 0
	global_load_lds_dwordx4 v[226:227], off
	s_waitcnt vmcnt(8)
	s_waitcnt lgkmcnt(0)
	s_barrier
	s_setprio 1
	s_waitcnt lgkmcnt(0)
	v_mfma_f32_16x16x32_f16 v[126:129], v[154:157], v[188:191], v[126:129]
	v_mfma_f32_16x16x32_f16 v[122:125], v[164:167], v[188:191], v[122:125]
	v_mfma_f32_16x16x32_f16 v[118:121], v[154:157], v[196:199], v[118:121]
	v_mfma_f32_16x16x32_f16 v[110:113], v[164:167], v[196:199], v[110:113]
	v_mfma_f32_16x16x32_f16 v[102:105], v[154:157], v[204:207], v[102:105]
	v_mfma_f32_16x16x32_f16 v[94:97], v[164:167], v[204:207], v[94:97]
	v_mfma_f32_16x16x32_f16 v[86:89], v[154:157], v[212:215], v[86:89]
	v_mfma_f32_16x16x32_f16 v[78:81], v[164:167], v[212:215], v[78:81]
	v_mfma_f32_16x16x32_f16 v[126:129], v[158:161], v[192:195], v[126:129]
	v_mfma_f32_16x16x32_f16 v[122:125], v[168:171], v[192:195], v[122:125]
	v_mfma_f32_16x16x32_f16 v[118:121], v[158:161], v[200:203], v[118:121]
	v_mfma_f32_16x16x32_f16 v[110:113], v[168:171], v[200:203], v[110:113]
	v_mfma_f32_16x16x32_f16 v[102:105], v[158:161], v[208:211], v[102:105]
	v_mfma_f32_16x16x32_f16 v[94:97], v[168:171], v[208:211], v[94:97]
	v_mfma_f32_16x16x32_f16 v[86:89], v[158:161], v[216:219], v[86:89]
	v_mfma_f32_16x16x32_f16 v[78:81], v[168:171], v[216:219], v[78:81]
	s_setprio 0
	s_setprio 1
	v_mfma_f32_16x16x32_f16 v[114:117], v[172:175], v[188:191], v[114:117]
	v_mfma_f32_16x16x32_f16 v[106:109], v[180:183], v[188:191], v[106:109]
	v_mfma_f32_16x16x32_f16 v[98:101], v[172:175], v[196:199], v[98:101]
	v_mfma_f32_16x16x32_f16 v[90:93], v[180:183], v[196:199], v[90:93]
	v_mfma_f32_16x16x32_f16 v[82:85], v[172:175], v[204:207], v[82:85]
	v_mfma_f32_16x16x32_f16 v[74:77], v[180:183], v[204:207], v[74:77]
	v_mfma_f32_16x16x32_f16 v[70:73], v[172:175], v[212:215], v[70:73]
	v_mfma_f32_16x16x32_f16 v[66:69], v[180:183], v[212:215], v[66:69]
	v_mfma_f32_16x16x32_f16 v[114:117], v[176:179], v[192:195], v[114:117]
	v_mfma_f32_16x16x32_f16 v[106:109], v[184:187], v[192:195], v[106:109]
	v_mfma_f32_16x16x32_f16 v[98:101], v[176:179], v[200:203], v[98:101]
	v_mfma_f32_16x16x32_f16 v[90:93], v[184:187], v[200:203], v[90:93]
	v_mfma_f32_16x16x32_f16 v[82:85], v[176:179], v[208:211], v[82:85]
	v_mfma_f32_16x16x32_f16 v[74:77], v[184:187], v[208:211], v[74:77]
	v_mfma_f32_16x16x32_f16 v[70:73], v[176:179], v[216:219], v[70:73]
	v_mfma_f32_16x16x32_f16 v[66:69], v[184:187], v[216:219], v[66:69]
	s_setprio 0
	s_barrier
; #define PG8_STAGE(bufoff, gbase, voff) do { _Pragma("unroll") for (int _i = 0; _i < 2; ++_i) \
;         __builtin_amdgcn_global_load_lds((const unsigned*)((const char*)(gbase) + (voff)[_i]), (PG8_LAS unsigned*)(lds + (bufoff) + ldsw + _i * 8192), 16, 0, 0); } while (0)
; #define PG8_LDA(dst, b, h) do { _Pragma("unroll") for (int m = 0; m < 4; ++m) _Pragma("unroll") for (int k = 0; k < 2; ++k) dst[m][k] = *(const PG8_LAS bf16x8*)(lds + PG8_SA(b, h) + aoff + m * 2048 + k * 1024); } while (0)
; #define PG8_LDB(dst, b, h) do { _Pragma("unroll") for (int n = 0; n < 2; ++n) _Pragma("unroll") for (int k = 0; k < 2; ++k) dst[n][k] = *(const PG8_LAS bf16x8*)(lds + PG8_SB(b, h) + boff + n * 2048 + k * 1024); } while (0)
; template <class Epi, class Sched, bool ALIGN_EPI = false, bool SP2 = false>
; __device__ __forceinline__ void gemm_phase(PG8_LAS unsigned char* lds, const Gemm g, const Sched& S, const Epi& E) {
;     ...
;         for (int t = 0; t < nt; t += 2) {
;             const bool last = (t == nt - 2);
;             const char* a1 = cA + (size_t)(t + 1) * kstep;
;             const char* a2 = last ? nA : cA + (size_t)(t + 2) * kstep; const char* b2 = last ? nB : cB + (size_t)(t + 2) * kstep;
;             const char* a3 = a2 + kstep; const char* b3 = b2 + kstep;
;             if (last && has_next) S.a_ready(nxt);
;             if constexpr (SP2) {
;             PG8_LDB(B0, 0, 0); PG8_LDB(B1, 0, 1); PG8_SCHED; PG8_LDA(At, 0, 0); PG8_STAGE(PG8_SA(1, 1), a1 + hstep, voffA);
;             PG8_WAIT_V(8); PG8_WAIT_L(0); PG8_BAR; PG8_MMA(0, 0, At, B0); PG8_MMA(0, 1, At, B1); PG8_BAR; PG8_SCHED;
;             PG8_LDA(At, 0, 1); PG8_STAGE(PG8_SB(0, 0), b2, voffB); PG8_STAGE(PG8_SB(0, 1), b2 + hstep, voffB); PG8_STAGE(PG8_SA(0, 0), a2, voffA);
;             PG8_WAIT_V(8); PG8_WAIT_L(0); PG8_BAR; PG8_MMA(1, 0, At, B0); PG8_MMA(1, 1, At, B1); PG8_BAR; PG8_SCHED;
;             PG8_LDB(B0, 1, 0); PG8_LDB(B1, 1, 1); PG8_SCHED; PG8_LDA(At, 1, 0); PG8_STAGE(PG8_SA(0, 1), a2 + hstep, voffA);
;             PG8_WAIT_V(8); PG8_WAIT_L(0); PG8_BAR; PG8_MMA(0, 0, At, B0); PG8_MMA(0, 1, At, B1); PG8_BAR; PG8_SCHED;
;             PG8_LDA(At, 1, 1); PG8_STAGE(PG8_SB(1, 0), b3, voffB); PG8_STAGE(PG8_SB(1, 1), b3 + hstep, voffB); PG8_STAGE(PG8_SA(1, 0), a3, voffA);
;             PG8_WAIT_V(8); PG8_WAIT_L(0); PG8_BAR; PG8_MMA(1, 0, At, B0); PG8_MMA(1, 1, At, B1); PG8_BAR; PG8_SCHED;
	s_add_i32 s28, s59, s36
	v_lshl_add_u64 v[146:147], v[146:147], 0, s[10:11]
	s_mov_b32 m0, s28
	ds_read_b128 v[188:191], v152 offset:49152
	ds_read_b128 v[192:195], v152 offset:50176
	ds_read_b128 v[196:199], v152 offset:51200
	ds_read_b128 v[200:203], v152 offset:52224
	ds_read_b128 v[204:207], v152 offset:53248
	ds_read_b128 v[208:211], v152 offset:54272
	ds_read_b128 v[212:215], v152 offset:55296
	ds_read_b128 v[216:219], v152 offset:56320
	global_load_lds_dwordx4 v[146:147], off
	s_add_i32 m0, s28, 0x2000
	s_add_u32 s26, s26, 0xb0080
	v_lshl_add_u64 v[146:147], v[220:221], 0, s[10:11]
	s_addc_u32 s27, s27, 0
	s_add_i32 s28, s60, s36
	global_load_lds_dwordx4 v[146:147], off
	v_lshl_add_u64 v[146:147], s[26:27], 0, v[132:133]
	s_mov_b32 m0, s28
	s_nop 0
	global_load_lds_dwordx4 v[146:147], off
	v_lshl_add_u64 v[146:147], s[26:27], 0, v[136:137]
	s_add_i32 m0, s28, 0x2000
	s_nop 0
	global_load_lds_dwordx4 v[146:147], off
	v_lshl_add_u64 v[146:147], v[222:223], 0, s[10:11]
	s_mov_b32 m0, s42
	s_nop 0
	global_load_lds_dwordx4 v[146:147], off
	v_lshl_add_u64 v[146:147], v[224:225], 0, s[10:11]
	s_mov_b32 m0, s43
	s_nop 0
	global_load_lds_dwordx4 v[146:147], off
	s_waitcnt vmcnt(8)
	s_waitcnt lgkmcnt(0)
	s_barrier
	s_setprio 1
	s_waitcnt lgkmcnt(0)
	v_mfma_f32_16x16x32_f16 v[62:65], v[154:157], v[188:191], v[62:65]
	v_mfma_f32_16x16x32_f16 v[58:61], v[164:167], v[188:191], v[58:61]
	v_mfma_f32_16x16x32_f16 v[54:57], v[154:157], v[196:199], v[54:57]
	v_mfma_f32_16x16x32_f16 v[46:49], v[164:167], v[196:199], v[46:49]
	v_mfma_f32_16x16x32_f16 v[38:41], v[154:157], v[204:207], v[38:41]
	v_mfma_f32_16x16x32_f16 v[30:33], v[164:167], v[204:207], v[30:33]
	v_mfma_f32_16x16x32_f16 v[22:25], v[154:157], v[212:215], v[22:25]
	v_mfma_f32_16x16x32_f16 v[14:17], v[164:167], v[212:215], v[14:17]
	v_mfma_f32_16x16x32_f16 v[62:65], v[158:161], v[192:195], v[62:65]
	v_mfma_f32_16x16x32_f16 v[58:61], v[168:171], v[192:195], v[58:61]
	v_mfma_f32_16x16x32_f16 v[54:57], v[158:161], v[200:203], v[54:57]
	v_mfma_f32_16x16x32_f16 v[46:49], v[168:171], v[200:203], v[46:49]
	v_mfma_f32_16x16x32_f16 v[38:41], v[158:161], v[208:211], v[38:41]
	v_mfma_f32_16x16x32_f16 v[30:33], v[168:171], v[208:211], v[30:33]
	v_mfma_f32_16x16x32_f16 v[22:25], v[158:161], v[216:219], v[22:25]
	v_mfma_f32_16x16x32_f16 v[14:17], v[168:171], v[216:219], v[14:17]
	s_setprio 0
	s_setprio 1
	v_mfma_f32_16x16x32_f16 v[50:53], v[172:175], v[188:191], v[50:53]
	v_mfma_f32_16x16x32_f16 v[42:45], v[180:183], v[188:191], v[42:45]
	v_mfma_f32_16x16x32_f16 v[34:37], v[172:175], v[196:199], v[34:37]
	v_mfma_f32_16x16x32_f16 v[26:29], v[180:183], v[196:199], v[26:29]
	v_mfma_f32_16x16x32_f16 v[18:21], v[172:175], v[204:207], v[18:21]
	v_mfma_f32_16x16x32_f16 v[10:13], v[180:183], v[204:207], v[10:13]
	v_mfma_f32_16x16x32_f16 v[6:9], v[172:175], v[212:215], v[6:9]
	v_mfma_f32_16x16x32_f16 v[2:5], v[180:183], v[212:215], v[2:5]
	v_mfma_f32_16x16x32_f16 v[50:53], v[176:179], v[192:195], v[50:53]
	v_mfma_f32_16x16x32_f16 v[42:45], v[184:187], v[192:195], v[42:45]
	v_mfma_f32_16x16x32_f16 v[34:37], v[176:179], v[200:203], v[34:37]
	v_mfma_f32_16x16x32_f16 v[26:29], v[184:187], v[200:203], v[26:29]
	v_mfma_f32_16x16x32_f16 v[18:21], v[176:179], v[208:211], v[18:21]
	v_mfma_f32_16x16x32_f16 v[10:13], v[184:187], v[208:211], v[10:13]
	v_mfma_f32_16x16x32_f16 v[6:9], v[176:179], v[216:219], v[6:9]
	v_mfma_f32_16x16x32_f16 v[2:5], v[184:187], v[216:219], v[2:5]
	s_setprio 0
	s_add_i32 s58, s58, 2
	s_add_u32 s24, s24, 0x100
	s_addc_u32 s25, s25, 0
	s_add_u32 s56, s56, 0x100
	s_addc_u32 s57, s57, 0
	s_cmp_gt_u32 s58, 41
	s_barrier
	s_cbranch_scc0 .LBB0_1109
	s_and_b64 vcc, exec, s[12:13]
	s_cbranch_vccz .LBB0_1112
	s_barrier
